# strategy 7: B-fragment LDS reads use one loop-invariant base VGPR with immediate offsets (no per-iteration base recomputation ahead of the reads)
# baseline (speedup 1.0000x reference)
.LBB0_445:
	s_add_u32 s56, s62, 0xb0080
	s_addc_u32 s57, s63, 0
	s_add_u32 s62, s60, 0x100
	v_mov_b32_e32 v2, 0
	s_addc_u32 s63, s61, 0
	s_mov_b32 s84, -2
	s_waitcnt lgkmcnt(0)
	v_add_u32_e32 v243, 0x10000, v191
	s_add_i32 s22, 0, 0x10000
	s_add_i32 s23, 0, 0x14000
	ds_read_b128 v[114:117], v243
	ds_read_b128 v[126:129], v243 offset:1024
	ds_read_b128 v[130:133], v243 offset:2048
	ds_read_b128 v[134:137], v243 offset:3072
	ds_read_b128 v[146:149], v243 offset:16384
	ds_read_b128 v[150:153], v243 offset:17408
	ds_read_b128 v[158:161], v243 offset:18432
	ds_read_b128 v[182:185], v243 offset:19456
	ds_read_b128 v[186:189], v193
	ds_read_b128 v[194:197], v193 offset:1024
	ds_read_b128 v[198:201], v193 offset:2048
	ds_read_b128 v[214:217], v193 offset:3072
	ds_read_b128 v[218:221], v193 offset:4096
	ds_read_b128 v[222:225], v193 offset:5120
	ds_read_b128 v[226:229], v193 offset:6144
	ds_read_b128 v[230:233], v193 offset:7168
	s_mov_b64 s[12:13], 0xb0000
	s_mov_b64 s[86:87], 0x108000
	s_mov_b64 s[96:97], 0x58080
	s_mov_b64 vcc, 0xb0080
	s_mov_b64 s[0:1], 0x108080
	s_cmp_eq_u64 s[40:41], 0
	s_cbranch_scc0 .Lpr_446
	s_setprio 1

.Lmid1_446:
	s_add_i32 s22, 0, 0x10000
	s_add_i32 s23, 0, 0x14000
	s_add_u32 s20, s56, 0xfff50080
	s_addc_u32 s21, s57, -1
	s_cmp_eq_u32 s84, 40
	s_cselect_b32 s61, s49, s21
	s_cselect_b32 s60, s48, s20
	s_cselect_b32 s21, s51, s63
	s_cselect_b32 s20, s50, s62
	s_add_i32 m0, s47, 0xc000
	v_lshl_add_u64 v[162:163], s[56:57], 0, v[156:157]
	global_load_lds_dwordx4 v[162:163], off
	v_lshl_add_u64 v[162:163], v[162:163], 0, s[2:3]
	s_add_i32 m0, s47, 0xe000
	s_nop 0
	global_load_lds_dwordx4 v[162:163], off
	s_waitcnt vmcnt(8) lgkmcnt(0)
	s_barrier
	v_mfma_f32_16x16x32_bf16 v[142:145], v[114:117], v[186:189], 0
	v_mfma_f32_16x16x32_bf16 v[142:145], v[126:129], v[194:197], v[142:145]
	v_mfma_f32_16x16x32_bf16 v[138:141], v[130:133], v[186:189], 0
	v_mfma_f32_16x16x32_bf16 v[138:141], v[134:137], v[194:197], v[138:141]
	v_mfma_f32_16x16x32_bf16 v[110:113], v[114:117], v[198:201], 0
	v_mfma_f32_16x16x32_bf16 v[110:113], v[126:129], v[214:217], v[110:113]
	v_mfma_f32_16x16x32_bf16 v[106:109], v[130:133], v[198:201], 0
	v_mfma_f32_16x16x32_bf16 v[106:109], v[134:137], v[214:217], v[106:109]
	v_mfma_f32_16x16x32_bf16 v[94:97], v[114:117], v[218:221], 0
	v_mfma_f32_16x16x32_bf16 v[94:97], v[126:129], v[222:225], v[94:97]
	v_mfma_f32_16x16x32_bf16 v[90:93], v[130:133], v[218:221], 0
	v_mfma_f32_16x16x32_bf16 v[90:93], v[134:137], v[222:225], v[90:93]
	v_mfma_f32_16x16x32_bf16 v[78:81], v[114:117], v[226:229], 0
	v_mfma_f32_16x16x32_bf16 v[78:81], v[126:129], v[230:233], v[78:81]
	v_mfma_f32_16x16x32_bf16 v[74:77], v[130:133], v[226:229], 0
	v_mfma_f32_16x16x32_bf16 v[74:77], v[134:137], v[230:233], v[74:77]
	v_mfma_f32_16x16x32_bf16 v[122:125], v[146:149], v[186:189], 0
	v_mfma_f32_16x16x32_bf16 v[122:125], v[150:153], v[194:197], v[122:125]
	v_mfma_f32_16x16x32_bf16 v[118:121], v[158:161], v[186:189], 0
	v_mfma_f32_16x16x32_bf16 v[118:121], v[182:185], v[194:197], v[118:121]
	v_mfma_f32_16x16x32_bf16 v[102:105], v[146:149], v[198:201], 0
	v_mfma_f32_16x16x32_bf16 v[102:105], v[150:153], v[214:217], v[102:105]
	v_mfma_f32_16x16x32_bf16 v[98:101], v[158:161], v[198:201], 0
	v_mfma_f32_16x16x32_bf16 v[98:101], v[182:185], v[214:217], v[98:101]
	v_mfma_f32_16x16x32_bf16 v[86:89], v[146:149], v[218:221], 0
	v_mfma_f32_16x16x32_bf16 v[86:89], v[150:153], v[222:225], v[86:89]
	v_mfma_f32_16x16x32_bf16 v[82:85], v[158:161], v[218:221], 0
	v_mfma_f32_16x16x32_bf16 v[82:85], v[182:185], v[222:225], v[82:85]
	v_mfma_f32_16x16x32_bf16 v[70:73], v[146:149], v[226:229], 0
	v_mfma_f32_16x16x32_bf16 v[70:73], v[150:153], v[230:233], v[70:73]
	v_mfma_f32_16x16x32_bf16 v[66:69], v[158:161], v[226:229], 0
	v_mfma_f32_16x16x32_bf16 v[66:69], v[182:185], v[230:233], v[66:69]
	s_barrier
	ds_read_b128 v[186:189], v193 offset:16384
	ds_read_b128 v[194:197], v193 offset:17408
	ds_read_b128 v[198:201], v193 offset:18432
	ds_read_b128 v[214:217], v193 offset:19456
	ds_read_b128 v[218:221], v193 offset:20480
	ds_read_b128 v[222:225], v193 offset:21504
	ds_read_b128 v[226:229], v193 offset:22528
	ds_read_b128 v[230:233], v193 offset:23552
	v_lshl_add_u64 v[162:163], s[20:21], 0, v[0:1]
	s_add_i32 s20, s22, s46
	s_mov_b32 m0, s20
	s_nop 0
	s_nop 0
	global_load_lds_dwordx4 v[162:163], off
	v_lshl_add_u64 v[202:203], v[162:163], 0, s[2:3]
	s_add_i32 m0, s20, 0x2000
	s_add_i32 s20, s23, s46
	global_load_lds_dwordx4 v[202:203], off
	v_lshl_add_u64 v[202:203], v[162:163], 0, s[12:13]
	s_mov_b32 m0, s20
	s_nop 0
	global_load_lds_dwordx4 v[202:203], off
	v_lshl_add_u64 v[202:203], v[162:163], 0, s[86:87]
	s_add_i32 m0, s20, 0x2000
	s_nop 0
	global_load_lds_dwordx4 v[202:203], off
	v_lshl_add_u64 v[202:203], s[60:61], 0, v[154:155]
	s_mov_b32 m0, s47
	v_lshl_add_u64 v[234:235], v[202:203], 0, s[2:3]
	global_load_lds_dwordx4 v[202:203], off
	s_mov_b32 m0, s68
	s_nop 0
	global_load_lds_dwordx4 v[234:235], off
	s_waitcnt vmcnt(8) lgkmcnt(0)
	s_barrier
	v_mfma_f32_16x16x32_bf16 v[62:65], v[114:117], v[186:189], 0
	v_mfma_f32_16x16x32_bf16 v[62:65], v[126:129], v[194:197], v[62:65]
	v_mfma_f32_16x16x32_bf16 v[58:61], v[130:133], v[186:189], 0
	v_mfma_f32_16x16x32_bf16 v[58:61], v[134:137], v[194:197], v[58:61]
	v_mfma_f32_16x16x32_bf16 v[46:49], v[114:117], v[198:201], 0
	v_mfma_f32_16x16x32_bf16 v[46:49], v[126:129], v[214:217], v[46:49]
	v_mfma_f32_16x16x32_bf16 v[42:45], v[130:133], v[198:201], 0
	v_mfma_f32_16x16x32_bf16 v[42:45], v[134:137], v[214:217], v[42:45]
	v_mfma_f32_16x16x32_bf16 v[30:33], v[114:117], v[218:221], 0
	v_mfma_f32_16x16x32_bf16 v[30:33], v[126:129], v[222:225], v[30:33]
	v_mfma_f32_16x16x32_bf16 v[26:29], v[130:133], v[218:221], 0
	v_mfma_f32_16x16x32_bf16 v[26:29], v[134:137], v[222:225], v[26:29]
	v_mfma_f32_16x16x32_bf16 v[14:17], v[114:117], v[226:229], 0
	v_mfma_f32_16x16x32_bf16 v[14:17], v[126:129], v[230:233], v[14:17]
	v_mfma_f32_16x16x32_bf16 v[10:13], v[130:133], v[226:229], 0
	v_mfma_f32_16x16x32_bf16 v[10:13], v[134:137], v[230:233], v[10:13]
	v_mfma_f32_16x16x32_bf16 v[54:57], v[146:149], v[186:189], 0
	v_mfma_f32_16x16x32_bf16 v[54:57], v[150:153], v[194:197], v[54:57]
	v_mfma_f32_16x16x32_bf16 v[50:53], v[158:161], v[186:189], 0
	v_mfma_f32_16x16x32_bf16 v[50:53], v[182:185], v[194:197], v[50:53]
	v_mfma_f32_16x16x32_bf16 v[38:41], v[146:149], v[198:201], 0
	v_mfma_f32_16x16x32_bf16 v[38:41], v[150:153], v[214:217], v[38:41]
	v_mfma_f32_16x16x32_bf16 v[34:37], v[158:161], v[198:201], 0
	v_mfma_f32_16x16x32_bf16 v[34:37], v[182:185], v[214:217], v[34:37]
	v_mfma_f32_16x16x32_bf16 v[22:25], v[146:149], v[218:221], 0
	v_mfma_f32_16x16x32_bf16 v[22:25], v[150:153], v[222:225], v[22:25]
	v_mfma_f32_16x16x32_bf16 v[18:21], v[158:161], v[218:221], 0
	v_mfma_f32_16x16x32_bf16 v[18:21], v[182:185], v[222:225], v[18:21]
	v_mfma_f32_16x16x32_bf16 v[6:9], v[146:149], v[226:229], 0
	v_mfma_f32_16x16x32_bf16 v[6:9], v[150:153], v[230:233], v[6:9]
	v_mfma_f32_16x16x32_bf16 v[2:5], v[158:161], v[226:229], 0
	v_mfma_f32_16x16x32_bf16 v[2:5], v[182:185], v[230:233], v[2:5]
	s_barrier
	s_add_i32 s20, 0, 0x18000
	s_add_i32 s21, 0, 0x1c000
	ds_read_b128 v[114:117], v243 offset:32768
	ds_read_b128 v[126:129], v243 offset:33792
	ds_read_b128 v[130:133], v243 offset:34816
	ds_read_b128 v[134:137], v243 offset:35840
	ds_read_b128 v[146:149], v243 offset:49152
	ds_read_b128 v[150:153], v243 offset:50176
	ds_read_b128 v[158:161], v243 offset:51200
	ds_read_b128 v[182:185], v243 offset:52224
	ds_read_b128 v[186:189], v193 offset:32768
	ds_read_b128 v[194:197], v193 offset:33792
	ds_read_b128 v[198:201], v193 offset:34816
	ds_read_b128 v[214:217], v193 offset:35840
	ds_read_b128 v[218:221], v193 offset:36864
	ds_read_b128 v[222:225], v193 offset:37888
	ds_read_b128 v[226:229], v193 offset:38912
	ds_read_b128 v[230:233], v193 offset:39936
	s_mov_b32 m0, s69
	v_lshl_add_u64 v[234:235], v[202:203], 0, s[12:13]
	global_load_lds_dwordx4 v[234:235], off
	v_lshl_add_u64 v[234:235], v[202:203], 0, s[86:87]
	s_mov_b32 m0, s76
	s_nop 0
	global_load_lds_dwordx4 v[234:235], off
	s_waitcnt vmcnt(8) lgkmcnt(0)
	s_barrier
	v_mfma_f32_16x16x32_bf16 v[142:145], v[114:117], v[186:189], v[142:145]
	v_mfma_f32_16x16x32_bf16 v[142:145], v[126:129], v[194:197], v[142:145]
	v_mfma_f32_16x16x32_bf16 v[138:141], v[130:133], v[186:189], v[138:141]
	v_mfma_f32_16x16x32_bf16 v[138:141], v[134:137], v[194:197], v[138:141]
	v_mfma_f32_16x16x32_bf16 v[110:113], v[114:117], v[198:201], v[110:113]
	v_mfma_f32_16x16x32_bf16 v[110:113], v[126:129], v[214:217], v[110:113]
	v_mfma_f32_16x16x32_bf16 v[106:109], v[130:133], v[198:201], v[106:109]
	v_mfma_f32_16x16x32_bf16 v[106:109], v[134:137], v[214:217], v[106:109]
	v_mfma_f32_16x16x32_bf16 v[94:97], v[114:117], v[218:221], v[94:97]
	v_mfma_f32_16x16x32_bf16 v[94:97], v[126:129], v[222:225], v[94:97]
	v_mfma_f32_16x16x32_bf16 v[90:93], v[130:133], v[218:221], v[90:93]
	v_mfma_f32_16x16x32_bf16 v[90:93], v[134:137], v[222:225], v[90:93]
	v_mfma_f32_16x16x32_bf16 v[78:81], v[114:117], v[226:229], v[78:81]
	v_mfma_f32_16x16x32_bf16 v[78:81], v[126:129], v[230:233], v[78:81]
	v_mfma_f32_16x16x32_bf16 v[74:77], v[130:133], v[226:229], v[74:77]
	v_mfma_f32_16x16x32_bf16 v[74:77], v[134:137], v[230:233], v[74:77]
	v_mfma_f32_16x16x32_bf16 v[122:125], v[146:149], v[186:189], v[122:125]
	v_mfma_f32_16x16x32_bf16 v[122:125], v[150:153], v[194:197], v[122:125]
	v_mfma_f32_16x16x32_bf16 v[118:121], v[158:161], v[186:189], v[118:121]
	v_mfma_f32_16x16x32_bf16 v[118:121], v[182:185], v[194:197], v[118:121]
	v_mfma_f32_16x16x32_bf16 v[102:105], v[146:149], v[198:201], v[102:105]
	v_mfma_f32_16x16x32_bf16 v[102:105], v[150:153], v[214:217], v[102:105]
	v_mfma_f32_16x16x32_bf16 v[98:101], v[158:161], v[198:201], v[98:101]
	v_mfma_f32_16x16x32_bf16 v[98:101], v[182:185], v[214:217], v[98:101]
	v_mfma_f32_16x16x32_bf16 v[86:89], v[146:149], v[218:221], v[86:89]
	v_mfma_f32_16x16x32_bf16 v[86:89], v[150:153], v[222:225], v[86:89]
	v_mfma_f32_16x16x32_bf16 v[82:85], v[158:161], v[218:221], v[82:85]
	v_mfma_f32_16x16x32_bf16 v[82:85], v[182:185], v[222:225], v[82:85]
	v_mfma_f32_16x16x32_bf16 v[70:73], v[146:149], v[226:229], v[70:73]
	v_mfma_f32_16x16x32_bf16 v[70:73], v[150:153], v[230:233], v[70:73]
	v_mfma_f32_16x16x32_bf16 v[66:69], v[158:161], v[226:229], v[66:69]
	v_mfma_f32_16x16x32_bf16 v[66:69], v[182:185], v[230:233], v[66:69]
	s_barrier
	ds_read_b128 v[186:189], v193 offset:49152
	ds_read_b128 v[194:197], v193 offset:50176
	ds_read_b128 v[198:201], v193 offset:51200
	ds_read_b128 v[214:217], v193 offset:52224
	ds_read_b128 v[218:221], v193 offset:53248
	ds_read_b128 v[222:225], v193 offset:54272
	ds_read_b128 v[226:229], v193 offset:55296
	ds_read_b128 v[230:233], v193 offset:56320
	s_add_i32 s20, s20, s46
	s_mov_b32 m0, s20
	v_lshl_add_u64 v[234:235], v[162:163], 0, s[34:35]
	global_load_lds_dwordx4 v[234:235], off
	v_lshl_add_u64 v[234:235], v[162:163], 0, s[96:97]
	s_add_i32 m0, s20, 0x2000
	s_add_i32 s20, s21, s46
	global_load_lds_dwordx4 v[234:235], off
	v_lshl_add_u64 v[234:235], v[162:163], 0, vcc
	s_mov_b32 m0, s20
	v_lshl_add_u64 v[162:163], v[162:163], 0, s[0:1]
	global_load_lds_dwordx4 v[234:235], off
	s_add_i32 m0, s20, 0x2000
	s_nop 0
	global_load_lds_dwordx4 v[162:163], off
	v_lshl_add_u64 v[162:163], v[202:203], 0, s[34:35]
	s_mov_b32 m0, s77
	s_nop 0
	global_load_lds_dwordx4 v[162:163], off
	v_lshl_add_u64 v[162:163], v[202:203], 0, s[96:97]
	s_mov_b32 m0, s78
	s_nop 0
	global_load_lds_dwordx4 v[162:163], off
	s_waitcnt vmcnt(8) lgkmcnt(0)
	s_barrier
	v_mfma_f32_16x16x32_bf16 v[62:65], v[114:117], v[186:189], v[62:65]
	v_mfma_f32_16x16x32_bf16 v[62:65], v[126:129], v[194:197], v[62:65]
	v_mfma_f32_16x16x32_bf16 v[58:61], v[130:133], v[186:189], v[58:61]
	v_mfma_f32_16x16x32_bf16 v[58:61], v[134:137], v[194:197], v[58:61]
	v_mfma_f32_16x16x32_bf16 v[46:49], v[114:117], v[198:201], v[46:49]
	v_mfma_f32_16x16x32_bf16 v[46:49], v[126:129], v[214:217], v[46:49]
	v_mfma_f32_16x16x32_bf16 v[42:45], v[130:133], v[198:201], v[42:45]
	v_mfma_f32_16x16x32_bf16 v[42:45], v[134:137], v[214:217], v[42:45]
	v_mfma_f32_16x16x32_bf16 v[30:33], v[114:117], v[218:221], v[30:33]
	v_mfma_f32_16x16x32_bf16 v[30:33], v[126:129], v[222:225], v[30:33]
	v_mfma_f32_16x16x32_bf16 v[26:29], v[130:133], v[218:221], v[26:29]
	v_mfma_f32_16x16x32_bf16 v[26:29], v[134:137], v[222:225], v[26:29]
	v_mfma_f32_16x16x32_bf16 v[14:17], v[114:117], v[226:229], v[14:17]
	v_mfma_f32_16x16x32_bf16 v[14:17], v[126:129], v[230:233], v[14:17]
	v_mfma_f32_16x16x32_bf16 v[10:13], v[130:133], v[226:229], v[10:13]
	v_mfma_f32_16x16x32_bf16 v[10:13], v[134:137], v[230:233], v[10:13]
	s_add_i32 s84, s84, 2
	s_add_u32 s56, s56, 0x100
	s_addc_u32 s57, s57, 0
	s_add_u32 s62, s62, 0x100
	s_addc_u32 s63, s63, 0
	v_mfma_f32_16x16x32_bf16 v[54:57], v[146:149], v[186:189], v[54:57]
	v_mfma_f32_16x16x32_bf16 v[54:57], v[150:153], v[194:197], v[54:57]
	v_mfma_f32_16x16x32_bf16 v[50:53], v[158:161], v[186:189], v[50:53]
	v_mfma_f32_16x16x32_bf16 v[50:53], v[182:185], v[194:197], v[50:53]
	v_mfma_f32_16x16x32_bf16 v[38:41], v[146:149], v[198:201], v[38:41]
	v_mfma_f32_16x16x32_bf16 v[38:41], v[150:153], v[214:217], v[38:41]
	v_mfma_f32_16x16x32_bf16 v[34:37], v[158:161], v[198:201], v[34:37]
	v_mfma_f32_16x16x32_bf16 v[34:37], v[182:185], v[214:217], v[34:37]
	v_mfma_f32_16x16x32_bf16 v[22:25], v[146:149], v[218:221], v[22:25]
	v_mfma_f32_16x16x32_bf16 v[22:25], v[150:153], v[222:225], v[22:25]
	v_mfma_f32_16x16x32_bf16 v[18:21], v[158:161], v[218:221], v[18:21]
	v_mfma_f32_16x16x32_bf16 v[18:21], v[182:185], v[222:225], v[18:21]
	v_mfma_f32_16x16x32_bf16 v[6:9], v[146:149], v[226:229], v[6:9]
	v_mfma_f32_16x16x32_bf16 v[6:9], v[150:153], v[230:233], v[6:9]
	v_mfma_f32_16x16x32_bf16 v[2:5], v[158:161], v[226:229], v[2:5]
	v_mfma_f32_16x16x32_bf16 v[2:5], v[182:185], v[230:233], v[2:5]
	s_barrier
	s_branch .LBB0_446
	.p2alignl 6, 3212836864
.LBB0_446:
	s_add_i32 s22, 0, 0x10000
	s_add_i32 s23, 0, 0x14000
	ds_read_b128 v[114:117], v243
	ds_read_b128 v[126:129], v243 offset:1024
	ds_read_b128 v[130:133], v243 offset:2048
	ds_read_b128 v[134:137], v243 offset:3072
	ds_read_b128 v[146:149], v243 offset:16384
	ds_read_b128 v[150:153], v243 offset:17408
	ds_read_b128 v[158:161], v243 offset:18432
	ds_read_b128 v[182:185], v243 offset:19456
	ds_read_b128 v[186:189], v193
	ds_read_b128 v[194:197], v193 offset:1024
	ds_read_b128 v[198:201], v193 offset:2048
	ds_read_b128 v[214:217], v193 offset:3072
	ds_read_b128 v[218:221], v193 offset:4096
	ds_read_b128 v[222:225], v193 offset:5120
	ds_read_b128 v[226:229], v193 offset:6144
	ds_read_b128 v[230:233], v193 offset:7168
	s_add_u32 s20, s56, 0xfff50080
	s_addc_u32 s21, s57, -1
	s_cmp_eq_u32 s84, 40
	s_cselect_b32 s61, s49, s21
	s_cselect_b32 s60, s48, s20
	s_cselect_b32 s21, s51, s63
	s_cselect_b32 s20, s50, s62
	s_add_i32 m0, s47, 0xc000
	v_lshl_add_u64 v[162:163], s[56:57], 0, v[156:157]
	global_load_lds_dwordx4 v[162:163], off
	v_lshl_add_u64 v[162:163], v[162:163], 0, s[2:3]
	s_add_i32 m0, s47, 0xe000
	s_nop 0
	global_load_lds_dwordx4 v[162:163], off
	s_waitcnt vmcnt(8) lgkmcnt(0)
	s_barrier
	v_mfma_f32_16x16x32_bf16 v[142:145], v[114:117], v[186:189], v[142:145]
	v_mfma_f32_16x16x32_bf16 v[142:145], v[126:129], v[194:197], v[142:145]
	v_mfma_f32_16x16x32_bf16 v[138:141], v[130:133], v[186:189], v[138:141]
	v_mfma_f32_16x16x32_bf16 v[138:141], v[134:137], v[194:197], v[138:141]
	v_mfma_f32_16x16x32_bf16 v[110:113], v[114:117], v[198:201], v[110:113]
	v_mfma_f32_16x16x32_bf16 v[110:113], v[126:129], v[214:217], v[110:113]
	v_mfma_f32_16x16x32_bf16 v[106:109], v[130:133], v[198:201], v[106:109]
	v_mfma_f32_16x16x32_bf16 v[106:109], v[134:137], v[214:217], v[106:109]
	v_mfma_f32_16x16x32_bf16 v[94:97], v[114:117], v[218:221], v[94:97]
	v_mfma_f32_16x16x32_bf16 v[94:97], v[126:129], v[222:225], v[94:97]
	v_mfma_f32_16x16x32_bf16 v[90:93], v[130:133], v[218:221], v[90:93]
	v_mfma_f32_16x16x32_bf16 v[90:93], v[134:137], v[222:225], v[90:93]
	v_mfma_f32_16x16x32_bf16 v[78:81], v[114:117], v[226:229], v[78:81]
	v_mfma_f32_16x16x32_bf16 v[78:81], v[126:129], v[230:233], v[78:81]
	v_mfma_f32_16x16x32_bf16 v[74:77], v[130:133], v[226:229], v[74:77]
	v_mfma_f32_16x16x32_bf16 v[74:77], v[134:137], v[230:233], v[74:77]
	v_mfma_f32_16x16x32_bf16 v[122:125], v[146:149], v[186:189], v[122:125]
	v_mfma_f32_16x16x32_bf16 v[122:125], v[150:153], v[194:197], v[122:125]
	v_mfma_f32_16x16x32_bf16 v[118:121], v[158:161], v[186:189], v[118:121]
	v_mfma_f32_16x16x32_bf16 v[118:121], v[182:185], v[194:197], v[118:121]
	v_mfma_f32_16x16x32_bf16 v[102:105], v[146:149], v[198:201], v[102:105]
	v_mfma_f32_16x16x32_bf16 v[102:105], v[150:153], v[214:217], v[102:105]
	v_mfma_f32_16x16x32_bf16 v[98:101], v[158:161], v[198:201], v[98:101]
	v_mfma_f32_16x16x32_bf16 v[98:101], v[182:185], v[214:217], v[98:101]
	v_mfma_f32_16x16x32_bf16 v[86:89], v[146:149], v[218:221], v[86:89]
	v_mfma_f32_16x16x32_bf16 v[86:89], v[150:153], v[222:225], v[86:89]
	v_mfma_f32_16x16x32_bf16 v[82:85], v[158:161], v[218:221], v[82:85]
	v_mfma_f32_16x16x32_bf16 v[82:85], v[182:185], v[222:225], v[82:85]
	v_mfma_f32_16x16x32_bf16 v[70:73], v[146:149], v[226:229], v[70:73]
	v_mfma_f32_16x16x32_bf16 v[70:73], v[150:153], v[230:233], v[70:73]
	v_mfma_f32_16x16x32_bf16 v[66:69], v[158:161], v[226:229], v[66:69]
	v_mfma_f32_16x16x32_bf16 v[66:69], v[182:185], v[230:233], v[66:69]
	s_barrier
	ds_read_b128 v[186:189], v193 offset:16384
	ds_read_b128 v[194:197], v193 offset:17408
	ds_read_b128 v[198:201], v193 offset:18432
	ds_read_b128 v[214:217], v193 offset:19456
	ds_read_b128 v[218:221], v193 offset:20480
	ds_read_b128 v[222:225], v193 offset:21504
	ds_read_b128 v[226:229], v193 offset:22528
	ds_read_b128 v[230:233], v193 offset:23552
	v_lshl_add_u64 v[162:163], s[20:21], 0, v[0:1]
	s_add_i32 s20, s22, s46
	s_mov_b32 m0, s20
	s_nop 0
	s_nop 0
	global_load_lds_dwordx4 v[162:163], off
	v_lshl_add_u64 v[202:203], v[162:163], 0, s[2:3]
	s_add_i32 m0, s20, 0x2000
	s_add_i32 s20, s23, s46
	global_load_lds_dwordx4 v[202:203], off
	v_lshl_add_u64 v[202:203], v[162:163], 0, s[12:13]
	s_mov_b32 m0, s20
	s_nop 0
	global_load_lds_dwordx4 v[202:203], off
	v_lshl_add_u64 v[202:203], v[162:163], 0, s[86:87]
	s_add_i32 m0, s20, 0x2000
	s_nop 0
	global_load_lds_dwordx4 v[202:203], off
	v_lshl_add_u64 v[202:203], s[60:61], 0, v[154:155]
	s_mov_b32 m0, s47
	v_lshl_add_u64 v[234:235], v[202:203], 0, s[2:3]
	global_load_lds_dwordx4 v[202:203], off
	s_mov_b32 m0, s68
	s_nop 0
	global_load_lds_dwordx4 v[234:235], off
	s_waitcnt vmcnt(8) lgkmcnt(0)
	s_barrier
	v_mfma_f32_16x16x32_bf16 v[62:65], v[114:117], v[186:189], v[62:65]
	v_mfma_f32_16x16x32_bf16 v[62:65], v[126:129], v[194:197], v[62:65]
	v_mfma_f32_16x16x32_bf16 v[58:61], v[130:133], v[186:189], v[58:61]
	v_mfma_f32_16x16x32_bf16 v[58:61], v[134:137], v[194:197], v[58:61]
	v_mfma_f32_16x16x32_bf16 v[46:49], v[114:117], v[198:201], v[46:49]
	v_mfma_f32_16x16x32_bf16 v[46:49], v[126:129], v[214:217], v[46:49]
	v_mfma_f32_16x16x32_bf16 v[42:45], v[130:133], v[198:201], v[42:45]
	v_mfma_f32_16x16x32_bf16 v[42:45], v[134:137], v[214:217], v[42:45]
	v_mfma_f32_16x16x32_bf16 v[30:33], v[114:117], v[218:221], v[30:33]
	v_mfma_f32_16x16x32_bf16 v[30:33], v[126:129], v[222:225], v[30:33]
	v_mfma_f32_16x16x32_bf16 v[26:29], v[130:133], v[218:221], v[26:29]
	v_mfma_f32_16x16x32_bf16 v[26:29], v[134:137], v[222:225], v[26:29]
	v_mfma_f32_16x16x32_bf16 v[14:17], v[114:117], v[226:229], v[14:17]
	v_mfma_f32_16x16x32_bf16 v[14:17], v[126:129], v[230:233], v[14:17]
	v_mfma_f32_16x16x32_bf16 v[10:13], v[130:133], v[226:229], v[10:13]
	v_mfma_f32_16x16x32_bf16 v[10:13], v[134:137], v[230:233], v[10:13]
	v_mfma_f32_16x16x32_bf16 v[54:57], v[146:149], v[186:189], v[54:57]
	v_mfma_f32_16x16x32_bf16 v[54:57], v[150:153], v[194:197], v[54:57]
	v_mfma_f32_16x16x32_bf16 v[50:53], v[158:161], v[186:189], v[50:53]
	v_mfma_f32_16x16x32_bf16 v[50:53], v[182:185], v[194:197], v[50:53]
	v_mfma_f32_16x16x32_bf16 v[38:41], v[146:149], v[198:201], v[38:41]
	v_mfma_f32_16x16x32_bf16 v[38:41], v[150:153], v[214:217], v[38:41]
	v_mfma_f32_16x16x32_bf16 v[34:37], v[158:161], v[198:201], v[34:37]
	v_mfma_f32_16x16x32_bf16 v[34:37], v[182:185], v[214:217], v[34:37]
	v_mfma_f32_16x16x32_bf16 v[22:25], v[146:149], v[218:221], v[22:25]
	v_mfma_f32_16x16x32_bf16 v[22:25], v[150:153], v[222:225], v[22:25]
	v_mfma_f32_16x16x32_bf16 v[18:21], v[158:161], v[218:221], v[18:21]
	v_mfma_f32_16x16x32_bf16 v[18:21], v[182:185], v[222:225], v[18:21]
	v_mfma_f32_16x16x32_bf16 v[6:9], v[146:149], v[226:229], v[6:9]
	v_mfma_f32_16x16x32_bf16 v[6:9], v[150:153], v[230:233], v[6:9]
	v_mfma_f32_16x16x32_bf16 v[2:5], v[158:161], v[226:229], v[2:5]
	v_mfma_f32_16x16x32_bf16 v[2:5], v[182:185], v[230:233], v[2:5]
	s_barrier
	s_add_i32 s20, 0, 0x18000
	s_add_i32 s21, 0, 0x1c000
	ds_read_b128 v[114:117], v243 offset:32768
	ds_read_b128 v[126:129], v243 offset:33792
	ds_read_b128 v[130:133], v243 offset:34816
	ds_read_b128 v[134:137], v243 offset:35840
	ds_read_b128 v[146:149], v243 offset:49152
	ds_read_b128 v[150:153], v243 offset:50176
	ds_read_b128 v[158:161], v243 offset:51200
	ds_read_b128 v[182:185], v243 offset:52224
	ds_read_b128 v[186:189], v193 offset:32768
	ds_read_b128 v[194:197], v193 offset:33792
	ds_read_b128 v[198:201], v193 offset:34816
	ds_read_b128 v[214:217], v193 offset:35840
	ds_read_b128 v[218:221], v193 offset:36864
	ds_read_b128 v[222:225], v193 offset:37888
	ds_read_b128 v[226:229], v193 offset:38912
	ds_read_b128 v[230:233], v193 offset:39936
	s_mov_b32 m0, s69
	v_lshl_add_u64 v[234:235], v[202:203], 0, s[12:13]
	global_load_lds_dwordx4 v[234:235], off
	v_lshl_add_u64 v[234:235], v[202:203], 0, s[86:87]
	s_mov_b32 m0, s76
	s_nop 0
	global_load_lds_dwordx4 v[234:235], off
	s_waitcnt vmcnt(8) lgkmcnt(0)
	s_barrier
	v_mfma_f32_16x16x32_bf16 v[142:145], v[114:117], v[186:189], v[142:145]
	v_mfma_f32_16x16x32_bf16 v[142:145], v[126:129], v[194:197], v[142:145]
	v_mfma_f32_16x16x32_bf16 v[138:141], v[130:133], v[186:189], v[138:141]
	v_mfma_f32_16x16x32_bf16 v[138:141], v[134:137], v[194:197], v[138:141]
	v_mfma_f32_16x16x32_bf16 v[110:113], v[114:117], v[198:201], v[110:113]
	v_mfma_f32_16x16x32_bf16 v[110:113], v[126:129], v[214:217], v[110:113]
	v_mfma_f32_16x16x32_bf16 v[106:109], v[130:133], v[198:201], v[106:109]
	v_mfma_f32_16x16x32_bf16 v[106:109], v[134:137], v[214:217], v[106:109]
	v_mfma_f32_16x16x32_bf16 v[94:97], v[114:117], v[218:221], v[94:97]
	v_mfma_f32_16x16x32_bf16 v[94:97], v[126:129], v[222:225], v[94:97]
	v_mfma_f32_16x16x32_bf16 v[90:93], v[130:133], v[218:221], v[90:93]
	v_mfma_f32_16x16x32_bf16 v[90:93], v[134:137], v[222:225], v[90:93]
	v_mfma_f32_16x16x32_bf16 v[78:81], v[114:117], v[226:229], v[78:81]
	v_mfma_f32_16x16x32_bf16 v[78:81], v[126:129], v[230:233], v[78:81]
	v_mfma_f32_16x16x32_bf16 v[74:77], v[130:133], v[226:229], v[74:77]
	v_mfma_f32_16x16x32_bf16 v[74:77], v[134:137], v[230:233], v[74:77]
	v_mfma_f32_16x16x32_bf16 v[122:125], v[146:149], v[186:189], v[122:125]
	v_mfma_f32_16x16x32_bf16 v[122:125], v[150:153], v[194:197], v[122:125]
	v_mfma_f32_16x16x32_bf16 v[118:121], v[158:161], v[186:189], v[118:121]
	v_mfma_f32_16x16x32_bf16 v[118:121], v[182:185], v[194:197], v[118:121]
	v_mfma_f32_16x16x32_bf16 v[102:105], v[146:149], v[198:201], v[102:105]
	v_mfma_f32_16x16x32_bf16 v[102:105], v[150:153], v[214:217], v[102:105]
	v_mfma_f32_16x16x32_bf16 v[98:101], v[158:161], v[198:201], v[98:101]
	v_mfma_f32_16x16x32_bf16 v[98:101], v[182:185], v[214:217], v[98:101]
	v_mfma_f32_16x16x32_bf16 v[86:89], v[146:149], v[218:221], v[86:89]
	v_mfma_f32_16x16x32_bf16 v[86:89], v[150:153], v[222:225], v[86:89]
	v_mfma_f32_16x16x32_bf16 v[82:85], v[158:161], v[218:221], v[82:85]
	v_mfma_f32_16x16x32_bf16 v[82:85], v[182:185], v[222:225], v[82:85]
	v_mfma_f32_16x16x32_bf16 v[70:73], v[146:149], v[226:229], v[70:73]
	v_mfma_f32_16x16x32_bf16 v[70:73], v[150:153], v[230:233], v[70:73]
	v_mfma_f32_16x16x32_bf16 v[66:69], v[158:161], v[226:229], v[66:69]
	v_mfma_f32_16x16x32_bf16 v[66:69], v[182:185], v[230:233], v[66:69]
	s_barrier
	ds_read_b128 v[186:189], v193 offset:49152
	ds_read_b128 v[194:197], v193 offset:50176
	ds_read_b128 v[198:201], v193 offset:51200
	ds_read_b128 v[214:217], v193 offset:52224
	ds_read_b128 v[218:221], v193 offset:53248
	ds_read_b128 v[222:225], v193 offset:54272
	ds_read_b128 v[226:229], v193 offset:55296
	ds_read_b128 v[230:233], v193 offset:56320
	s_add_i32 s20, s20, s46
	s_mov_b32 m0, s20
	v_lshl_add_u64 v[234:235], v[162:163], 0, s[34:35]
	global_load_lds_dwordx4 v[234:235], off
	v_lshl_add_u64 v[234:235], v[162:163], 0, s[96:97]
	s_add_i32 m0, s20, 0x2000
	s_add_i32 s20, s21, s46
	global_load_lds_dwordx4 v[234:235], off
	v_lshl_add_u64 v[234:235], v[162:163], 0, vcc
	s_mov_b32 m0, s20
	v_lshl_add_u64 v[162:163], v[162:163], 0, s[0:1]
	global_load_lds_dwordx4 v[234:235], off
	s_add_i32 m0, s20, 0x2000
	s_nop 0
	global_load_lds_dwordx4 v[162:163], off
	v_lshl_add_u64 v[162:163], v[202:203], 0, s[34:35]
	s_mov_b32 m0, s77
	s_nop 0
	global_load_lds_dwordx4 v[162:163], off
	v_lshl_add_u64 v[162:163], v[202:203], 0, s[96:97]
	s_mov_b32 m0, s78
	s_nop 0
	global_load_lds_dwordx4 v[162:163], off
	s_waitcnt vmcnt(8) lgkmcnt(0)
	s_barrier
	v_mfma_f32_16x16x32_bf16 v[62:65], v[114:117], v[186:189], v[62:65]
	v_mfma_f32_16x16x32_bf16 v[62:65], v[126:129], v[194:197], v[62:65]
	v_mfma_f32_16x16x32_bf16 v[58:61], v[130:133], v[186:189], v[58:61]
	v_mfma_f32_16x16x32_bf16 v[58:61], v[134:137], v[194:197], v[58:61]
	v_mfma_f32_16x16x32_bf16 v[46:49], v[114:117], v[198:201], v[46:49]
	v_mfma_f32_16x16x32_bf16 v[46:49], v[126:129], v[214:217], v[46:49]
	v_mfma_f32_16x16x32_bf16 v[42:45], v[130:133], v[198:201], v[42:45]
	v_mfma_f32_16x16x32_bf16 v[42:45], v[134:137], v[214:217], v[42:45]
	v_mfma_f32_16x16x32_bf16 v[30:33], v[114:117], v[218:221], v[30:33]
	v_mfma_f32_16x16x32_bf16 v[30:33], v[126:129], v[222:225], v[30:33]
	v_mfma_f32_16x16x32_bf16 v[26:29], v[130:133], v[218:221], v[26:29]
	v_mfma_f32_16x16x32_bf16 v[26:29], v[134:137], v[222:225], v[26:29]
	v_mfma_f32_16x16x32_bf16 v[14:17], v[114:117], v[226:229], v[14:17]
	v_mfma_f32_16x16x32_bf16 v[14:17], v[126:129], v[230:233], v[14:17]
	v_mfma_f32_16x16x32_bf16 v[10:13], v[130:133], v[226:229], v[10:13]
	v_mfma_f32_16x16x32_bf16 v[10:13], v[134:137], v[230:233], v[10:13]
	s_add_i32 s84, s84, 2
	s_add_u32 s56, s56, 0x100
	s_addc_u32 s57, s57, 0
	s_add_u32 s62, s62, 0x100
	s_addc_u32 s63, s63, 0
	v_mfma_f32_16x16x32_bf16 v[54:57], v[146:149], v[186:189], v[54:57]
	v_mfma_f32_16x16x32_bf16 v[54:57], v[150:153], v[194:197], v[54:57]
	v_mfma_f32_16x16x32_bf16 v[50:53], v[158:161], v[186:189], v[50:53]
	v_mfma_f32_16x16x32_bf16 v[50:53], v[182:185], v[194:197], v[50:53]
	v_mfma_f32_16x16x32_bf16 v[38:41], v[146:149], v[198:201], v[38:41]
	v_mfma_f32_16x16x32_bf16 v[38:41], v[150:153], v[214:217], v[38:41]
	v_mfma_f32_16x16x32_bf16 v[34:37], v[158:161], v[198:201], v[34:37]
	v_mfma_f32_16x16x32_bf16 v[34:37], v[182:185], v[214:217], v[34:37]
	v_mfma_f32_16x16x32_bf16 v[22:25], v[146:149], v[218:221], v[22:25]
	v_mfma_f32_16x16x32_bf16 v[22:25], v[150:153], v[222:225], v[22:25]
	v_mfma_f32_16x16x32_bf16 v[18:21], v[158:161], v[218:221], v[18:21]
	v_mfma_f32_16x16x32_bf16 v[18:21], v[182:185], v[222:225], v[18:21]
	v_mfma_f32_16x16x32_bf16 v[6:9], v[146:149], v[226:229], v[6:9]
	v_mfma_f32_16x16x32_bf16 v[6:9], v[150:153], v[230:233], v[6:9]
	v_mfma_f32_16x16x32_bf16 v[2:5], v[158:161], v[226:229], v[2:5]
	v_mfma_f32_16x16x32_bf16 v[2:5], v[182:185], v[230:233], v[2:5]
	s_barrier
	s_cmp_gt_u32 s84, 41
	s_cbranch_scc0 .LBB0_446
	s_setprio 0
	s_and_b64 vcc, exec, s[40:41]
	s_cbranch_vccz .LBB0_449
	s_barrier

.LBB0_487:
	s_ashr_i32 s57, s56, 31
	s_lshl_b64 s[20:21], s[56:57], 19
	s_add_u32 s60, s94, s20
	s_addc_u32 s61, s95, s21
	s_and_b64 s[20:21], s[54:55], exec
	s_cselect_b32 s57, s61, s69
	s_cselect_b32 s86, s60, s68
	s_ashr_i32 s51, s50, 31
	s_lshl_b64 s[20:21], s[50:51], 19
	s_add_u32 s62, s15, s20
	s_addc_u32 s63, s42, s21
	s_and_b64 s[20:21], s[54:55], exec
	s_cselect_b32 s51, s63, s77
	s_cselect_b32 s87, s62, s76
	s_add_u32 s68, s68, 0x40080
	s_addc_u32 s69, s69, 0
	s_add_u32 s91, s76, 0x100
	v_mov_b32_e32 v2, 0
	s_addc_u32 s96, s77, 0
	s_mov_b32 s97, -2
	v_add_u32_e32 v243, 0x10000, v139
	s_add_i32 s22, 0, 0x10000
	s_add_i32 s23, 0, 0x14000
	ds_read_b128 v[134:137], v243
	ds_read_b128 v[144:147], v243 offset:1024
	ds_read_b128 v[148:151], v243 offset:2048
	ds_read_b128 v[152:155], v243 offset:3072
	ds_read_b128 v[156:159], v243 offset:16384
	ds_read_b128 v[160:163], v243 offset:17408
	ds_read_b128 v[182:185], v243 offset:18432
	ds_read_b128 v[186:189], v243 offset:19456
	ds_read_b128 v[190:193], v142
	ds_read_b128 v[194:197], v142 offset:1024
	ds_read_b128 v[198:201], v142 offset:2048
	ds_read_b128 v[214:217], v142 offset:3072
	ds_read_b128 v[218:221], v142 offset:4096
	ds_read_b128 v[222:225], v142 offset:5120
	ds_read_b128 v[226:229], v142 offset:6144
	ds_read_b128 v[230:233], v142 offset:7168
	s_cmp_eq_u64 s[48:49], 0
	s_cbranch_scc0 .Lpr_488
	s_setprio 1

.Lmid1_488:
	s_add_i32 s22, 0, 0x10000
	s_add_i32 s23, 0, 0x14000
	s_add_u32 s20, s68, 0xfffc0080
	s_addc_u32 s21, s69, -1
	s_cmp_eq_u32 s97, 12
	s_cselect_b32 s77, s57, s21
	s_cselect_b32 s76, s86, s20
	s_cselect_b32 s21, s51, s96
	s_cselect_b32 s20, s87, s91
	s_add_i32 m0, s43, 0xc000
	v_lshl_add_u64 v[202:203], s[68:69], 0, v[132:133]
	global_load_lds_dwordx4 v[202:203], off
	v_lshl_add_u64 v[202:203], v[202:203], 0, s[72:73]
	s_add_i32 m0, s43, 0xe000
	s_nop 0
	global_load_lds_dwordx4 v[202:203], off
	s_waitcnt vmcnt(8) lgkmcnt(0)
	s_barrier
	v_mfma_f32_16x16x32_bf16 v[126:129], v[134:137], v[190:193], 0
	v_mfma_f32_16x16x32_bf16 v[126:129], v[144:147], v[194:197], v[126:129]
	v_mfma_f32_16x16x32_bf16 v[114:117], v[148:151], v[190:193], 0
	v_mfma_f32_16x16x32_bf16 v[114:117], v[152:155], v[194:197], v[114:117]
	v_mfma_f32_16x16x32_bf16 v[110:113], v[134:137], v[198:201], 0
	v_mfma_f32_16x16x32_bf16 v[110:113], v[144:147], v[214:217], v[110:113]
	v_mfma_f32_16x16x32_bf16 v[98:101], v[148:151], v[198:201], 0
	v_mfma_f32_16x16x32_bf16 v[98:101], v[152:155], v[214:217], v[98:101]
	v_mfma_f32_16x16x32_bf16 v[94:97], v[134:137], v[218:221], 0
	v_mfma_f32_16x16x32_bf16 v[94:97], v[144:147], v[222:225], v[94:97]
	v_mfma_f32_16x16x32_bf16 v[82:85], v[148:151], v[218:221], 0
	v_mfma_f32_16x16x32_bf16 v[82:85], v[152:155], v[222:225], v[82:85]
	v_mfma_f32_16x16x32_bf16 v[78:81], v[134:137], v[226:229], 0
	v_mfma_f32_16x16x32_bf16 v[78:81], v[144:147], v[230:233], v[78:81]
	v_mfma_f32_16x16x32_bf16 v[66:69], v[148:151], v[226:229], 0
	v_mfma_f32_16x16x32_bf16 v[66:69], v[152:155], v[230:233], v[66:69]
	v_mfma_f32_16x16x32_bf16 v[122:125], v[156:159], v[190:193], 0
	v_mfma_f32_16x16x32_bf16 v[122:125], v[160:163], v[194:197], v[122:125]
	v_mfma_f32_16x16x32_bf16 v[118:121], v[182:185], v[190:193], 0
	v_mfma_f32_16x16x32_bf16 v[118:121], v[186:189], v[194:197], v[118:121]
	v_mfma_f32_16x16x32_bf16 v[106:109], v[156:159], v[198:201], 0
	v_mfma_f32_16x16x32_bf16 v[106:109], v[160:163], v[214:217], v[106:109]
	v_mfma_f32_16x16x32_bf16 v[102:105], v[182:185], v[198:201], 0
	v_mfma_f32_16x16x32_bf16 v[102:105], v[186:189], v[214:217], v[102:105]
	v_mfma_f32_16x16x32_bf16 v[90:93], v[156:159], v[218:221], 0
	v_mfma_f32_16x16x32_bf16 v[90:93], v[160:163], v[222:225], v[90:93]
	v_mfma_f32_16x16x32_bf16 v[86:89], v[182:185], v[218:221], 0
	v_mfma_f32_16x16x32_bf16 v[86:89], v[186:189], v[222:225], v[86:89]
	v_mfma_f32_16x16x32_bf16 v[74:77], v[156:159], v[226:229], 0
	v_mfma_f32_16x16x32_bf16 v[74:77], v[160:163], v[230:233], v[74:77]
	v_mfma_f32_16x16x32_bf16 v[70:73], v[182:185], v[226:229], 0
	v_mfma_f32_16x16x32_bf16 v[70:73], v[186:189], v[230:233], v[70:73]
	s_barrier
	ds_read_b128 v[190:193], v142 offset:16384
	ds_read_b128 v[194:197], v142 offset:17408
	ds_read_b128 v[198:201], v142 offset:18432
	ds_read_b128 v[214:217], v142 offset:19456
	ds_read_b128 v[218:221], v142 offset:20480
	ds_read_b128 v[222:225], v142 offset:21504
	ds_read_b128 v[226:229], v142 offset:22528
	ds_read_b128 v[230:233], v142 offset:23552
	v_lshl_add_u64 v[202:203], s[20:21], 0, v[0:1]
	s_add_i32 s20, s22, s14
	s_mov_b32 m0, s20
	s_nop 0
	s_nop 0
	global_load_lds_dwordx4 v[202:203], off
	v_lshl_add_u64 v[234:235], v[202:203], 0, s[72:73]
	s_add_i32 m0, s20, 0x2000
	s_add_i32 s20, s23, s14
	global_load_lds_dwordx4 v[234:235], off
	v_lshl_add_u64 v[234:235], v[202:203], 0, s[28:29]
	s_mov_b32 m0, s20
	s_nop 0
	global_load_lds_dwordx4 v[234:235], off
	v_lshl_add_u64 v[234:235], v[202:203], 0, s[82:83]
	s_add_i32 m0, s20, 0x2000
	s_nop 0
	global_load_lds_dwordx4 v[234:235], off
	v_lshl_add_u64 v[234:235], s[76:77], 0, v[130:131]
	s_mov_b32 m0, s43
	v_lshl_add_u64 v[236:237], v[234:235], 0, s[72:73]
	global_load_lds_dwordx4 v[234:235], off
	s_mov_b32 m0, s46
	s_nop 0
	global_load_lds_dwordx4 v[236:237], off
	s_waitcnt vmcnt(8) lgkmcnt(0)
	s_barrier
	v_mfma_f32_16x16x32_bf16 v[62:65], v[134:137], v[190:193], 0
	v_mfma_f32_16x16x32_bf16 v[62:65], v[144:147], v[194:197], v[62:65]
	v_mfma_f32_16x16x32_bf16 v[50:53], v[148:151], v[190:193], 0
	v_mfma_f32_16x16x32_bf16 v[50:53], v[152:155], v[194:197], v[50:53]
	v_mfma_f32_16x16x32_bf16 v[46:49], v[134:137], v[198:201], 0
	v_mfma_f32_16x16x32_bf16 v[46:49], v[144:147], v[214:217], v[46:49]
	v_mfma_f32_16x16x32_bf16 v[34:37], v[148:151], v[198:201], 0
	v_mfma_f32_16x16x32_bf16 v[34:37], v[152:155], v[214:217], v[34:37]
	v_mfma_f32_16x16x32_bf16 v[30:33], v[134:137], v[218:221], 0
	v_mfma_f32_16x16x32_bf16 v[30:33], v[144:147], v[222:225], v[30:33]
	v_mfma_f32_16x16x32_bf16 v[18:21], v[148:151], v[218:221], 0
	v_mfma_f32_16x16x32_bf16 v[18:21], v[152:155], v[222:225], v[18:21]
	v_mfma_f32_16x16x32_bf16 v[14:17], v[134:137], v[226:229], 0
	v_mfma_f32_16x16x32_bf16 v[14:17], v[144:147], v[230:233], v[14:17]
	v_mfma_f32_16x16x32_bf16 v[6:9], v[148:151], v[226:229], 0
	v_mfma_f32_16x16x32_bf16 v[6:9], v[152:155], v[230:233], v[6:9]
	v_mfma_f32_16x16x32_bf16 v[58:61], v[156:159], v[190:193], 0
	v_mfma_f32_16x16x32_bf16 v[58:61], v[160:163], v[194:197], v[58:61]
	v_mfma_f32_16x16x32_bf16 v[54:57], v[182:185], v[190:193], 0
	v_mfma_f32_16x16x32_bf16 v[54:57], v[186:189], v[194:197], v[54:57]
	v_mfma_f32_16x16x32_bf16 v[42:45], v[156:159], v[198:201], 0
	v_mfma_f32_16x16x32_bf16 v[42:45], v[160:163], v[214:217], v[42:45]
	v_mfma_f32_16x16x32_bf16 v[38:41], v[182:185], v[198:201], 0
	v_mfma_f32_16x16x32_bf16 v[38:41], v[186:189], v[214:217], v[38:41]
	v_mfma_f32_16x16x32_bf16 v[26:29], v[156:159], v[218:221], 0
	v_mfma_f32_16x16x32_bf16 v[26:29], v[160:163], v[222:225], v[26:29]
	v_mfma_f32_16x16x32_bf16 v[22:25], v[182:185], v[218:221], 0
	v_mfma_f32_16x16x32_bf16 v[22:25], v[186:189], v[222:225], v[22:25]
	v_mfma_f32_16x16x32_bf16 v[10:13], v[156:159], v[226:229], 0
	v_mfma_f32_16x16x32_bf16 v[10:13], v[160:163], v[230:233], v[10:13]
	v_mfma_f32_16x16x32_bf16 v[2:5], v[182:185], v[226:229], 0
	v_mfma_f32_16x16x32_bf16 v[2:5], v[186:189], v[230:233], v[2:5]
	s_barrier
	s_add_i32 s20, 0, 0x18000
	s_add_i32 s21, 0, 0x1c000
	ds_read_b128 v[134:137], v243 offset:32768
	ds_read_b128 v[144:147], v243 offset:33792
	ds_read_b128 v[148:151], v243 offset:34816
	ds_read_b128 v[152:155], v243 offset:35840
	ds_read_b128 v[156:159], v243 offset:49152
	ds_read_b128 v[160:163], v243 offset:50176
	ds_read_b128 v[182:185], v243 offset:51200
	ds_read_b128 v[186:189], v243 offset:52224
	ds_read_b128 v[190:193], v142 offset:32768
	ds_read_b128 v[194:197], v142 offset:33792
	ds_read_b128 v[198:201], v142 offset:34816
	ds_read_b128 v[214:217], v142 offset:35840
	ds_read_b128 v[218:221], v142 offset:36864
	ds_read_b128 v[222:225], v142 offset:37888
	ds_read_b128 v[226:229], v142 offset:38912
	ds_read_b128 v[230:233], v142 offset:39936
	s_mov_b32 m0, s47
	v_lshl_add_u64 v[236:237], v[234:235], 0, s[28:29]
	global_load_lds_dwordx4 v[236:237], off
	v_lshl_add_u64 v[236:237], v[234:235], 0, s[82:83]
	s_mov_b32 m0, s78
	s_nop 0
	global_load_lds_dwordx4 v[236:237], off
	s_waitcnt vmcnt(8) lgkmcnt(0)
	s_barrier
	v_mfma_f32_16x16x32_bf16 v[126:129], v[134:137], v[190:193], v[126:129]
	v_mfma_f32_16x16x32_bf16 v[126:129], v[144:147], v[194:197], v[126:129]
	v_mfma_f32_16x16x32_bf16 v[114:117], v[148:151], v[190:193], v[114:117]
	v_mfma_f32_16x16x32_bf16 v[114:117], v[152:155], v[194:197], v[114:117]
	v_mfma_f32_16x16x32_bf16 v[110:113], v[134:137], v[198:201], v[110:113]
	v_mfma_f32_16x16x32_bf16 v[110:113], v[144:147], v[214:217], v[110:113]
	v_mfma_f32_16x16x32_bf16 v[98:101], v[148:151], v[198:201], v[98:101]
	v_mfma_f32_16x16x32_bf16 v[98:101], v[152:155], v[214:217], v[98:101]
	v_mfma_f32_16x16x32_bf16 v[94:97], v[134:137], v[218:221], v[94:97]
	v_mfma_f32_16x16x32_bf16 v[94:97], v[144:147], v[222:225], v[94:97]
	v_mfma_f32_16x16x32_bf16 v[82:85], v[148:151], v[218:221], v[82:85]
	v_mfma_f32_16x16x32_bf16 v[82:85], v[152:155], v[222:225], v[82:85]
	v_mfma_f32_16x16x32_bf16 v[78:81], v[134:137], v[226:229], v[78:81]
	v_mfma_f32_16x16x32_bf16 v[78:81], v[144:147], v[230:233], v[78:81]
	v_mfma_f32_16x16x32_bf16 v[66:69], v[148:151], v[226:229], v[66:69]
	v_mfma_f32_16x16x32_bf16 v[66:69], v[152:155], v[230:233], v[66:69]
	v_mfma_f32_16x16x32_bf16 v[122:125], v[156:159], v[190:193], v[122:125]
	v_mfma_f32_16x16x32_bf16 v[122:125], v[160:163], v[194:197], v[122:125]
	v_mfma_f32_16x16x32_bf16 v[118:121], v[182:185], v[190:193], v[118:121]
	v_mfma_f32_16x16x32_bf16 v[118:121], v[186:189], v[194:197], v[118:121]
	v_mfma_f32_16x16x32_bf16 v[106:109], v[156:159], v[198:201], v[106:109]
	v_mfma_f32_16x16x32_bf16 v[106:109], v[160:163], v[214:217], v[106:109]
	v_mfma_f32_16x16x32_bf16 v[102:105], v[182:185], v[198:201], v[102:105]
	v_mfma_f32_16x16x32_bf16 v[102:105], v[186:189], v[214:217], v[102:105]
	v_mfma_f32_16x16x32_bf16 v[90:93], v[156:159], v[218:221], v[90:93]
	v_mfma_f32_16x16x32_bf16 v[90:93], v[160:163], v[222:225], v[90:93]
	v_mfma_f32_16x16x32_bf16 v[86:89], v[182:185], v[218:221], v[86:89]
	v_mfma_f32_16x16x32_bf16 v[86:89], v[186:189], v[222:225], v[86:89]
	v_mfma_f32_16x16x32_bf16 v[74:77], v[156:159], v[226:229], v[74:77]
	v_mfma_f32_16x16x32_bf16 v[74:77], v[160:163], v[230:233], v[74:77]
	v_mfma_f32_16x16x32_bf16 v[70:73], v[182:185], v[226:229], v[70:73]
	v_mfma_f32_16x16x32_bf16 v[70:73], v[186:189], v[230:233], v[70:73]
	s_barrier
	ds_read_b128 v[190:193], v142 offset:49152
	ds_read_b128 v[194:197], v142 offset:50176
	ds_read_b128 v[198:201], v142 offset:51200
	ds_read_b128 v[214:217], v142 offset:52224
	ds_read_b128 v[218:221], v142 offset:53248
	ds_read_b128 v[222:225], v142 offset:54272
	ds_read_b128 v[226:229], v142 offset:55296
	ds_read_b128 v[230:233], v142 offset:56320
	s_add_i32 s20, s20, s14
	s_mov_b32 m0, s20
	v_lshl_add_u64 v[236:237], v[202:203], 0, s[34:35]
	global_load_lds_dwordx4 v[236:237], off
	v_lshl_add_u64 v[236:237], v[202:203], 0, s[38:39]
	s_add_i32 m0, s20, 0x2000
	s_add_i32 s20, s21, s14
	global_load_lds_dwordx4 v[236:237], off
	v_lshl_add_u64 v[236:237], v[202:203], 0, s[44:45]
	s_mov_b32 m0, s20
	v_lshl_add_u64 v[202:203], v[202:203], 0, s[10:11]
	global_load_lds_dwordx4 v[236:237], off
	s_add_i32 m0, s20, 0x2000
	s_nop 0
	global_load_lds_dwordx4 v[202:203], off
	v_lshl_add_u64 v[202:203], v[234:235], 0, s[34:35]
	s_mov_b32 m0, s79
	s_nop 0
	global_load_lds_dwordx4 v[202:203], off
	v_lshl_add_u64 v[202:203], v[234:235], 0, s[38:39]
	s_mov_b32 m0, s88
	s_nop 0
	global_load_lds_dwordx4 v[202:203], off
	s_waitcnt vmcnt(8) lgkmcnt(0)
	s_barrier
	v_mfma_f32_16x16x32_bf16 v[62:65], v[134:137], v[190:193], v[62:65]
	v_mfma_f32_16x16x32_bf16 v[62:65], v[144:147], v[194:197], v[62:65]
	v_mfma_f32_16x16x32_bf16 v[50:53], v[148:151], v[190:193], v[50:53]
	v_mfma_f32_16x16x32_bf16 v[50:53], v[152:155], v[194:197], v[50:53]
	v_mfma_f32_16x16x32_bf16 v[46:49], v[134:137], v[198:201], v[46:49]
	v_mfma_f32_16x16x32_bf16 v[46:49], v[144:147], v[214:217], v[46:49]
	v_mfma_f32_16x16x32_bf16 v[34:37], v[148:151], v[198:201], v[34:37]
	v_mfma_f32_16x16x32_bf16 v[34:37], v[152:155], v[214:217], v[34:37]
	v_mfma_f32_16x16x32_bf16 v[30:33], v[134:137], v[218:221], v[30:33]
	v_mfma_f32_16x16x32_bf16 v[30:33], v[144:147], v[222:225], v[30:33]
	v_mfma_f32_16x16x32_bf16 v[18:21], v[148:151], v[218:221], v[18:21]
	v_mfma_f32_16x16x32_bf16 v[18:21], v[152:155], v[222:225], v[18:21]
	v_mfma_f32_16x16x32_bf16 v[14:17], v[134:137], v[226:229], v[14:17]
	v_mfma_f32_16x16x32_bf16 v[14:17], v[144:147], v[230:233], v[14:17]
	v_mfma_f32_16x16x32_bf16 v[6:9], v[148:151], v[226:229], v[6:9]
	v_mfma_f32_16x16x32_bf16 v[6:9], v[152:155], v[230:233], v[6:9]
	s_add_i32 s97, s97, 2
	s_add_u32 s68, s68, 0x100
	s_addc_u32 s69, s69, 0
	s_add_u32 s91, s91, 0x100
	s_addc_u32 s96, s96, 0
	v_mfma_f32_16x16x32_bf16 v[58:61], v[156:159], v[190:193], v[58:61]
	v_mfma_f32_16x16x32_bf16 v[58:61], v[160:163], v[194:197], v[58:61]
	v_mfma_f32_16x16x32_bf16 v[54:57], v[182:185], v[190:193], v[54:57]
	v_mfma_f32_16x16x32_bf16 v[54:57], v[186:189], v[194:197], v[54:57]
	v_mfma_f32_16x16x32_bf16 v[42:45], v[156:159], v[198:201], v[42:45]
	v_mfma_f32_16x16x32_bf16 v[42:45], v[160:163], v[214:217], v[42:45]
	v_mfma_f32_16x16x32_bf16 v[38:41], v[182:185], v[198:201], v[38:41]
	v_mfma_f32_16x16x32_bf16 v[38:41], v[186:189], v[214:217], v[38:41]
	v_mfma_f32_16x16x32_bf16 v[26:29], v[156:159], v[218:221], v[26:29]
	v_mfma_f32_16x16x32_bf16 v[26:29], v[160:163], v[222:225], v[26:29]
	v_mfma_f32_16x16x32_bf16 v[22:25], v[182:185], v[218:221], v[22:25]
	v_mfma_f32_16x16x32_bf16 v[22:25], v[186:189], v[222:225], v[22:25]
	v_mfma_f32_16x16x32_bf16 v[10:13], v[156:159], v[226:229], v[10:13]
	v_mfma_f32_16x16x32_bf16 v[10:13], v[160:163], v[230:233], v[10:13]
	v_mfma_f32_16x16x32_bf16 v[2:5], v[182:185], v[226:229], v[2:5]
	v_mfma_f32_16x16x32_bf16 v[2:5], v[186:189], v[230:233], v[2:5]
	s_barrier
	s_branch .LBB0_488
	.p2alignl 6, 3212836864
.LBB0_488:
	s_add_i32 s22, 0, 0x10000
	s_add_i32 s23, 0, 0x14000
	ds_read_b128 v[134:137], v243
	ds_read_b128 v[144:147], v243 offset:1024
	ds_read_b128 v[148:151], v243 offset:2048
	ds_read_b128 v[152:155], v243 offset:3072
	ds_read_b128 v[156:159], v243 offset:16384
	ds_read_b128 v[160:163], v243 offset:17408
	ds_read_b128 v[182:185], v243 offset:18432
	ds_read_b128 v[186:189], v243 offset:19456
	ds_read_b128 v[190:193], v142
	ds_read_b128 v[194:197], v142 offset:1024
	ds_read_b128 v[198:201], v142 offset:2048
	ds_read_b128 v[214:217], v142 offset:3072
	ds_read_b128 v[218:221], v142 offset:4096
	ds_read_b128 v[222:225], v142 offset:5120
	ds_read_b128 v[226:229], v142 offset:6144
	ds_read_b128 v[230:233], v142 offset:7168
	s_add_u32 s20, s68, 0xfffc0080
	s_addc_u32 s21, s69, -1
	s_cmp_eq_u32 s97, 12
	s_cselect_b32 s77, s57, s21
	s_cselect_b32 s76, s86, s20
	s_cselect_b32 s21, s51, s96
	s_cselect_b32 s20, s87, s91
	s_add_i32 m0, s43, 0xc000
	v_lshl_add_u64 v[202:203], s[68:69], 0, v[132:133]
	global_load_lds_dwordx4 v[202:203], off
	v_lshl_add_u64 v[202:203], v[202:203], 0, s[72:73]
	s_add_i32 m0, s43, 0xe000
	s_nop 0
	global_load_lds_dwordx4 v[202:203], off
	s_waitcnt vmcnt(8) lgkmcnt(0)
	s_barrier
	v_mfma_f32_16x16x32_bf16 v[126:129], v[134:137], v[190:193], v[126:129]
	v_mfma_f32_16x16x32_bf16 v[126:129], v[144:147], v[194:197], v[126:129]
	v_mfma_f32_16x16x32_bf16 v[114:117], v[148:151], v[190:193], v[114:117]
	v_mfma_f32_16x16x32_bf16 v[114:117], v[152:155], v[194:197], v[114:117]
	v_mfma_f32_16x16x32_bf16 v[110:113], v[134:137], v[198:201], v[110:113]
	v_mfma_f32_16x16x32_bf16 v[110:113], v[144:147], v[214:217], v[110:113]
	v_mfma_f32_16x16x32_bf16 v[98:101], v[148:151], v[198:201], v[98:101]
	v_mfma_f32_16x16x32_bf16 v[98:101], v[152:155], v[214:217], v[98:101]
	v_mfma_f32_16x16x32_bf16 v[94:97], v[134:137], v[218:221], v[94:97]
	v_mfma_f32_16x16x32_bf16 v[94:97], v[144:147], v[222:225], v[94:97]
	v_mfma_f32_16x16x32_bf16 v[82:85], v[148:151], v[218:221], v[82:85]
	v_mfma_f32_16x16x32_bf16 v[82:85], v[152:155], v[222:225], v[82:85]
	v_mfma_f32_16x16x32_bf16 v[78:81], v[134:137], v[226:229], v[78:81]
	v_mfma_f32_16x16x32_bf16 v[78:81], v[144:147], v[230:233], v[78:81]
	v_mfma_f32_16x16x32_bf16 v[66:69], v[148:151], v[226:229], v[66:69]
	v_mfma_f32_16x16x32_bf16 v[66:69], v[152:155], v[230:233], v[66:69]
	v_mfma_f32_16x16x32_bf16 v[122:125], v[156:159], v[190:193], v[122:125]
	v_mfma_f32_16x16x32_bf16 v[122:125], v[160:163], v[194:197], v[122:125]
	v_mfma_f32_16x16x32_bf16 v[118:121], v[182:185], v[190:193], v[118:121]
	v_mfma_f32_16x16x32_bf16 v[118:121], v[186:189], v[194:197], v[118:121]
	v_mfma_f32_16x16x32_bf16 v[106:109], v[156:159], v[198:201], v[106:109]
	v_mfma_f32_16x16x32_bf16 v[106:109], v[160:163], v[214:217], v[106:109]
	v_mfma_f32_16x16x32_bf16 v[102:105], v[182:185], v[198:201], v[102:105]
	v_mfma_f32_16x16x32_bf16 v[102:105], v[186:189], v[214:217], v[102:105]
	v_mfma_f32_16x16x32_bf16 v[90:93], v[156:159], v[218:221], v[90:93]
	v_mfma_f32_16x16x32_bf16 v[90:93], v[160:163], v[222:225], v[90:93]
	v_mfma_f32_16x16x32_bf16 v[86:89], v[182:185], v[218:221], v[86:89]
	v_mfma_f32_16x16x32_bf16 v[86:89], v[186:189], v[222:225], v[86:89]
	v_mfma_f32_16x16x32_bf16 v[74:77], v[156:159], v[226:229], v[74:77]
	v_mfma_f32_16x16x32_bf16 v[74:77], v[160:163], v[230:233], v[74:77]
	v_mfma_f32_16x16x32_bf16 v[70:73], v[182:185], v[226:229], v[70:73]
	v_mfma_f32_16x16x32_bf16 v[70:73], v[186:189], v[230:233], v[70:73]
	s_barrier
	ds_read_b128 v[190:193], v142 offset:16384
	ds_read_b128 v[194:197], v142 offset:17408
	ds_read_b128 v[198:201], v142 offset:18432
	ds_read_b128 v[214:217], v142 offset:19456
	ds_read_b128 v[218:221], v142 offset:20480
	ds_read_b128 v[222:225], v142 offset:21504
	ds_read_b128 v[226:229], v142 offset:22528
	ds_read_b128 v[230:233], v142 offset:23552
	v_lshl_add_u64 v[202:203], s[20:21], 0, v[0:1]
	s_add_i32 s20, s22, s14
	s_mov_b32 m0, s20
	s_nop 0
	s_nop 0
	global_load_lds_dwordx4 v[202:203], off
	v_lshl_add_u64 v[234:235], v[202:203], 0, s[72:73]
	s_add_i32 m0, s20, 0x2000
	s_add_i32 s20, s23, s14
	global_load_lds_dwordx4 v[234:235], off
	v_lshl_add_u64 v[234:235], v[202:203], 0, s[28:29]
	s_mov_b32 m0, s20
	s_nop 0
	global_load_lds_dwordx4 v[234:235], off
	v_lshl_add_u64 v[234:235], v[202:203], 0, s[82:83]
	s_add_i32 m0, s20, 0x2000
	s_nop 0
	global_load_lds_dwordx4 v[234:235], off
	v_lshl_add_u64 v[234:235], s[76:77], 0, v[130:131]
	s_mov_b32 m0, s43
	v_lshl_add_u64 v[236:237], v[234:235], 0, s[72:73]
	global_load_lds_dwordx4 v[234:235], off
	s_mov_b32 m0, s46
	s_nop 0
	global_load_lds_dwordx4 v[236:237], off
	s_waitcnt vmcnt(8) lgkmcnt(0)
	s_barrier
	v_mfma_f32_16x16x32_bf16 v[62:65], v[134:137], v[190:193], v[62:65]
	v_mfma_f32_16x16x32_bf16 v[62:65], v[144:147], v[194:197], v[62:65]
	v_mfma_f32_16x16x32_bf16 v[50:53], v[148:151], v[190:193], v[50:53]
	v_mfma_f32_16x16x32_bf16 v[50:53], v[152:155], v[194:197], v[50:53]
	v_mfma_f32_16x16x32_bf16 v[46:49], v[134:137], v[198:201], v[46:49]
	v_mfma_f32_16x16x32_bf16 v[46:49], v[144:147], v[214:217], v[46:49]
	v_mfma_f32_16x16x32_bf16 v[34:37], v[148:151], v[198:201], v[34:37]
	v_mfma_f32_16x16x32_bf16 v[34:37], v[152:155], v[214:217], v[34:37]
	v_mfma_f32_16x16x32_bf16 v[30:33], v[134:137], v[218:221], v[30:33]
	v_mfma_f32_16x16x32_bf16 v[30:33], v[144:147], v[222:225], v[30:33]
	v_mfma_f32_16x16x32_bf16 v[18:21], v[148:151], v[218:221], v[18:21]
	v_mfma_f32_16x16x32_bf16 v[18:21], v[152:155], v[222:225], v[18:21]
	v_mfma_f32_16x16x32_bf16 v[14:17], v[134:137], v[226:229], v[14:17]
	v_mfma_f32_16x16x32_bf16 v[14:17], v[144:147], v[230:233], v[14:17]
	v_mfma_f32_16x16x32_bf16 v[6:9], v[148:151], v[226:229], v[6:9]
	v_mfma_f32_16x16x32_bf16 v[6:9], v[152:155], v[230:233], v[6:9]
	v_mfma_f32_16x16x32_bf16 v[58:61], v[156:159], v[190:193], v[58:61]
	v_mfma_f32_16x16x32_bf16 v[58:61], v[160:163], v[194:197], v[58:61]
	v_mfma_f32_16x16x32_bf16 v[54:57], v[182:185], v[190:193], v[54:57]
	v_mfma_f32_16x16x32_bf16 v[54:57], v[186:189], v[194:197], v[54:57]
	v_mfma_f32_16x16x32_bf16 v[42:45], v[156:159], v[198:201], v[42:45]
	v_mfma_f32_16x16x32_bf16 v[42:45], v[160:163], v[214:217], v[42:45]
	v_mfma_f32_16x16x32_bf16 v[38:41], v[182:185], v[198:201], v[38:41]
	v_mfma_f32_16x16x32_bf16 v[38:41], v[186:189], v[214:217], v[38:41]
	v_mfma_f32_16x16x32_bf16 v[26:29], v[156:159], v[218:221], v[26:29]
	v_mfma_f32_16x16x32_bf16 v[26:29], v[160:163], v[222:225], v[26:29]
	v_mfma_f32_16x16x32_bf16 v[22:25], v[182:185], v[218:221], v[22:25]
	v_mfma_f32_16x16x32_bf16 v[22:25], v[186:189], v[222:225], v[22:25]
	v_mfma_f32_16x16x32_bf16 v[10:13], v[156:159], v[226:229], v[10:13]
	v_mfma_f32_16x16x32_bf16 v[10:13], v[160:163], v[230:233], v[10:13]
	v_mfma_f32_16x16x32_bf16 v[2:5], v[182:185], v[226:229], v[2:5]
	v_mfma_f32_16x16x32_bf16 v[2:5], v[186:189], v[230:233], v[2:5]
	s_barrier
	s_add_i32 s20, 0, 0x18000
	s_add_i32 s21, 0, 0x1c000
	ds_read_b128 v[134:137], v243 offset:32768
	ds_read_b128 v[144:147], v243 offset:33792
	ds_read_b128 v[148:151], v243 offset:34816
	ds_read_b128 v[152:155], v243 offset:35840
	ds_read_b128 v[156:159], v243 offset:49152
	ds_read_b128 v[160:163], v243 offset:50176
	ds_read_b128 v[182:185], v243 offset:51200
	ds_read_b128 v[186:189], v243 offset:52224
	ds_read_b128 v[190:193], v142 offset:32768
	ds_read_b128 v[194:197], v142 offset:33792
	ds_read_b128 v[198:201], v142 offset:34816
	ds_read_b128 v[214:217], v142 offset:35840
	ds_read_b128 v[218:221], v142 offset:36864
	ds_read_b128 v[222:225], v142 offset:37888
	ds_read_b128 v[226:229], v142 offset:38912
	ds_read_b128 v[230:233], v142 offset:39936
	s_mov_b32 m0, s47
	v_lshl_add_u64 v[236:237], v[234:235], 0, s[28:29]
	global_load_lds_dwordx4 v[236:237], off
	v_lshl_add_u64 v[236:237], v[234:235], 0, s[82:83]
	s_mov_b32 m0, s78
	s_nop 0
	global_load_lds_dwordx4 v[236:237], off
	s_waitcnt vmcnt(8) lgkmcnt(0)
	s_barrier
	v_mfma_f32_16x16x32_bf16 v[126:129], v[134:137], v[190:193], v[126:129]
	v_mfma_f32_16x16x32_bf16 v[126:129], v[144:147], v[194:197], v[126:129]
	v_mfma_f32_16x16x32_bf16 v[114:117], v[148:151], v[190:193], v[114:117]
	v_mfma_f32_16x16x32_bf16 v[114:117], v[152:155], v[194:197], v[114:117]
	v_mfma_f32_16x16x32_bf16 v[110:113], v[134:137], v[198:201], v[110:113]
	v_mfma_f32_16x16x32_bf16 v[110:113], v[144:147], v[214:217], v[110:113]
	v_mfma_f32_16x16x32_bf16 v[98:101], v[148:151], v[198:201], v[98:101]
	v_mfma_f32_16x16x32_bf16 v[98:101], v[152:155], v[214:217], v[98:101]
	v_mfma_f32_16x16x32_bf16 v[94:97], v[134:137], v[218:221], v[94:97]
	v_mfma_f32_16x16x32_bf16 v[94:97], v[144:147], v[222:225], v[94:97]
	v_mfma_f32_16x16x32_bf16 v[82:85], v[148:151], v[218:221], v[82:85]
	v_mfma_f32_16x16x32_bf16 v[82:85], v[152:155], v[222:225], v[82:85]
	v_mfma_f32_16x16x32_bf16 v[78:81], v[134:137], v[226:229], v[78:81]
	v_mfma_f32_16x16x32_bf16 v[78:81], v[144:147], v[230:233], v[78:81]
	v_mfma_f32_16x16x32_bf16 v[66:69], v[148:151], v[226:229], v[66:69]
	v_mfma_f32_16x16x32_bf16 v[66:69], v[152:155], v[230:233], v[66:69]
	v_mfma_f32_16x16x32_bf16 v[122:125], v[156:159], v[190:193], v[122:125]
	v_mfma_f32_16x16x32_bf16 v[122:125], v[160:163], v[194:197], v[122:125]
	v_mfma_f32_16x16x32_bf16 v[118:121], v[182:185], v[190:193], v[118:121]
	v_mfma_f32_16x16x32_bf16 v[118:121], v[186:189], v[194:197], v[118:121]
	v_mfma_f32_16x16x32_bf16 v[106:109], v[156:159], v[198:201], v[106:109]
	v_mfma_f32_16x16x32_bf16 v[106:109], v[160:163], v[214:217], v[106:109]
	v_mfma_f32_16x16x32_bf16 v[102:105], v[182:185], v[198:201], v[102:105]
	v_mfma_f32_16x16x32_bf16 v[102:105], v[186:189], v[214:217], v[102:105]
	v_mfma_f32_16x16x32_bf16 v[90:93], v[156:159], v[218:221], v[90:93]
	v_mfma_f32_16x16x32_bf16 v[90:93], v[160:163], v[222:225], v[90:93]
	v_mfma_f32_16x16x32_bf16 v[86:89], v[182:185], v[218:221], v[86:89]
	v_mfma_f32_16x16x32_bf16 v[86:89], v[186:189], v[222:225], v[86:89]
	v_mfma_f32_16x16x32_bf16 v[74:77], v[156:159], v[226:229], v[74:77]
	v_mfma_f32_16x16x32_bf16 v[74:77], v[160:163], v[230:233], v[74:77]
	v_mfma_f32_16x16x32_bf16 v[70:73], v[182:185], v[226:229], v[70:73]
	v_mfma_f32_16x16x32_bf16 v[70:73], v[186:189], v[230:233], v[70:73]
	s_barrier
	ds_read_b128 v[190:193], v142 offset:49152
	ds_read_b128 v[194:197], v142 offset:50176
	ds_read_b128 v[198:201], v142 offset:51200
	ds_read_b128 v[214:217], v142 offset:52224
	ds_read_b128 v[218:221], v142 offset:53248
	ds_read_b128 v[222:225], v142 offset:54272
	ds_read_b128 v[226:229], v142 offset:55296
	ds_read_b128 v[230:233], v142 offset:56320
	s_add_i32 s20, s20, s14
	s_mov_b32 m0, s20
	v_lshl_add_u64 v[236:237], v[202:203], 0, s[34:35]
	global_load_lds_dwordx4 v[236:237], off
	v_lshl_add_u64 v[236:237], v[202:203], 0, s[38:39]
	s_add_i32 m0, s20, 0x2000
	s_add_i32 s20, s21, s14
	global_load_lds_dwordx4 v[236:237], off
	v_lshl_add_u64 v[236:237], v[202:203], 0, s[44:45]
	s_mov_b32 m0, s20
	v_lshl_add_u64 v[202:203], v[202:203], 0, s[10:11]
	global_load_lds_dwordx4 v[236:237], off
	s_add_i32 m0, s20, 0x2000
	s_nop 0
	global_load_lds_dwordx4 v[202:203], off
	v_lshl_add_u64 v[202:203], v[234:235], 0, s[34:35]
	s_mov_b32 m0, s79
	s_nop 0
	global_load_lds_dwordx4 v[202:203], off
	v_lshl_add_u64 v[202:203], v[234:235], 0, s[38:39]
	s_mov_b32 m0, s88
	s_nop 0
	global_load_lds_dwordx4 v[202:203], off
	s_waitcnt vmcnt(8) lgkmcnt(0)
	s_barrier
	v_mfma_f32_16x16x32_bf16 v[62:65], v[134:137], v[190:193], v[62:65]
	v_mfma_f32_16x16x32_bf16 v[62:65], v[144:147], v[194:197], v[62:65]
	v_mfma_f32_16x16x32_bf16 v[50:53], v[148:151], v[190:193], v[50:53]
	v_mfma_f32_16x16x32_bf16 v[50:53], v[152:155], v[194:197], v[50:53]
	v_mfma_f32_16x16x32_bf16 v[46:49], v[134:137], v[198:201], v[46:49]
	v_mfma_f32_16x16x32_bf16 v[46:49], v[144:147], v[214:217], v[46:49]
	v_mfma_f32_16x16x32_bf16 v[34:37], v[148:151], v[198:201], v[34:37]
	v_mfma_f32_16x16x32_bf16 v[34:37], v[152:155], v[214:217], v[34:37]
	v_mfma_f32_16x16x32_bf16 v[30:33], v[134:137], v[218:221], v[30:33]
	v_mfma_f32_16x16x32_bf16 v[30:33], v[144:147], v[222:225], v[30:33]
	v_mfma_f32_16x16x32_bf16 v[18:21], v[148:151], v[218:221], v[18:21]
	v_mfma_f32_16x16x32_bf16 v[18:21], v[152:155], v[222:225], v[18:21]
	v_mfma_f32_16x16x32_bf16 v[14:17], v[134:137], v[226:229], v[14:17]
	v_mfma_f32_16x16x32_bf16 v[14:17], v[144:147], v[230:233], v[14:17]
	v_mfma_f32_16x16x32_bf16 v[6:9], v[148:151], v[226:229], v[6:9]
	v_mfma_f32_16x16x32_bf16 v[6:9], v[152:155], v[230:233], v[6:9]
	s_add_i32 s97, s97, 2
	s_add_u32 s68, s68, 0x100
	s_addc_u32 s69, s69, 0
	s_add_u32 s91, s91, 0x100
	s_addc_u32 s96, s96, 0
	v_mfma_f32_16x16x32_bf16 v[58:61], v[156:159], v[190:193], v[58:61]
	v_mfma_f32_16x16x32_bf16 v[58:61], v[160:163], v[194:197], v[58:61]
	v_mfma_f32_16x16x32_bf16 v[54:57], v[182:185], v[190:193], v[54:57]
	v_mfma_f32_16x16x32_bf16 v[54:57], v[186:189], v[194:197], v[54:57]
	v_mfma_f32_16x16x32_bf16 v[42:45], v[156:159], v[198:201], v[42:45]
	v_mfma_f32_16x16x32_bf16 v[42:45], v[160:163], v[214:217], v[42:45]
	v_mfma_f32_16x16x32_bf16 v[38:41], v[182:185], v[198:201], v[38:41]
	v_mfma_f32_16x16x32_bf16 v[38:41], v[186:189], v[214:217], v[38:41]
	v_mfma_f32_16x16x32_bf16 v[26:29], v[156:159], v[218:221], v[26:29]
	v_mfma_f32_16x16x32_bf16 v[26:29], v[160:163], v[222:225], v[26:29]
	v_mfma_f32_16x16x32_bf16 v[22:25], v[182:185], v[218:221], v[22:25]
	v_mfma_f32_16x16x32_bf16 v[22:25], v[186:189], v[222:225], v[22:25]
	v_mfma_f32_16x16x32_bf16 v[10:13], v[156:159], v[226:229], v[10:13]
	v_mfma_f32_16x16x32_bf16 v[10:13], v[160:163], v[230:233], v[10:13]
	v_mfma_f32_16x16x32_bf16 v[2:5], v[182:185], v[226:229], v[2:5]
	v_mfma_f32_16x16x32_bf16 v[2:5], v[186:189], v[230:233], v[2:5]
	s_barrier
	s_cmp_gt_u32 s97, 13
	s_cbranch_scc0 .LBB0_488
	s_setprio 0
	s_and_b64 vcc, exec, s[48:49]
	s_cbranch_vccz .LBB0_491
	s_barrier

.LBB0_603:
	s_ashr_i32 s51, s50, 31
	s_lshl_b64 s[20:21], s[50:51], 18
	s_add_u32 s78, s0, s20
	s_addc_u32 s79, s1, s21
	s_and_b64 s[20:21], s[56:57], exec
	s_cselect_b32 s42, s79, s7
	s_cselect_b32 s43, s78, s6
	s_ashr_i32 s49, s48, 31
	s_lshl_b64 s[20:21], s[48:49], 18
	s_add_u32 s40, s76, s20
	s_addc_u32 s41, s77, s21
	s_and_b64 s[20:21], s[56:57], exec
	s_cselect_b32 s46, s41, s69
	s_cselect_b32 s47, s40, s68
	s_add_u32 s6, s6, 0x20080
	s_addc_u32 s7, s7, 0
	s_add_u32 s49, s68, 0x100
	v_mov_b32_e32 v2, 0
	s_addc_u32 s51, s69, 0
	s_mov_b32 s84, -2
	s_waitcnt lgkmcnt(0)
	v_add_u32_e32 v243, 0x10000, v139
	s_add_i32 s22, 0, 0x10000
	s_add_i32 s23, 0, 0x14000
	ds_read_b128 v[134:137], v243
	ds_read_b128 v[142:145], v243 offset:1024
	ds_read_b128 v[146:149], v243 offset:2048
	ds_read_b128 v[150:153], v243 offset:3072
	ds_read_b128 v[154:157], v243 offset:16384
	ds_read_b128 v[158:161], v243 offset:17408
	ds_read_b128 v[182:185], v243 offset:18432
	ds_read_b128 v[186:189], v243 offset:19456
	ds_read_b128 v[190:193], v141
	ds_read_b128 v[194:197], v141 offset:1024
	ds_read_b128 v[198:201], v141 offset:2048
	ds_read_b128 v[214:217], v141 offset:3072
	ds_read_b128 v[218:221], v141 offset:4096
	ds_read_b128 v[222:225], v141 offset:5120
	ds_read_b128 v[226:229], v141 offset:6144
	ds_read_b128 v[230:233], v141 offset:7168
	s_cmp_eq_u64 s[52:53], 0
	s_cbranch_scc0 .Lpr_604
	s_setprio 1

.Lmid1_604:
	s_add_i32 s22, 0, 0x10000
	s_add_i32 s23, 0, 0x14000
	s_add_u32 s20, s6, 0xfffe0080
	s_addc_u32 s21, s7, -1
	s_cmp_eq_u32 s84, 4
	s_cselect_b32 s69, s42, s21
	s_cselect_b32 s68, s43, s20
	s_cselect_b32 s21, s46, s51
	s_cselect_b32 s20, s47, s49
	s_add_i32 m0, s89, 0xc000
	v_lshl_add_u64 v[162:163], s[6:7], 0, v[132:133]
	global_load_lds_dwordx4 v[162:163], off
	v_lshl_add_u64 v[162:163], v[162:163], 0, s[64:65]
	s_add_i32 m0, s89, 0xe000
	s_nop 0
	global_load_lds_dwordx4 v[162:163], off
	s_waitcnt vmcnt(8) lgkmcnt(0)
	s_barrier
	v_mfma_f32_16x16x32_bf16 v[126:129], v[134:137], v[190:193], 0
	v_mfma_f32_16x16x32_bf16 v[126:129], v[142:145], v[194:197], v[126:129]
	v_mfma_f32_16x16x32_bf16 v[122:125], v[146:149], v[190:193], 0
	v_mfma_f32_16x16x32_bf16 v[122:125], v[150:153], v[194:197], v[122:125]
	v_mfma_f32_16x16x32_bf16 v[110:113], v[134:137], v[198:201], 0
	v_mfma_f32_16x16x32_bf16 v[110:113], v[142:145], v[214:217], v[110:113]
	v_mfma_f32_16x16x32_bf16 v[106:109], v[146:149], v[198:201], 0
	v_mfma_f32_16x16x32_bf16 v[106:109], v[150:153], v[214:217], v[106:109]
	v_mfma_f32_16x16x32_bf16 v[94:97], v[134:137], v[218:221], 0
	v_mfma_f32_16x16x32_bf16 v[94:97], v[142:145], v[222:225], v[94:97]
	v_mfma_f32_16x16x32_bf16 v[90:93], v[146:149], v[218:221], 0
	v_mfma_f32_16x16x32_bf16 v[90:93], v[150:153], v[222:225], v[90:93]
	v_mfma_f32_16x16x32_bf16 v[78:81], v[134:137], v[226:229], 0
	v_mfma_f32_16x16x32_bf16 v[78:81], v[142:145], v[230:233], v[78:81]
	v_mfma_f32_16x16x32_bf16 v[74:77], v[146:149], v[226:229], 0
	v_mfma_f32_16x16x32_bf16 v[74:77], v[150:153], v[230:233], v[74:77]
	v_mfma_f32_16x16x32_bf16 v[118:121], v[154:157], v[190:193], 0
	v_mfma_f32_16x16x32_bf16 v[118:121], v[158:161], v[194:197], v[118:121]
	v_mfma_f32_16x16x32_bf16 v[114:117], v[182:185], v[190:193], 0
	v_mfma_f32_16x16x32_bf16 v[114:117], v[186:189], v[194:197], v[114:117]
	v_mfma_f32_16x16x32_bf16 v[102:105], v[154:157], v[198:201], 0
	v_mfma_f32_16x16x32_bf16 v[102:105], v[158:161], v[214:217], v[102:105]
	v_mfma_f32_16x16x32_bf16 v[98:101], v[182:185], v[198:201], 0
	v_mfma_f32_16x16x32_bf16 v[98:101], v[186:189], v[214:217], v[98:101]
	v_mfma_f32_16x16x32_bf16 v[86:89], v[154:157], v[218:221], 0
	v_mfma_f32_16x16x32_bf16 v[86:89], v[158:161], v[222:225], v[86:89]
	v_mfma_f32_16x16x32_bf16 v[82:85], v[182:185], v[218:221], 0
	v_mfma_f32_16x16x32_bf16 v[82:85], v[186:189], v[222:225], v[82:85]
	v_mfma_f32_16x16x32_bf16 v[70:73], v[154:157], v[226:229], 0
	v_mfma_f32_16x16x32_bf16 v[70:73], v[158:161], v[230:233], v[70:73]
	v_mfma_f32_16x16x32_bf16 v[66:69], v[182:185], v[226:229], 0
	v_mfma_f32_16x16x32_bf16 v[66:69], v[186:189], v[230:233], v[66:69]
	s_barrier
	ds_read_b128 v[190:193], v141 offset:16384
	ds_read_b128 v[194:197], v141 offset:17408
	ds_read_b128 v[198:201], v141 offset:18432
	ds_read_b128 v[214:217], v141 offset:19456
	ds_read_b128 v[218:221], v141 offset:20480
	ds_read_b128 v[222:225], v141 offset:21504
	ds_read_b128 v[226:229], v141 offset:22528
	ds_read_b128 v[230:233], v141 offset:23552
	v_lshl_add_u64 v[162:163], s[20:21], 0, v[0:1]
	s_add_i32 s20, s22, s88
	s_mov_b32 m0, s20
	s_nop 0
	s_nop 0
	global_load_lds_dwordx4 v[162:163], off
	v_lshl_add_u64 v[202:203], v[162:163], 0, s[64:65]
	s_add_i32 m0, s20, 0x2000
	s_add_i32 s20, s23, s88
	global_load_lds_dwordx4 v[202:203], off
	v_lshl_add_u64 v[202:203], v[162:163], 0, s[72:73]
	s_mov_b32 m0, s20
	s_nop 0
	global_load_lds_dwordx4 v[202:203], off
	v_lshl_add_u64 v[202:203], v[162:163], 0, s[74:75]
	s_add_i32 m0, s20, 0x2000
	s_nop 0
	global_load_lds_dwordx4 v[202:203], off
	v_lshl_add_u64 v[202:203], s[68:69], 0, v[130:131]
	s_mov_b32 m0, s89
	v_lshl_add_u64 v[234:235], v[202:203], 0, s[64:65]
	global_load_lds_dwordx4 v[202:203], off
	s_mov_b32 m0, s90
	s_nop 0
	global_load_lds_dwordx4 v[234:235], off
	s_waitcnt vmcnt(8) lgkmcnt(0)
	s_barrier
	v_mfma_f32_16x16x32_bf16 v[62:65], v[134:137], v[190:193], 0
	v_mfma_f32_16x16x32_bf16 v[62:65], v[142:145], v[194:197], v[62:65]
	v_mfma_f32_16x16x32_bf16 v[58:61], v[146:149], v[190:193], 0
	v_mfma_f32_16x16x32_bf16 v[58:61], v[150:153], v[194:197], v[58:61]
	v_mfma_f32_16x16x32_bf16 v[46:49], v[134:137], v[198:201], 0
	v_mfma_f32_16x16x32_bf16 v[46:49], v[142:145], v[214:217], v[46:49]
	v_mfma_f32_16x16x32_bf16 v[42:45], v[146:149], v[198:201], 0
	v_mfma_f32_16x16x32_bf16 v[42:45], v[150:153], v[214:217], v[42:45]
	v_mfma_f32_16x16x32_bf16 v[30:33], v[134:137], v[218:221], 0
	v_mfma_f32_16x16x32_bf16 v[30:33], v[142:145], v[222:225], v[30:33]
	v_mfma_f32_16x16x32_bf16 v[26:29], v[146:149], v[218:221], 0
	v_mfma_f32_16x16x32_bf16 v[26:29], v[150:153], v[222:225], v[26:29]
	v_mfma_f32_16x16x32_bf16 v[14:17], v[134:137], v[226:229], 0
	v_mfma_f32_16x16x32_bf16 v[14:17], v[142:145], v[230:233], v[14:17]
	v_mfma_f32_16x16x32_bf16 v[10:13], v[146:149], v[226:229], 0
	v_mfma_f32_16x16x32_bf16 v[10:13], v[150:153], v[230:233], v[10:13]
	v_mfma_f32_16x16x32_bf16 v[54:57], v[154:157], v[190:193], 0
	v_mfma_f32_16x16x32_bf16 v[54:57], v[158:161], v[194:197], v[54:57]
	v_mfma_f32_16x16x32_bf16 v[50:53], v[182:185], v[190:193], 0
	v_mfma_f32_16x16x32_bf16 v[50:53], v[186:189], v[194:197], v[50:53]
	v_mfma_f32_16x16x32_bf16 v[38:41], v[154:157], v[198:201], 0
	v_mfma_f32_16x16x32_bf16 v[38:41], v[158:161], v[214:217], v[38:41]
	v_mfma_f32_16x16x32_bf16 v[34:37], v[182:185], v[198:201], 0
	v_mfma_f32_16x16x32_bf16 v[34:37], v[186:189], v[214:217], v[34:37]
	v_mfma_f32_16x16x32_bf16 v[22:25], v[154:157], v[218:221], 0
	v_mfma_f32_16x16x32_bf16 v[22:25], v[158:161], v[222:225], v[22:25]
	v_mfma_f32_16x16x32_bf16 v[18:21], v[182:185], v[218:221], 0
	v_mfma_f32_16x16x32_bf16 v[18:21], v[186:189], v[222:225], v[18:21]
	v_mfma_f32_16x16x32_bf16 v[6:9], v[154:157], v[226:229], 0
	v_mfma_f32_16x16x32_bf16 v[6:9], v[158:161], v[230:233], v[6:9]
	v_mfma_f32_16x16x32_bf16 v[2:5], v[182:185], v[226:229], 0
	v_mfma_f32_16x16x32_bf16 v[2:5], v[186:189], v[230:233], v[2:5]
	s_barrier
	s_add_i32 s20, 0, 0x18000
	s_add_i32 s21, 0, 0x1c000
	ds_read_b128 v[134:137], v243 offset:32768
	ds_read_b128 v[142:145], v243 offset:33792
	ds_read_b128 v[146:149], v243 offset:34816
	ds_read_b128 v[150:153], v243 offset:35840
	ds_read_b128 v[154:157], v243 offset:49152
	ds_read_b128 v[158:161], v243 offset:50176
	ds_read_b128 v[182:185], v243 offset:51200
	ds_read_b128 v[186:189], v243 offset:52224
	ds_read_b128 v[190:193], v141 offset:32768
	ds_read_b128 v[194:197], v141 offset:33792
	ds_read_b128 v[198:201], v141 offset:34816
	ds_read_b128 v[214:217], v141 offset:35840
	ds_read_b128 v[218:221], v141 offset:36864
	ds_read_b128 v[222:225], v141 offset:37888
	ds_read_b128 v[226:229], v141 offset:38912
	ds_read_b128 v[230:233], v141 offset:39936
	s_mov_b32 m0, s91
	v_lshl_add_u64 v[234:235], v[202:203], 0, s[72:73]
	global_load_lds_dwordx4 v[234:235], off
	v_lshl_add_u64 v[234:235], v[202:203], 0, s[74:75]
	s_mov_b32 m0, s96
	s_nop 0
	global_load_lds_dwordx4 v[234:235], off
	s_waitcnt vmcnt(8) lgkmcnt(0)
	s_barrier
	v_mfma_f32_16x16x32_bf16 v[126:129], v[134:137], v[190:193], v[126:129]
	v_mfma_f32_16x16x32_bf16 v[126:129], v[142:145], v[194:197], v[126:129]
	v_mfma_f32_16x16x32_bf16 v[122:125], v[146:149], v[190:193], v[122:125]
	v_mfma_f32_16x16x32_bf16 v[122:125], v[150:153], v[194:197], v[122:125]
	v_mfma_f32_16x16x32_bf16 v[110:113], v[134:137], v[198:201], v[110:113]
	v_mfma_f32_16x16x32_bf16 v[110:113], v[142:145], v[214:217], v[110:113]
	v_mfma_f32_16x16x32_bf16 v[106:109], v[146:149], v[198:201], v[106:109]
	v_mfma_f32_16x16x32_bf16 v[106:109], v[150:153], v[214:217], v[106:109]
	v_mfma_f32_16x16x32_bf16 v[94:97], v[134:137], v[218:221], v[94:97]
	v_mfma_f32_16x16x32_bf16 v[94:97], v[142:145], v[222:225], v[94:97]
	v_mfma_f32_16x16x32_bf16 v[90:93], v[146:149], v[218:221], v[90:93]
	v_mfma_f32_16x16x32_bf16 v[90:93], v[150:153], v[222:225], v[90:93]
	v_mfma_f32_16x16x32_bf16 v[78:81], v[134:137], v[226:229], v[78:81]
	v_mfma_f32_16x16x32_bf16 v[78:81], v[142:145], v[230:233], v[78:81]
	v_mfma_f32_16x16x32_bf16 v[74:77], v[146:149], v[226:229], v[74:77]
	v_mfma_f32_16x16x32_bf16 v[74:77], v[150:153], v[230:233], v[74:77]
	v_mfma_f32_16x16x32_bf16 v[118:121], v[154:157], v[190:193], v[118:121]
	v_mfma_f32_16x16x32_bf16 v[118:121], v[158:161], v[194:197], v[118:121]
	v_mfma_f32_16x16x32_bf16 v[114:117], v[182:185], v[190:193], v[114:117]
	v_mfma_f32_16x16x32_bf16 v[114:117], v[186:189], v[194:197], v[114:117]
	v_mfma_f32_16x16x32_bf16 v[102:105], v[154:157], v[198:201], v[102:105]
	v_mfma_f32_16x16x32_bf16 v[102:105], v[158:161], v[214:217], v[102:105]
	v_mfma_f32_16x16x32_bf16 v[98:101], v[182:185], v[198:201], v[98:101]
	v_mfma_f32_16x16x32_bf16 v[98:101], v[186:189], v[214:217], v[98:101]
	v_mfma_f32_16x16x32_bf16 v[86:89], v[154:157], v[218:221], v[86:89]
	v_mfma_f32_16x16x32_bf16 v[86:89], v[158:161], v[222:225], v[86:89]
	v_mfma_f32_16x16x32_bf16 v[82:85], v[182:185], v[218:221], v[82:85]
	v_mfma_f32_16x16x32_bf16 v[82:85], v[186:189], v[222:225], v[82:85]
	v_mfma_f32_16x16x32_bf16 v[70:73], v[154:157], v[226:229], v[70:73]
	v_mfma_f32_16x16x32_bf16 v[70:73], v[158:161], v[230:233], v[70:73]
	v_mfma_f32_16x16x32_bf16 v[66:69], v[182:185], v[226:229], v[66:69]
	v_mfma_f32_16x16x32_bf16 v[66:69], v[186:189], v[230:233], v[66:69]
	s_barrier
	ds_read_b128 v[190:193], v141 offset:49152
	ds_read_b128 v[194:197], v141 offset:50176
	ds_read_b128 v[198:201], v141 offset:51200
	ds_read_b128 v[214:217], v141 offset:52224
	ds_read_b128 v[218:221], v141 offset:53248
	ds_read_b128 v[222:225], v141 offset:54272
	ds_read_b128 v[226:229], v141 offset:55296
	ds_read_b128 v[230:233], v141 offset:56320
	s_add_i32 s20, s20, s88
	s_mov_b32 m0, s20
	v_lshl_add_u64 v[234:235], v[162:163], 0, s[34:35]
	global_load_lds_dwordx4 v[234:235], off
	v_lshl_add_u64 v[234:235], v[162:163], 0, s[80:81]
	s_add_i32 m0, s20, 0x2000
	s_add_i32 s20, s21, s88
	global_load_lds_dwordx4 v[234:235], off
	v_lshl_add_u64 v[234:235], v[162:163], 0, s[38:39]
	s_mov_b32 m0, s20
	v_lshl_add_u64 v[162:163], v[162:163], 0, s[86:87]
	global_load_lds_dwordx4 v[234:235], off
	s_add_i32 m0, s20, 0x2000
	s_nop 0
	global_load_lds_dwordx4 v[162:163], off
	v_lshl_add_u64 v[162:163], v[202:203], 0, s[34:35]
	s_mov_b32 m0, s97
	s_nop 0
	global_load_lds_dwordx4 v[162:163], off
	v_lshl_add_u64 v[162:163], v[202:203], 0, s[80:81]
	s_mov_b32 m0, s58
	s_nop 0
	global_load_lds_dwordx4 v[162:163], off
	s_waitcnt vmcnt(8) lgkmcnt(0)
	s_barrier
	v_mfma_f32_16x16x32_bf16 v[62:65], v[134:137], v[190:193], v[62:65]
	v_mfma_f32_16x16x32_bf16 v[62:65], v[142:145], v[194:197], v[62:65]
	v_mfma_f32_16x16x32_bf16 v[58:61], v[146:149], v[190:193], v[58:61]
	v_mfma_f32_16x16x32_bf16 v[58:61], v[150:153], v[194:197], v[58:61]
	v_mfma_f32_16x16x32_bf16 v[46:49], v[134:137], v[198:201], v[46:49]
	v_mfma_f32_16x16x32_bf16 v[46:49], v[142:145], v[214:217], v[46:49]
	v_mfma_f32_16x16x32_bf16 v[42:45], v[146:149], v[198:201], v[42:45]
	v_mfma_f32_16x16x32_bf16 v[42:45], v[150:153], v[214:217], v[42:45]
	v_mfma_f32_16x16x32_bf16 v[30:33], v[134:137], v[218:221], v[30:33]
	v_mfma_f32_16x16x32_bf16 v[30:33], v[142:145], v[222:225], v[30:33]
	v_mfma_f32_16x16x32_bf16 v[26:29], v[146:149], v[218:221], v[26:29]
	v_mfma_f32_16x16x32_bf16 v[26:29], v[150:153], v[222:225], v[26:29]
	v_mfma_f32_16x16x32_bf16 v[14:17], v[134:137], v[226:229], v[14:17]
	v_mfma_f32_16x16x32_bf16 v[14:17], v[142:145], v[230:233], v[14:17]
	v_mfma_f32_16x16x32_bf16 v[10:13], v[146:149], v[226:229], v[10:13]
	v_mfma_f32_16x16x32_bf16 v[10:13], v[150:153], v[230:233], v[10:13]
	s_add_i32 s84, s84, 2
	s_add_u32 s6, s6, 0x100
	s_addc_u32 s7, s7, 0
	s_add_u32 s49, s49, 0x100
	s_addc_u32 s51, s51, 0
	v_mfma_f32_16x16x32_bf16 v[54:57], v[154:157], v[190:193], v[54:57]
	v_mfma_f32_16x16x32_bf16 v[54:57], v[158:161], v[194:197], v[54:57]
	v_mfma_f32_16x16x32_bf16 v[50:53], v[182:185], v[190:193], v[50:53]
	v_mfma_f32_16x16x32_bf16 v[50:53], v[186:189], v[194:197], v[50:53]
	v_mfma_f32_16x16x32_bf16 v[38:41], v[154:157], v[198:201], v[38:41]
	v_mfma_f32_16x16x32_bf16 v[38:41], v[158:161], v[214:217], v[38:41]
	v_mfma_f32_16x16x32_bf16 v[34:37], v[182:185], v[198:201], v[34:37]
	v_mfma_f32_16x16x32_bf16 v[34:37], v[186:189], v[214:217], v[34:37]
	v_mfma_f32_16x16x32_bf16 v[22:25], v[154:157], v[218:221], v[22:25]
	v_mfma_f32_16x16x32_bf16 v[22:25], v[158:161], v[222:225], v[22:25]
	v_mfma_f32_16x16x32_bf16 v[18:21], v[182:185], v[218:221], v[18:21]
	v_mfma_f32_16x16x32_bf16 v[18:21], v[186:189], v[222:225], v[18:21]
	v_mfma_f32_16x16x32_bf16 v[6:9], v[154:157], v[226:229], v[6:9]
	v_mfma_f32_16x16x32_bf16 v[6:9], v[158:161], v[230:233], v[6:9]
	v_mfma_f32_16x16x32_bf16 v[2:5], v[182:185], v[226:229], v[2:5]
	v_mfma_f32_16x16x32_bf16 v[2:5], v[186:189], v[230:233], v[2:5]
	s_barrier
	s_branch .LBB0_604
	.p2alignl 6, 3212836864
.LBB0_604:
	s_add_i32 s22, 0, 0x10000
	s_add_i32 s23, 0, 0x14000
	ds_read_b128 v[134:137], v243
	ds_read_b128 v[142:145], v243 offset:1024
	ds_read_b128 v[146:149], v243 offset:2048
	ds_read_b128 v[150:153], v243 offset:3072
	ds_read_b128 v[154:157], v243 offset:16384
	ds_read_b128 v[158:161], v243 offset:17408
	ds_read_b128 v[182:185], v243 offset:18432
	ds_read_b128 v[186:189], v243 offset:19456
	ds_read_b128 v[190:193], v141
	ds_read_b128 v[194:197], v141 offset:1024
	ds_read_b128 v[198:201], v141 offset:2048
	ds_read_b128 v[214:217], v141 offset:3072
	ds_read_b128 v[218:221], v141 offset:4096
	ds_read_b128 v[222:225], v141 offset:5120
	ds_read_b128 v[226:229], v141 offset:6144
	ds_read_b128 v[230:233], v141 offset:7168
	s_add_u32 s20, s6, 0xfffe0080
	s_addc_u32 s21, s7, -1
	s_cmp_eq_u32 s84, 4
	s_cselect_b32 s69, s42, s21
	s_cselect_b32 s68, s43, s20
	s_cselect_b32 s21, s46, s51
	s_cselect_b32 s20, s47, s49
	s_add_i32 m0, s89, 0xc000
	v_lshl_add_u64 v[162:163], s[6:7], 0, v[132:133]
	global_load_lds_dwordx4 v[162:163], off
	v_lshl_add_u64 v[162:163], v[162:163], 0, s[64:65]
	s_add_i32 m0, s89, 0xe000
	s_nop 0
	global_load_lds_dwordx4 v[162:163], off
	s_waitcnt vmcnt(8) lgkmcnt(0)
	s_barrier
	v_mfma_f32_16x16x32_bf16 v[126:129], v[134:137], v[190:193], v[126:129]
	v_mfma_f32_16x16x32_bf16 v[126:129], v[142:145], v[194:197], v[126:129]
	v_mfma_f32_16x16x32_bf16 v[122:125], v[146:149], v[190:193], v[122:125]
	v_mfma_f32_16x16x32_bf16 v[122:125], v[150:153], v[194:197], v[122:125]
	v_mfma_f32_16x16x32_bf16 v[110:113], v[134:137], v[198:201], v[110:113]
	v_mfma_f32_16x16x32_bf16 v[110:113], v[142:145], v[214:217], v[110:113]
	v_mfma_f32_16x16x32_bf16 v[106:109], v[146:149], v[198:201], v[106:109]
	v_mfma_f32_16x16x32_bf16 v[106:109], v[150:153], v[214:217], v[106:109]
	v_mfma_f32_16x16x32_bf16 v[94:97], v[134:137], v[218:221], v[94:97]
	v_mfma_f32_16x16x32_bf16 v[94:97], v[142:145], v[222:225], v[94:97]
	v_mfma_f32_16x16x32_bf16 v[90:93], v[146:149], v[218:221], v[90:93]
	v_mfma_f32_16x16x32_bf16 v[90:93], v[150:153], v[222:225], v[90:93]
	v_mfma_f32_16x16x32_bf16 v[78:81], v[134:137], v[226:229], v[78:81]
	v_mfma_f32_16x16x32_bf16 v[78:81], v[142:145], v[230:233], v[78:81]
	v_mfma_f32_16x16x32_bf16 v[74:77], v[146:149], v[226:229], v[74:77]
	v_mfma_f32_16x16x32_bf16 v[74:77], v[150:153], v[230:233], v[74:77]
	v_mfma_f32_16x16x32_bf16 v[118:121], v[154:157], v[190:193], v[118:121]
	v_mfma_f32_16x16x32_bf16 v[118:121], v[158:161], v[194:197], v[118:121]
	v_mfma_f32_16x16x32_bf16 v[114:117], v[182:185], v[190:193], v[114:117]
	v_mfma_f32_16x16x32_bf16 v[114:117], v[186:189], v[194:197], v[114:117]
	v_mfma_f32_16x16x32_bf16 v[102:105], v[154:157], v[198:201], v[102:105]
	v_mfma_f32_16x16x32_bf16 v[102:105], v[158:161], v[214:217], v[102:105]
	v_mfma_f32_16x16x32_bf16 v[98:101], v[182:185], v[198:201], v[98:101]
	v_mfma_f32_16x16x32_bf16 v[98:101], v[186:189], v[214:217], v[98:101]
	v_mfma_f32_16x16x32_bf16 v[86:89], v[154:157], v[218:221], v[86:89]
	v_mfma_f32_16x16x32_bf16 v[86:89], v[158:161], v[222:225], v[86:89]
	v_mfma_f32_16x16x32_bf16 v[82:85], v[182:185], v[218:221], v[82:85]
	v_mfma_f32_16x16x32_bf16 v[82:85], v[186:189], v[222:225], v[82:85]
	v_mfma_f32_16x16x32_bf16 v[70:73], v[154:157], v[226:229], v[70:73]
	v_mfma_f32_16x16x32_bf16 v[70:73], v[158:161], v[230:233], v[70:73]
	v_mfma_f32_16x16x32_bf16 v[66:69], v[182:185], v[226:229], v[66:69]
	v_mfma_f32_16x16x32_bf16 v[66:69], v[186:189], v[230:233], v[66:69]
	s_barrier
	ds_read_b128 v[190:193], v141 offset:16384
	ds_read_b128 v[194:197], v141 offset:17408
	ds_read_b128 v[198:201], v141 offset:18432
	ds_read_b128 v[214:217], v141 offset:19456
	ds_read_b128 v[218:221], v141 offset:20480
	ds_read_b128 v[222:225], v141 offset:21504
	ds_read_b128 v[226:229], v141 offset:22528
	ds_read_b128 v[230:233], v141 offset:23552
	v_lshl_add_u64 v[162:163], s[20:21], 0, v[0:1]
	s_add_i32 s20, s22, s88
	s_mov_b32 m0, s20
	s_nop 0
	s_nop 0
	global_load_lds_dwordx4 v[162:163], off
	v_lshl_add_u64 v[202:203], v[162:163], 0, s[64:65]
	s_add_i32 m0, s20, 0x2000
	s_add_i32 s20, s23, s88
	global_load_lds_dwordx4 v[202:203], off
	v_lshl_add_u64 v[202:203], v[162:163], 0, s[72:73]
	s_mov_b32 m0, s20
	s_nop 0
	global_load_lds_dwordx4 v[202:203], off
	v_lshl_add_u64 v[202:203], v[162:163], 0, s[74:75]
	s_add_i32 m0, s20, 0x2000
	s_nop 0
	global_load_lds_dwordx4 v[202:203], off
	v_lshl_add_u64 v[202:203], s[68:69], 0, v[130:131]
	s_mov_b32 m0, s89
	v_lshl_add_u64 v[234:235], v[202:203], 0, s[64:65]
	global_load_lds_dwordx4 v[202:203], off
	s_mov_b32 m0, s90
	s_nop 0
	global_load_lds_dwordx4 v[234:235], off
	s_waitcnt vmcnt(8) lgkmcnt(0)
	s_barrier
	v_mfma_f32_16x16x32_bf16 v[62:65], v[134:137], v[190:193], v[62:65]
	v_mfma_f32_16x16x32_bf16 v[62:65], v[142:145], v[194:197], v[62:65]
	v_mfma_f32_16x16x32_bf16 v[58:61], v[146:149], v[190:193], v[58:61]
	v_mfma_f32_16x16x32_bf16 v[58:61], v[150:153], v[194:197], v[58:61]
	v_mfma_f32_16x16x32_bf16 v[46:49], v[134:137], v[198:201], v[46:49]
	v_mfma_f32_16x16x32_bf16 v[46:49], v[142:145], v[214:217], v[46:49]
	v_mfma_f32_16x16x32_bf16 v[42:45], v[146:149], v[198:201], v[42:45]
	v_mfma_f32_16x16x32_bf16 v[42:45], v[150:153], v[214:217], v[42:45]
	v_mfma_f32_16x16x32_bf16 v[30:33], v[134:137], v[218:221], v[30:33]
	v_mfma_f32_16x16x32_bf16 v[30:33], v[142:145], v[222:225], v[30:33]
	v_mfma_f32_16x16x32_bf16 v[26:29], v[146:149], v[218:221], v[26:29]
	v_mfma_f32_16x16x32_bf16 v[26:29], v[150:153], v[222:225], v[26:29]
	v_mfma_f32_16x16x32_bf16 v[14:17], v[134:137], v[226:229], v[14:17]
	v_mfma_f32_16x16x32_bf16 v[14:17], v[142:145], v[230:233], v[14:17]
	v_mfma_f32_16x16x32_bf16 v[10:13], v[146:149], v[226:229], v[10:13]
	v_mfma_f32_16x16x32_bf16 v[10:13], v[150:153], v[230:233], v[10:13]
	v_mfma_f32_16x16x32_bf16 v[54:57], v[154:157], v[190:193], v[54:57]
	v_mfma_f32_16x16x32_bf16 v[54:57], v[158:161], v[194:197], v[54:57]
	v_mfma_f32_16x16x32_bf16 v[50:53], v[182:185], v[190:193], v[50:53]
	v_mfma_f32_16x16x32_bf16 v[50:53], v[186:189], v[194:197], v[50:53]
	v_mfma_f32_16x16x32_bf16 v[38:41], v[154:157], v[198:201], v[38:41]
	v_mfma_f32_16x16x32_bf16 v[38:41], v[158:161], v[214:217], v[38:41]
	v_mfma_f32_16x16x32_bf16 v[34:37], v[182:185], v[198:201], v[34:37]
	v_mfma_f32_16x16x32_bf16 v[34:37], v[186:189], v[214:217], v[34:37]
	v_mfma_f32_16x16x32_bf16 v[22:25], v[154:157], v[218:221], v[22:25]
	v_mfma_f32_16x16x32_bf16 v[22:25], v[158:161], v[222:225], v[22:25]
	v_mfma_f32_16x16x32_bf16 v[18:21], v[182:185], v[218:221], v[18:21]
	v_mfma_f32_16x16x32_bf16 v[18:21], v[186:189], v[222:225], v[18:21]
	v_mfma_f32_16x16x32_bf16 v[6:9], v[154:157], v[226:229], v[6:9]
	v_mfma_f32_16x16x32_bf16 v[6:9], v[158:161], v[230:233], v[6:9]
	v_mfma_f32_16x16x32_bf16 v[2:5], v[182:185], v[226:229], v[2:5]
	v_mfma_f32_16x16x32_bf16 v[2:5], v[186:189], v[230:233], v[2:5]
	s_barrier
	s_add_i32 s20, 0, 0x18000
	s_add_i32 s21, 0, 0x1c000
	ds_read_b128 v[134:137], v243 offset:32768
	ds_read_b128 v[142:145], v243 offset:33792
	ds_read_b128 v[146:149], v243 offset:34816
	ds_read_b128 v[150:153], v243 offset:35840
	ds_read_b128 v[154:157], v243 offset:49152
	ds_read_b128 v[158:161], v243 offset:50176
	ds_read_b128 v[182:185], v243 offset:51200
	ds_read_b128 v[186:189], v243 offset:52224
	ds_read_b128 v[190:193], v141 offset:32768
	ds_read_b128 v[194:197], v141 offset:33792
	ds_read_b128 v[198:201], v141 offset:34816
	ds_read_b128 v[214:217], v141 offset:35840
	ds_read_b128 v[218:221], v141 offset:36864
	ds_read_b128 v[222:225], v141 offset:37888
	ds_read_b128 v[226:229], v141 offset:38912
	ds_read_b128 v[230:233], v141 offset:39936
	s_mov_b32 m0, s91
	v_lshl_add_u64 v[234:235], v[202:203], 0, s[72:73]
	global_load_lds_dwordx4 v[234:235], off
	v_lshl_add_u64 v[234:235], v[202:203], 0, s[74:75]
	s_mov_b32 m0, s96
	s_nop 0
	global_load_lds_dwordx4 v[234:235], off
	s_waitcnt vmcnt(8) lgkmcnt(0)
	s_barrier
	v_mfma_f32_16x16x32_bf16 v[126:129], v[134:137], v[190:193], v[126:129]
	v_mfma_f32_16x16x32_bf16 v[126:129], v[142:145], v[194:197], v[126:129]
	v_mfma_f32_16x16x32_bf16 v[122:125], v[146:149], v[190:193], v[122:125]
	v_mfma_f32_16x16x32_bf16 v[122:125], v[150:153], v[194:197], v[122:125]
	v_mfma_f32_16x16x32_bf16 v[110:113], v[134:137], v[198:201], v[110:113]
	v_mfma_f32_16x16x32_bf16 v[110:113], v[142:145], v[214:217], v[110:113]
	v_mfma_f32_16x16x32_bf16 v[106:109], v[146:149], v[198:201], v[106:109]
	v_mfma_f32_16x16x32_bf16 v[106:109], v[150:153], v[214:217], v[106:109]
	v_mfma_f32_16x16x32_bf16 v[94:97], v[134:137], v[218:221], v[94:97]
	v_mfma_f32_16x16x32_bf16 v[94:97], v[142:145], v[222:225], v[94:97]
	v_mfma_f32_16x16x32_bf16 v[90:93], v[146:149], v[218:221], v[90:93]
	v_mfma_f32_16x16x32_bf16 v[90:93], v[150:153], v[222:225], v[90:93]
	v_mfma_f32_16x16x32_bf16 v[78:81], v[134:137], v[226:229], v[78:81]
	v_mfma_f32_16x16x32_bf16 v[78:81], v[142:145], v[230:233], v[78:81]
	v_mfma_f32_16x16x32_bf16 v[74:77], v[146:149], v[226:229], v[74:77]
	v_mfma_f32_16x16x32_bf16 v[74:77], v[150:153], v[230:233], v[74:77]
	v_mfma_f32_16x16x32_bf16 v[118:121], v[154:157], v[190:193], v[118:121]
	v_mfma_f32_16x16x32_bf16 v[118:121], v[158:161], v[194:197], v[118:121]
	v_mfma_f32_16x16x32_bf16 v[114:117], v[182:185], v[190:193], v[114:117]
	v_mfma_f32_16x16x32_bf16 v[114:117], v[186:189], v[194:197], v[114:117]
	v_mfma_f32_16x16x32_bf16 v[102:105], v[154:157], v[198:201], v[102:105]
	v_mfma_f32_16x16x32_bf16 v[102:105], v[158:161], v[214:217], v[102:105]
	v_mfma_f32_16x16x32_bf16 v[98:101], v[182:185], v[198:201], v[98:101]
	v_mfma_f32_16x16x32_bf16 v[98:101], v[186:189], v[214:217], v[98:101]
	v_mfma_f32_16x16x32_bf16 v[86:89], v[154:157], v[218:221], v[86:89]
	v_mfma_f32_16x16x32_bf16 v[86:89], v[158:161], v[222:225], v[86:89]
	v_mfma_f32_16x16x32_bf16 v[82:85], v[182:185], v[218:221], v[82:85]
	v_mfma_f32_16x16x32_bf16 v[82:85], v[186:189], v[222:225], v[82:85]
	v_mfma_f32_16x16x32_bf16 v[70:73], v[154:157], v[226:229], v[70:73]
	v_mfma_f32_16x16x32_bf16 v[70:73], v[158:161], v[230:233], v[70:73]
	v_mfma_f32_16x16x32_bf16 v[66:69], v[182:185], v[226:229], v[66:69]
	v_mfma_f32_16x16x32_bf16 v[66:69], v[186:189], v[230:233], v[66:69]
	s_barrier
	ds_read_b128 v[190:193], v141 offset:49152
	ds_read_b128 v[194:197], v141 offset:50176
	ds_read_b128 v[198:201], v141 offset:51200
	ds_read_b128 v[214:217], v141 offset:52224
	ds_read_b128 v[218:221], v141 offset:53248
	ds_read_b128 v[222:225], v141 offset:54272
	ds_read_b128 v[226:229], v141 offset:55296
	ds_read_b128 v[230:233], v141 offset:56320
	s_add_i32 s20, s20, s88
	s_mov_b32 m0, s20
	v_lshl_add_u64 v[234:235], v[162:163], 0, s[34:35]
	global_load_lds_dwordx4 v[234:235], off
	v_lshl_add_u64 v[234:235], v[162:163], 0, s[80:81]
	s_add_i32 m0, s20, 0x2000
	s_add_i32 s20, s21, s88
	global_load_lds_dwordx4 v[234:235], off
	v_lshl_add_u64 v[234:235], v[162:163], 0, s[38:39]
	s_mov_b32 m0, s20
	v_lshl_add_u64 v[162:163], v[162:163], 0, s[86:87]
	global_load_lds_dwordx4 v[234:235], off
	s_add_i32 m0, s20, 0x2000
	s_nop 0
	global_load_lds_dwordx4 v[162:163], off
	v_lshl_add_u64 v[162:163], v[202:203], 0, s[34:35]
	s_mov_b32 m0, s97
	s_nop 0
	global_load_lds_dwordx4 v[162:163], off
	v_lshl_add_u64 v[162:163], v[202:203], 0, s[80:81]
	s_mov_b32 m0, s58
	s_nop 0
	global_load_lds_dwordx4 v[162:163], off
	s_waitcnt vmcnt(8) lgkmcnt(0)
	s_barrier
	v_mfma_f32_16x16x32_bf16 v[62:65], v[134:137], v[190:193], v[62:65]
	v_mfma_f32_16x16x32_bf16 v[62:65], v[142:145], v[194:197], v[62:65]
	v_mfma_f32_16x16x32_bf16 v[58:61], v[146:149], v[190:193], v[58:61]
	v_mfma_f32_16x16x32_bf16 v[58:61], v[150:153], v[194:197], v[58:61]
	v_mfma_f32_16x16x32_bf16 v[46:49], v[134:137], v[198:201], v[46:49]
	v_mfma_f32_16x16x32_bf16 v[46:49], v[142:145], v[214:217], v[46:49]
	v_mfma_f32_16x16x32_bf16 v[42:45], v[146:149], v[198:201], v[42:45]
	v_mfma_f32_16x16x32_bf16 v[42:45], v[150:153], v[214:217], v[42:45]
	v_mfma_f32_16x16x32_bf16 v[30:33], v[134:137], v[218:221], v[30:33]
	v_mfma_f32_16x16x32_bf16 v[30:33], v[142:145], v[222:225], v[30:33]
	v_mfma_f32_16x16x32_bf16 v[26:29], v[146:149], v[218:221], v[26:29]
	v_mfma_f32_16x16x32_bf16 v[26:29], v[150:153], v[222:225], v[26:29]
	v_mfma_f32_16x16x32_bf16 v[14:17], v[134:137], v[226:229], v[14:17]
	v_mfma_f32_16x16x32_bf16 v[14:17], v[142:145], v[230:233], v[14:17]
	v_mfma_f32_16x16x32_bf16 v[10:13], v[146:149], v[226:229], v[10:13]
	v_mfma_f32_16x16x32_bf16 v[10:13], v[150:153], v[230:233], v[10:13]
	s_add_i32 s84, s84, 2
	s_add_u32 s6, s6, 0x100
	s_addc_u32 s7, s7, 0
	s_add_u32 s49, s49, 0x100
	s_addc_u32 s51, s51, 0
	v_mfma_f32_16x16x32_bf16 v[54:57], v[154:157], v[190:193], v[54:57]
	v_mfma_f32_16x16x32_bf16 v[54:57], v[158:161], v[194:197], v[54:57]
	v_mfma_f32_16x16x32_bf16 v[50:53], v[182:185], v[190:193], v[50:53]
	v_mfma_f32_16x16x32_bf16 v[50:53], v[186:189], v[194:197], v[50:53]
	v_mfma_f32_16x16x32_bf16 v[38:41], v[154:157], v[198:201], v[38:41]
	v_mfma_f32_16x16x32_bf16 v[38:41], v[158:161], v[214:217], v[38:41]
	v_mfma_f32_16x16x32_bf16 v[34:37], v[182:185], v[198:201], v[34:37]
	v_mfma_f32_16x16x32_bf16 v[34:37], v[186:189], v[214:217], v[34:37]
	v_mfma_f32_16x16x32_bf16 v[22:25], v[154:157], v[218:221], v[22:25]
	v_mfma_f32_16x16x32_bf16 v[22:25], v[158:161], v[222:225], v[22:25]
	v_mfma_f32_16x16x32_bf16 v[18:21], v[182:185], v[218:221], v[18:21]
	v_mfma_f32_16x16x32_bf16 v[18:21], v[186:189], v[222:225], v[18:21]
	v_mfma_f32_16x16x32_bf16 v[6:9], v[154:157], v[226:229], v[6:9]
	v_mfma_f32_16x16x32_bf16 v[6:9], v[158:161], v[230:233], v[6:9]
	v_mfma_f32_16x16x32_bf16 v[2:5], v[182:185], v[226:229], v[2:5]
	v_mfma_f32_16x16x32_bf16 v[2:5], v[186:189], v[230:233], v[2:5]
	s_barrier
	s_cmp_gt_u32 s84, 5
	s_cbranch_scc0 .LBB0_604
	s_setprio 0
	s_and_b64 vcc, exec, s[52:53]
	s_cbranch_vccz .LBB0_607
	s_barrier

.LBB0_777:
	s_ashr_i32 s61, s60, 31
	s_lshl_b64 s[20:21], s[60:61], 19
	s_add_u32 s62, s94, s20
	s_addc_u32 s63, s95, s21
	s_and_b64 s[20:21], s[56:57], exec
	s_cselect_b32 s61, s63, s77
	s_cselect_b32 s85, s62, s76
	s_ashr_i32 s59, s58, 31
	s_lshl_b64 s[20:21], s[58:59], 19
	s_add_u32 s68, s15, s20
	s_addc_u32 s69, s42, s21
	s_and_b64 s[20:21], s[56:57], exec
	s_cselect_b32 s59, s69, s79
	s_cselect_b32 s86, s68, s78
	s_add_u32 s76, s76, 0x40080
	s_addc_u32 s77, s77, 0
	s_add_u32 s87, s78, 0x100
	v_mov_b32_e32 v2, 0
	s_addc_u32 vcc_lo, s79, 0
	s_mov_b32 vcc_hi, -2
	s_waitcnt lgkmcnt(0)
	v_add_u32_e32 v243, 0x10000, v193
	s_add_i32 s22, 0, 0x10000
	s_add_i32 s23, 0, 0x14000
	ds_read_b128 v[130:133], v243
	ds_read_b128 v[134:137], v243 offset:1024
	ds_read_b128 v[138:141], v243 offset:2048
	ds_read_b128 v[142:145], v243 offset:3072
	ds_read_b128 v[146:149], v243 offset:16384
	ds_read_b128 v[150:153], v243 offset:17408
	ds_read_b128 v[154:157], v243 offset:18432
	ds_read_b128 v[158:161], v243 offset:19456
	ds_read_b128 v[184:187], v196
	ds_read_b128 v[188:191], v196 offset:1024
	ds_read_b128 v[198:201], v196 offset:2048
	ds_read_b128 v[214:217], v196 offset:3072
	ds_read_b128 v[218:221], v196 offset:4096
	ds_read_b128 v[222:225], v196 offset:5120
	ds_read_b128 v[226:229], v196 offset:6144
	ds_read_b128 v[230:233], v196 offset:7168
	s_cmp_eq_u64 s[50:51], 0
	s_cbranch_scc0 .Lpr_778
	s_setprio 1

.Lmid1_778:
	s_add_i32 s22, 0, 0x10000
	s_add_i32 s23, 0, 0x14000
	s_add_u32 s20, s76, 0xfffc0080
	s_addc_u32 s21, s77, -1
	s_cmp_eq_u32 vcc_hi, 12
	s_cselect_b32 s79, s61, s21
	s_cselect_b32 s78, s85, s20
	s_cselect_b32 s21, s59, vcc_lo
	s_cselect_b32 s20, s86, s87
	s_add_i32 m0, s43, 0xc000
	v_lshl_add_u64 v[202:203], s[76:77], 0, v[182:183]
	global_load_lds_dwordx4 v[202:203], off
	v_lshl_add_u64 v[202:203], v[202:203], 0, s[72:73]
	s_add_i32 m0, s43, 0xe000
	s_nop 0
	global_load_lds_dwordx4 v[202:203], off
	s_waitcnt vmcnt(8) lgkmcnt(0)
	s_barrier
	v_mfma_f32_16x16x32_bf16 v[126:129], v[130:133], v[184:187], 0
	v_mfma_f32_16x16x32_bf16 v[126:129], v[134:137], v[188:191], v[126:129]
	v_mfma_f32_16x16x32_bf16 v[122:125], v[138:141], v[184:187], 0
	v_mfma_f32_16x16x32_bf16 v[122:125], v[142:145], v[188:191], v[122:125]
	v_mfma_f32_16x16x32_bf16 v[110:113], v[130:133], v[198:201], 0
	v_mfma_f32_16x16x32_bf16 v[110:113], v[134:137], v[214:217], v[110:113]
	v_mfma_f32_16x16x32_bf16 v[106:109], v[138:141], v[198:201], 0
	v_mfma_f32_16x16x32_bf16 v[106:109], v[142:145], v[214:217], v[106:109]
	v_mfma_f32_16x16x32_bf16 v[94:97], v[130:133], v[218:221], 0
	v_mfma_f32_16x16x32_bf16 v[94:97], v[134:137], v[222:225], v[94:97]
	v_mfma_f32_16x16x32_bf16 v[90:93], v[138:141], v[218:221], 0
	v_mfma_f32_16x16x32_bf16 v[90:93], v[142:145], v[222:225], v[90:93]
	v_mfma_f32_16x16x32_bf16 v[78:81], v[130:133], v[226:229], 0
	v_mfma_f32_16x16x32_bf16 v[78:81], v[134:137], v[230:233], v[78:81]
	v_mfma_f32_16x16x32_bf16 v[74:77], v[138:141], v[226:229], 0
	v_mfma_f32_16x16x32_bf16 v[74:77], v[142:145], v[230:233], v[74:77]
	v_mfma_f32_16x16x32_bf16 v[118:121], v[146:149], v[184:187], 0
	v_mfma_f32_16x16x32_bf16 v[118:121], v[150:153], v[188:191], v[118:121]
	v_mfma_f32_16x16x32_bf16 v[114:117], v[154:157], v[184:187], 0
	v_mfma_f32_16x16x32_bf16 v[114:117], v[158:161], v[188:191], v[114:117]
	v_mfma_f32_16x16x32_bf16 v[102:105], v[146:149], v[198:201], 0
	v_mfma_f32_16x16x32_bf16 v[102:105], v[150:153], v[214:217], v[102:105]
	v_mfma_f32_16x16x32_bf16 v[98:101], v[154:157], v[198:201], 0
	v_mfma_f32_16x16x32_bf16 v[98:101], v[158:161], v[214:217], v[98:101]
	v_mfma_f32_16x16x32_bf16 v[86:89], v[146:149], v[218:221], 0
	v_mfma_f32_16x16x32_bf16 v[86:89], v[150:153], v[222:225], v[86:89]
	v_mfma_f32_16x16x32_bf16 v[82:85], v[154:157], v[218:221], 0
	v_mfma_f32_16x16x32_bf16 v[82:85], v[158:161], v[222:225], v[82:85]
	v_mfma_f32_16x16x32_bf16 v[70:73], v[146:149], v[226:229], 0
	v_mfma_f32_16x16x32_bf16 v[70:73], v[150:153], v[230:233], v[70:73]
	v_mfma_f32_16x16x32_bf16 v[66:69], v[154:157], v[226:229], 0
	v_mfma_f32_16x16x32_bf16 v[66:69], v[158:161], v[230:233], v[66:69]
	s_barrier
	ds_read_b128 v[184:187], v196 offset:16384
	ds_read_b128 v[188:191], v196 offset:17408
	ds_read_b128 v[198:201], v196 offset:18432
	ds_read_b128 v[214:217], v196 offset:19456
	ds_read_b128 v[218:221], v196 offset:20480
	ds_read_b128 v[222:225], v196 offset:21504
	ds_read_b128 v[226:229], v196 offset:22528
	ds_read_b128 v[230:233], v196 offset:23552
	v_lshl_add_u64 v[202:203], s[20:21], 0, v[0:1]
	s_add_i32 s20, s22, s14
	s_mov_b32 m0, s20
	s_nop 0
	s_nop 0
	global_load_lds_dwordx4 v[202:203], off
	v_lshl_add_u64 v[234:235], v[202:203], 0, s[72:73]
	s_add_i32 m0, s20, 0x2000
	s_add_i32 s20, s23, s14
	global_load_lds_dwordx4 v[234:235], off
	v_lshl_add_u64 v[234:235], v[202:203], 0, s[28:29]
	s_mov_b32 m0, s20
	s_nop 0
	global_load_lds_dwordx4 v[234:235], off
	v_lshl_add_u64 v[234:235], v[202:203], 0, s[82:83]
	s_add_i32 m0, s20, 0x2000
	s_nop 0
	global_load_lds_dwordx4 v[234:235], off
	v_lshl_add_u64 v[234:235], s[78:79], 0, v[162:163]
	s_mov_b32 m0, s43
	v_lshl_add_u64 v[236:237], v[234:235], 0, s[72:73]
	global_load_lds_dwordx4 v[234:235], off
	s_mov_b32 m0, s46
	s_nop 0
	global_load_lds_dwordx4 v[236:237], off
	s_waitcnt vmcnt(8) lgkmcnt(0)
	s_barrier
	v_mfma_f32_16x16x32_bf16 v[62:65], v[130:133], v[184:187], 0
	v_mfma_f32_16x16x32_bf16 v[62:65], v[134:137], v[188:191], v[62:65]
	v_mfma_f32_16x16x32_bf16 v[58:61], v[138:141], v[184:187], 0
	v_mfma_f32_16x16x32_bf16 v[58:61], v[142:145], v[188:191], v[58:61]
	v_mfma_f32_16x16x32_bf16 v[46:49], v[130:133], v[198:201], 0
	v_mfma_f32_16x16x32_bf16 v[46:49], v[134:137], v[214:217], v[46:49]
	v_mfma_f32_16x16x32_bf16 v[42:45], v[138:141], v[198:201], 0
	v_mfma_f32_16x16x32_bf16 v[42:45], v[142:145], v[214:217], v[42:45]
	v_mfma_f32_16x16x32_bf16 v[30:33], v[130:133], v[218:221], 0
	v_mfma_f32_16x16x32_bf16 v[30:33], v[134:137], v[222:225], v[30:33]
	v_mfma_f32_16x16x32_bf16 v[26:29], v[138:141], v[218:221], 0
	v_mfma_f32_16x16x32_bf16 v[26:29], v[142:145], v[222:225], v[26:29]
	v_mfma_f32_16x16x32_bf16 v[14:17], v[130:133], v[226:229], 0
	v_mfma_f32_16x16x32_bf16 v[14:17], v[134:137], v[230:233], v[14:17]
	v_mfma_f32_16x16x32_bf16 v[10:13], v[138:141], v[226:229], 0
	v_mfma_f32_16x16x32_bf16 v[10:13], v[142:145], v[230:233], v[10:13]
	v_mfma_f32_16x16x32_bf16 v[54:57], v[146:149], v[184:187], 0
	v_mfma_f32_16x16x32_bf16 v[54:57], v[150:153], v[188:191], v[54:57]
	v_mfma_f32_16x16x32_bf16 v[50:53], v[154:157], v[184:187], 0
	v_mfma_f32_16x16x32_bf16 v[50:53], v[158:161], v[188:191], v[50:53]
	v_mfma_f32_16x16x32_bf16 v[38:41], v[146:149], v[198:201], 0
	v_mfma_f32_16x16x32_bf16 v[38:41], v[150:153], v[214:217], v[38:41]
	v_mfma_f32_16x16x32_bf16 v[34:37], v[154:157], v[198:201], 0
	v_mfma_f32_16x16x32_bf16 v[34:37], v[158:161], v[214:217], v[34:37]
	v_mfma_f32_16x16x32_bf16 v[22:25], v[146:149], v[218:221], 0
	v_mfma_f32_16x16x32_bf16 v[22:25], v[150:153], v[222:225], v[22:25]
	v_mfma_f32_16x16x32_bf16 v[18:21], v[154:157], v[218:221], 0
	v_mfma_f32_16x16x32_bf16 v[18:21], v[158:161], v[222:225], v[18:21]
	v_mfma_f32_16x16x32_bf16 v[6:9], v[146:149], v[226:229], 0
	v_mfma_f32_16x16x32_bf16 v[6:9], v[150:153], v[230:233], v[6:9]
	v_mfma_f32_16x16x32_bf16 v[2:5], v[154:157], v[226:229], 0
	v_mfma_f32_16x16x32_bf16 v[2:5], v[158:161], v[230:233], v[2:5]
	s_barrier
	s_add_i32 s20, 0, 0x18000
	s_add_i32 s21, 0, 0x1c000
	ds_read_b128 v[130:133], v243 offset:32768
	ds_read_b128 v[134:137], v243 offset:33792
	ds_read_b128 v[138:141], v243 offset:34816
	ds_read_b128 v[142:145], v243 offset:35840
	ds_read_b128 v[146:149], v243 offset:49152
	ds_read_b128 v[150:153], v243 offset:50176
	ds_read_b128 v[154:157], v243 offset:51200
	ds_read_b128 v[158:161], v243 offset:52224
	ds_read_b128 v[184:187], v196 offset:32768
	ds_read_b128 v[188:191], v196 offset:33792
	ds_read_b128 v[198:201], v196 offset:34816
	ds_read_b128 v[214:217], v196 offset:35840
	ds_read_b128 v[218:221], v196 offset:36864
	ds_read_b128 v[222:225], v196 offset:37888
	ds_read_b128 v[226:229], v196 offset:38912
	ds_read_b128 v[230:233], v196 offset:39936
	s_mov_b32 m0, s47
	v_lshl_add_u64 v[236:237], v[234:235], 0, s[28:29]
	global_load_lds_dwordx4 v[236:237], off
	v_lshl_add_u64 v[236:237], v[234:235], 0, s[82:83]
	s_mov_b32 m0, s88
	s_nop 0
	global_load_lds_dwordx4 v[236:237], off
	s_waitcnt vmcnt(8) lgkmcnt(0)
	s_barrier
	v_mfma_f32_16x16x32_bf16 v[126:129], v[130:133], v[184:187], v[126:129]
	v_mfma_f32_16x16x32_bf16 v[126:129], v[134:137], v[188:191], v[126:129]
	v_mfma_f32_16x16x32_bf16 v[122:125], v[138:141], v[184:187], v[122:125]
	v_mfma_f32_16x16x32_bf16 v[122:125], v[142:145], v[188:191], v[122:125]
	v_mfma_f32_16x16x32_bf16 v[110:113], v[130:133], v[198:201], v[110:113]
	v_mfma_f32_16x16x32_bf16 v[110:113], v[134:137], v[214:217], v[110:113]
	v_mfma_f32_16x16x32_bf16 v[106:109], v[138:141], v[198:201], v[106:109]
	v_mfma_f32_16x16x32_bf16 v[106:109], v[142:145], v[214:217], v[106:109]
	v_mfma_f32_16x16x32_bf16 v[94:97], v[130:133], v[218:221], v[94:97]
	v_mfma_f32_16x16x32_bf16 v[94:97], v[134:137], v[222:225], v[94:97]
	v_mfma_f32_16x16x32_bf16 v[90:93], v[138:141], v[218:221], v[90:93]
	v_mfma_f32_16x16x32_bf16 v[90:93], v[142:145], v[222:225], v[90:93]
	v_mfma_f32_16x16x32_bf16 v[78:81], v[130:133], v[226:229], v[78:81]
	v_mfma_f32_16x16x32_bf16 v[78:81], v[134:137], v[230:233], v[78:81]
	v_mfma_f32_16x16x32_bf16 v[74:77], v[138:141], v[226:229], v[74:77]
	v_mfma_f32_16x16x32_bf16 v[74:77], v[142:145], v[230:233], v[74:77]
	v_mfma_f32_16x16x32_bf16 v[118:121], v[146:149], v[184:187], v[118:121]
	v_mfma_f32_16x16x32_bf16 v[118:121], v[150:153], v[188:191], v[118:121]
	v_mfma_f32_16x16x32_bf16 v[114:117], v[154:157], v[184:187], v[114:117]
	v_mfma_f32_16x16x32_bf16 v[114:117], v[158:161], v[188:191], v[114:117]
	v_mfma_f32_16x16x32_bf16 v[102:105], v[146:149], v[198:201], v[102:105]
	v_mfma_f32_16x16x32_bf16 v[102:105], v[150:153], v[214:217], v[102:105]
	v_mfma_f32_16x16x32_bf16 v[98:101], v[154:157], v[198:201], v[98:101]
	v_mfma_f32_16x16x32_bf16 v[98:101], v[158:161], v[214:217], v[98:101]
	v_mfma_f32_16x16x32_bf16 v[86:89], v[146:149], v[218:221], v[86:89]
	v_mfma_f32_16x16x32_bf16 v[86:89], v[150:153], v[222:225], v[86:89]
	v_mfma_f32_16x16x32_bf16 v[82:85], v[154:157], v[218:221], v[82:85]
	v_mfma_f32_16x16x32_bf16 v[82:85], v[158:161], v[222:225], v[82:85]
	v_mfma_f32_16x16x32_bf16 v[70:73], v[146:149], v[226:229], v[70:73]
	v_mfma_f32_16x16x32_bf16 v[70:73], v[150:153], v[230:233], v[70:73]
	v_mfma_f32_16x16x32_bf16 v[66:69], v[154:157], v[226:229], v[66:69]
	v_mfma_f32_16x16x32_bf16 v[66:69], v[158:161], v[230:233], v[66:69]
	s_barrier
	ds_read_b128 v[184:187], v196 offset:49152
	ds_read_b128 v[188:191], v196 offset:50176
	ds_read_b128 v[198:201], v196 offset:51200
	ds_read_b128 v[214:217], v196 offset:52224
	ds_read_b128 v[218:221], v196 offset:53248
	ds_read_b128 v[222:225], v196 offset:54272
	ds_read_b128 v[226:229], v196 offset:55296
	ds_read_b128 v[230:233], v196 offset:56320
	s_add_i32 s20, s20, s14
	s_mov_b32 m0, s20
	v_lshl_add_u64 v[236:237], v[202:203], 0, s[34:35]
	global_load_lds_dwordx4 v[236:237], off
	v_lshl_add_u64 v[236:237], v[202:203], 0, s[38:39]
	s_add_i32 m0, s20, 0x2000
	s_add_i32 s20, s21, s14
	global_load_lds_dwordx4 v[236:237], off
	v_lshl_add_u64 v[236:237], v[202:203], 0, s[44:45]
	s_mov_b32 m0, s20
	v_lshl_add_u64 v[202:203], v[202:203], 0, s[10:11]
	global_load_lds_dwordx4 v[236:237], off
	s_add_i32 m0, s20, 0x2000
	s_nop 0
	global_load_lds_dwordx4 v[202:203], off
	v_lshl_add_u64 v[202:203], v[234:235], 0, s[34:35]
	s_mov_b32 m0, s89
	s_nop 0
	global_load_lds_dwordx4 v[202:203], off
	v_lshl_add_u64 v[202:203], v[234:235], 0, s[38:39]
	s_mov_b32 m0, s90
	s_nop 0
	global_load_lds_dwordx4 v[202:203], off
	s_waitcnt vmcnt(8) lgkmcnt(0)
	s_barrier
	v_mfma_f32_16x16x32_bf16 v[62:65], v[130:133], v[184:187], v[62:65]
	v_mfma_f32_16x16x32_bf16 v[62:65], v[134:137], v[188:191], v[62:65]
	v_mfma_f32_16x16x32_bf16 v[58:61], v[138:141], v[184:187], v[58:61]
	v_mfma_f32_16x16x32_bf16 v[58:61], v[142:145], v[188:191], v[58:61]
	v_mfma_f32_16x16x32_bf16 v[46:49], v[130:133], v[198:201], v[46:49]
	v_mfma_f32_16x16x32_bf16 v[46:49], v[134:137], v[214:217], v[46:49]
	v_mfma_f32_16x16x32_bf16 v[42:45], v[138:141], v[198:201], v[42:45]
	v_mfma_f32_16x16x32_bf16 v[42:45], v[142:145], v[214:217], v[42:45]
	v_mfma_f32_16x16x32_bf16 v[30:33], v[130:133], v[218:221], v[30:33]
	v_mfma_f32_16x16x32_bf16 v[30:33], v[134:137], v[222:225], v[30:33]
	v_mfma_f32_16x16x32_bf16 v[26:29], v[138:141], v[218:221], v[26:29]
	v_mfma_f32_16x16x32_bf16 v[26:29], v[142:145], v[222:225], v[26:29]
	v_mfma_f32_16x16x32_bf16 v[14:17], v[130:133], v[226:229], v[14:17]
	v_mfma_f32_16x16x32_bf16 v[14:17], v[134:137], v[230:233], v[14:17]
	v_mfma_f32_16x16x32_bf16 v[10:13], v[138:141], v[226:229], v[10:13]
	v_mfma_f32_16x16x32_bf16 v[10:13], v[142:145], v[230:233], v[10:13]
	s_add_i32 vcc_hi, vcc_hi, 2
	s_add_u32 s76, s76, 0x100
	s_addc_u32 s77, s77, 0
	s_add_u32 s87, s87, 0x100
	s_addc_u32 vcc_lo, vcc_lo, 0
	v_mfma_f32_16x16x32_bf16 v[54:57], v[146:149], v[184:187], v[54:57]
	v_mfma_f32_16x16x32_bf16 v[54:57], v[150:153], v[188:191], v[54:57]
	v_mfma_f32_16x16x32_bf16 v[50:53], v[154:157], v[184:187], v[50:53]
	v_mfma_f32_16x16x32_bf16 v[50:53], v[158:161], v[188:191], v[50:53]
	v_mfma_f32_16x16x32_bf16 v[38:41], v[146:149], v[198:201], v[38:41]
	v_mfma_f32_16x16x32_bf16 v[38:41], v[150:153], v[214:217], v[38:41]
	v_mfma_f32_16x16x32_bf16 v[34:37], v[154:157], v[198:201], v[34:37]
	v_mfma_f32_16x16x32_bf16 v[34:37], v[158:161], v[214:217], v[34:37]
	v_mfma_f32_16x16x32_bf16 v[22:25], v[146:149], v[218:221], v[22:25]
	v_mfma_f32_16x16x32_bf16 v[22:25], v[150:153], v[222:225], v[22:25]
	v_mfma_f32_16x16x32_bf16 v[18:21], v[154:157], v[218:221], v[18:21]
	v_mfma_f32_16x16x32_bf16 v[18:21], v[158:161], v[222:225], v[18:21]
	v_mfma_f32_16x16x32_bf16 v[6:9], v[146:149], v[226:229], v[6:9]
	v_mfma_f32_16x16x32_bf16 v[6:9], v[150:153], v[230:233], v[6:9]
	v_mfma_f32_16x16x32_bf16 v[2:5], v[154:157], v[226:229], v[2:5]
	v_mfma_f32_16x16x32_bf16 v[2:5], v[158:161], v[230:233], v[2:5]
	s_barrier
	s_branch .LBB0_778
	.p2alignl 6, 3212836864
.LBB0_778:
	s_add_i32 s22, 0, 0x10000
	s_add_i32 s23, 0, 0x14000
	ds_read_b128 v[130:133], v243
	ds_read_b128 v[134:137], v243 offset:1024
	ds_read_b128 v[138:141], v243 offset:2048
	ds_read_b128 v[142:145], v243 offset:3072
	ds_read_b128 v[146:149], v243 offset:16384
	ds_read_b128 v[150:153], v243 offset:17408
	ds_read_b128 v[154:157], v243 offset:18432
	ds_read_b128 v[158:161], v243 offset:19456
	ds_read_b128 v[184:187], v196
	ds_read_b128 v[188:191], v196 offset:1024
	ds_read_b128 v[198:201], v196 offset:2048
	ds_read_b128 v[214:217], v196 offset:3072
	ds_read_b128 v[218:221], v196 offset:4096
	ds_read_b128 v[222:225], v196 offset:5120
	ds_read_b128 v[226:229], v196 offset:6144
	ds_read_b128 v[230:233], v196 offset:7168
	s_add_u32 s20, s76, 0xfffc0080
	s_addc_u32 s21, s77, -1
	s_cmp_eq_u32 vcc_hi, 12
	s_cselect_b32 s79, s61, s21
	s_cselect_b32 s78, s85, s20
	s_cselect_b32 s21, s59, vcc_lo
	s_cselect_b32 s20, s86, s87
	s_add_i32 m0, s43, 0xc000
	v_lshl_add_u64 v[202:203], s[76:77], 0, v[182:183]
	global_load_lds_dwordx4 v[202:203], off
	v_lshl_add_u64 v[202:203], v[202:203], 0, s[72:73]
	s_add_i32 m0, s43, 0xe000
	s_nop 0
	global_load_lds_dwordx4 v[202:203], off
	s_waitcnt vmcnt(8) lgkmcnt(0)
	s_barrier
	v_mfma_f32_16x16x32_bf16 v[126:129], v[130:133], v[184:187], v[126:129]
	v_mfma_f32_16x16x32_bf16 v[126:129], v[134:137], v[188:191], v[126:129]
	v_mfma_f32_16x16x32_bf16 v[122:125], v[138:141], v[184:187], v[122:125]
	v_mfma_f32_16x16x32_bf16 v[122:125], v[142:145], v[188:191], v[122:125]
	v_mfma_f32_16x16x32_bf16 v[110:113], v[130:133], v[198:201], v[110:113]
	v_mfma_f32_16x16x32_bf16 v[110:113], v[134:137], v[214:217], v[110:113]
	v_mfma_f32_16x16x32_bf16 v[106:109], v[138:141], v[198:201], v[106:109]
	v_mfma_f32_16x16x32_bf16 v[106:109], v[142:145], v[214:217], v[106:109]
	v_mfma_f32_16x16x32_bf16 v[94:97], v[130:133], v[218:221], v[94:97]
	v_mfma_f32_16x16x32_bf16 v[94:97], v[134:137], v[222:225], v[94:97]
	v_mfma_f32_16x16x32_bf16 v[90:93], v[138:141], v[218:221], v[90:93]
	v_mfma_f32_16x16x32_bf16 v[90:93], v[142:145], v[222:225], v[90:93]
	v_mfma_f32_16x16x32_bf16 v[78:81], v[130:133], v[226:229], v[78:81]
	v_mfma_f32_16x16x32_bf16 v[78:81], v[134:137], v[230:233], v[78:81]
	v_mfma_f32_16x16x32_bf16 v[74:77], v[138:141], v[226:229], v[74:77]
	v_mfma_f32_16x16x32_bf16 v[74:77], v[142:145], v[230:233], v[74:77]
	v_mfma_f32_16x16x32_bf16 v[118:121], v[146:149], v[184:187], v[118:121]
	v_mfma_f32_16x16x32_bf16 v[118:121], v[150:153], v[188:191], v[118:121]
	v_mfma_f32_16x16x32_bf16 v[114:117], v[154:157], v[184:187], v[114:117]
	v_mfma_f32_16x16x32_bf16 v[114:117], v[158:161], v[188:191], v[114:117]
	v_mfma_f32_16x16x32_bf16 v[102:105], v[146:149], v[198:201], v[102:105]
	v_mfma_f32_16x16x32_bf16 v[102:105], v[150:153], v[214:217], v[102:105]
	v_mfma_f32_16x16x32_bf16 v[98:101], v[154:157], v[198:201], v[98:101]
	v_mfma_f32_16x16x32_bf16 v[98:101], v[158:161], v[214:217], v[98:101]
	v_mfma_f32_16x16x32_bf16 v[86:89], v[146:149], v[218:221], v[86:89]
	v_mfma_f32_16x16x32_bf16 v[86:89], v[150:153], v[222:225], v[86:89]
	v_mfma_f32_16x16x32_bf16 v[82:85], v[154:157], v[218:221], v[82:85]
	v_mfma_f32_16x16x32_bf16 v[82:85], v[158:161], v[222:225], v[82:85]
	v_mfma_f32_16x16x32_bf16 v[70:73], v[146:149], v[226:229], v[70:73]
	v_mfma_f32_16x16x32_bf16 v[70:73], v[150:153], v[230:233], v[70:73]
	v_mfma_f32_16x16x32_bf16 v[66:69], v[154:157], v[226:229], v[66:69]
	v_mfma_f32_16x16x32_bf16 v[66:69], v[158:161], v[230:233], v[66:69]
	s_barrier
	ds_read_b128 v[184:187], v196 offset:16384
	ds_read_b128 v[188:191], v196 offset:17408
	ds_read_b128 v[198:201], v196 offset:18432
	ds_read_b128 v[214:217], v196 offset:19456
	ds_read_b128 v[218:221], v196 offset:20480
	ds_read_b128 v[222:225], v196 offset:21504
	ds_read_b128 v[226:229], v196 offset:22528
	ds_read_b128 v[230:233], v196 offset:23552
	v_lshl_add_u64 v[202:203], s[20:21], 0, v[0:1]
	s_add_i32 s20, s22, s14
	s_mov_b32 m0, s20
	s_nop 0
	s_nop 0
	global_load_lds_dwordx4 v[202:203], off
	v_lshl_add_u64 v[234:235], v[202:203], 0, s[72:73]
	s_add_i32 m0, s20, 0x2000
	s_add_i32 s20, s23, s14
	global_load_lds_dwordx4 v[234:235], off
	v_lshl_add_u64 v[234:235], v[202:203], 0, s[28:29]
	s_mov_b32 m0, s20
	s_nop 0
	global_load_lds_dwordx4 v[234:235], off
	v_lshl_add_u64 v[234:235], v[202:203], 0, s[82:83]
	s_add_i32 m0, s20, 0x2000
	s_nop 0
	global_load_lds_dwordx4 v[234:235], off
	v_lshl_add_u64 v[234:235], s[78:79], 0, v[162:163]
	s_mov_b32 m0, s43
	v_lshl_add_u64 v[236:237], v[234:235], 0, s[72:73]
	global_load_lds_dwordx4 v[234:235], off
	s_mov_b32 m0, s46
	s_nop 0
	global_load_lds_dwordx4 v[236:237], off
	s_waitcnt vmcnt(8) lgkmcnt(0)
	s_barrier
	v_mfma_f32_16x16x32_bf16 v[62:65], v[130:133], v[184:187], v[62:65]
	v_mfma_f32_16x16x32_bf16 v[62:65], v[134:137], v[188:191], v[62:65]
	v_mfma_f32_16x16x32_bf16 v[58:61], v[138:141], v[184:187], v[58:61]
	v_mfma_f32_16x16x32_bf16 v[58:61], v[142:145], v[188:191], v[58:61]
	v_mfma_f32_16x16x32_bf16 v[46:49], v[130:133], v[198:201], v[46:49]
	v_mfma_f32_16x16x32_bf16 v[46:49], v[134:137], v[214:217], v[46:49]
	v_mfma_f32_16x16x32_bf16 v[42:45], v[138:141], v[198:201], v[42:45]
	v_mfma_f32_16x16x32_bf16 v[42:45], v[142:145], v[214:217], v[42:45]
	v_mfma_f32_16x16x32_bf16 v[30:33], v[130:133], v[218:221], v[30:33]
	v_mfma_f32_16x16x32_bf16 v[30:33], v[134:137], v[222:225], v[30:33]
	v_mfma_f32_16x16x32_bf16 v[26:29], v[138:141], v[218:221], v[26:29]
	v_mfma_f32_16x16x32_bf16 v[26:29], v[142:145], v[222:225], v[26:29]
	v_mfma_f32_16x16x32_bf16 v[14:17], v[130:133], v[226:229], v[14:17]
	v_mfma_f32_16x16x32_bf16 v[14:17], v[134:137], v[230:233], v[14:17]
	v_mfma_f32_16x16x32_bf16 v[10:13], v[138:141], v[226:229], v[10:13]
	v_mfma_f32_16x16x32_bf16 v[10:13], v[142:145], v[230:233], v[10:13]
	v_mfma_f32_16x16x32_bf16 v[54:57], v[146:149], v[184:187], v[54:57]
	v_mfma_f32_16x16x32_bf16 v[54:57], v[150:153], v[188:191], v[54:57]
	v_mfma_f32_16x16x32_bf16 v[50:53], v[154:157], v[184:187], v[50:53]
	v_mfma_f32_16x16x32_bf16 v[50:53], v[158:161], v[188:191], v[50:53]
	v_mfma_f32_16x16x32_bf16 v[38:41], v[146:149], v[198:201], v[38:41]
	v_mfma_f32_16x16x32_bf16 v[38:41], v[150:153], v[214:217], v[38:41]
	v_mfma_f32_16x16x32_bf16 v[34:37], v[154:157], v[198:201], v[34:37]
	v_mfma_f32_16x16x32_bf16 v[34:37], v[158:161], v[214:217], v[34:37]
	v_mfma_f32_16x16x32_bf16 v[22:25], v[146:149], v[218:221], v[22:25]
	v_mfma_f32_16x16x32_bf16 v[22:25], v[150:153], v[222:225], v[22:25]
	v_mfma_f32_16x16x32_bf16 v[18:21], v[154:157], v[218:221], v[18:21]
	v_mfma_f32_16x16x32_bf16 v[18:21], v[158:161], v[222:225], v[18:21]
	v_mfma_f32_16x16x32_bf16 v[6:9], v[146:149], v[226:229], v[6:9]
	v_mfma_f32_16x16x32_bf16 v[6:9], v[150:153], v[230:233], v[6:9]
	v_mfma_f32_16x16x32_bf16 v[2:5], v[154:157], v[226:229], v[2:5]
	v_mfma_f32_16x16x32_bf16 v[2:5], v[158:161], v[230:233], v[2:5]
	s_barrier
	s_add_i32 s20, 0, 0x18000
	s_add_i32 s21, 0, 0x1c000
	ds_read_b128 v[130:133], v243 offset:32768
	ds_read_b128 v[134:137], v243 offset:33792
	ds_read_b128 v[138:141], v243 offset:34816
	ds_read_b128 v[142:145], v243 offset:35840
	ds_read_b128 v[146:149], v243 offset:49152
	ds_read_b128 v[150:153], v243 offset:50176
	ds_read_b128 v[154:157], v243 offset:51200
	ds_read_b128 v[158:161], v243 offset:52224
	ds_read_b128 v[184:187], v196 offset:32768
	ds_read_b128 v[188:191], v196 offset:33792
	ds_read_b128 v[198:201], v196 offset:34816
	ds_read_b128 v[214:217], v196 offset:35840
	ds_read_b128 v[218:221], v196 offset:36864
	ds_read_b128 v[222:225], v196 offset:37888
	ds_read_b128 v[226:229], v196 offset:38912
	ds_read_b128 v[230:233], v196 offset:39936
	s_mov_b32 m0, s47
	v_lshl_add_u64 v[236:237], v[234:235], 0, s[28:29]
	global_load_lds_dwordx4 v[236:237], off
	v_lshl_add_u64 v[236:237], v[234:235], 0, s[82:83]
	s_mov_b32 m0, s88
	s_nop 0
	global_load_lds_dwordx4 v[236:237], off
	s_waitcnt vmcnt(8) lgkmcnt(0)
	s_barrier
	v_mfma_f32_16x16x32_bf16 v[126:129], v[130:133], v[184:187], v[126:129]
	v_mfma_f32_16x16x32_bf16 v[126:129], v[134:137], v[188:191], v[126:129]
	v_mfma_f32_16x16x32_bf16 v[122:125], v[138:141], v[184:187], v[122:125]
	v_mfma_f32_16x16x32_bf16 v[122:125], v[142:145], v[188:191], v[122:125]
	v_mfma_f32_16x16x32_bf16 v[110:113], v[130:133], v[198:201], v[110:113]
	v_mfma_f32_16x16x32_bf16 v[110:113], v[134:137], v[214:217], v[110:113]
	v_mfma_f32_16x16x32_bf16 v[106:109], v[138:141], v[198:201], v[106:109]
	v_mfma_f32_16x16x32_bf16 v[106:109], v[142:145], v[214:217], v[106:109]
	v_mfma_f32_16x16x32_bf16 v[94:97], v[130:133], v[218:221], v[94:97]
	v_mfma_f32_16x16x32_bf16 v[94:97], v[134:137], v[222:225], v[94:97]
	v_mfma_f32_16x16x32_bf16 v[90:93], v[138:141], v[218:221], v[90:93]
	v_mfma_f32_16x16x32_bf16 v[90:93], v[142:145], v[222:225], v[90:93]
	v_mfma_f32_16x16x32_bf16 v[78:81], v[130:133], v[226:229], v[78:81]
	v_mfma_f32_16x16x32_bf16 v[78:81], v[134:137], v[230:233], v[78:81]
	v_mfma_f32_16x16x32_bf16 v[74:77], v[138:141], v[226:229], v[74:77]
	v_mfma_f32_16x16x32_bf16 v[74:77], v[142:145], v[230:233], v[74:77]
	v_mfma_f32_16x16x32_bf16 v[118:121], v[146:149], v[184:187], v[118:121]
	v_mfma_f32_16x16x32_bf16 v[118:121], v[150:153], v[188:191], v[118:121]
	v_mfma_f32_16x16x32_bf16 v[114:117], v[154:157], v[184:187], v[114:117]
	v_mfma_f32_16x16x32_bf16 v[114:117], v[158:161], v[188:191], v[114:117]
	v_mfma_f32_16x16x32_bf16 v[102:105], v[146:149], v[198:201], v[102:105]
	v_mfma_f32_16x16x32_bf16 v[102:105], v[150:153], v[214:217], v[102:105]
	v_mfma_f32_16x16x32_bf16 v[98:101], v[154:157], v[198:201], v[98:101]
	v_mfma_f32_16x16x32_bf16 v[98:101], v[158:161], v[214:217], v[98:101]
	v_mfma_f32_16x16x32_bf16 v[86:89], v[146:149], v[218:221], v[86:89]
	v_mfma_f32_16x16x32_bf16 v[86:89], v[150:153], v[222:225], v[86:89]
	v_mfma_f32_16x16x32_bf16 v[82:85], v[154:157], v[218:221], v[82:85]
	v_mfma_f32_16x16x32_bf16 v[82:85], v[158:161], v[222:225], v[82:85]
	v_mfma_f32_16x16x32_bf16 v[70:73], v[146:149], v[226:229], v[70:73]
	v_mfma_f32_16x16x32_bf16 v[70:73], v[150:153], v[230:233], v[70:73]
	v_mfma_f32_16x16x32_bf16 v[66:69], v[154:157], v[226:229], v[66:69]
	v_mfma_f32_16x16x32_bf16 v[66:69], v[158:161], v[230:233], v[66:69]
	s_barrier
	ds_read_b128 v[184:187], v196 offset:49152
	ds_read_b128 v[188:191], v196 offset:50176
	ds_read_b128 v[198:201], v196 offset:51200
	ds_read_b128 v[214:217], v196 offset:52224
	ds_read_b128 v[218:221], v196 offset:53248
	ds_read_b128 v[222:225], v196 offset:54272
	ds_read_b128 v[226:229], v196 offset:55296
	ds_read_b128 v[230:233], v196 offset:56320
	s_add_i32 s20, s20, s14
	s_mov_b32 m0, s20
	v_lshl_add_u64 v[236:237], v[202:203], 0, s[34:35]
	global_load_lds_dwordx4 v[236:237], off
	v_lshl_add_u64 v[236:237], v[202:203], 0, s[38:39]
	s_add_i32 m0, s20, 0x2000
	s_add_i32 s20, s21, s14
	global_load_lds_dwordx4 v[236:237], off
	v_lshl_add_u64 v[236:237], v[202:203], 0, s[44:45]
	s_mov_b32 m0, s20
	v_lshl_add_u64 v[202:203], v[202:203], 0, s[10:11]
	global_load_lds_dwordx4 v[236:237], off
	s_add_i32 m0, s20, 0x2000
	s_nop 0
	global_load_lds_dwordx4 v[202:203], off
	v_lshl_add_u64 v[202:203], v[234:235], 0, s[34:35]
	s_mov_b32 m0, s89
	s_nop 0
	global_load_lds_dwordx4 v[202:203], off
	v_lshl_add_u64 v[202:203], v[234:235], 0, s[38:39]
	s_mov_b32 m0, s90
	s_nop 0
	global_load_lds_dwordx4 v[202:203], off
	s_waitcnt vmcnt(8) lgkmcnt(0)
	s_barrier
	v_mfma_f32_16x16x32_bf16 v[62:65], v[130:133], v[184:187], v[62:65]
	v_mfma_f32_16x16x32_bf16 v[62:65], v[134:137], v[188:191], v[62:65]
	v_mfma_f32_16x16x32_bf16 v[58:61], v[138:141], v[184:187], v[58:61]
	v_mfma_f32_16x16x32_bf16 v[58:61], v[142:145], v[188:191], v[58:61]
	v_mfma_f32_16x16x32_bf16 v[46:49], v[130:133], v[198:201], v[46:49]
	v_mfma_f32_16x16x32_bf16 v[46:49], v[134:137], v[214:217], v[46:49]
	v_mfma_f32_16x16x32_bf16 v[42:45], v[138:141], v[198:201], v[42:45]
	v_mfma_f32_16x16x32_bf16 v[42:45], v[142:145], v[214:217], v[42:45]
	v_mfma_f32_16x16x32_bf16 v[30:33], v[130:133], v[218:221], v[30:33]
	v_mfma_f32_16x16x32_bf16 v[30:33], v[134:137], v[222:225], v[30:33]
	v_mfma_f32_16x16x32_bf16 v[26:29], v[138:141], v[218:221], v[26:29]
	v_mfma_f32_16x16x32_bf16 v[26:29], v[142:145], v[222:225], v[26:29]
	v_mfma_f32_16x16x32_bf16 v[14:17], v[130:133], v[226:229], v[14:17]
	v_mfma_f32_16x16x32_bf16 v[14:17], v[134:137], v[230:233], v[14:17]
	v_mfma_f32_16x16x32_bf16 v[10:13], v[138:141], v[226:229], v[10:13]
	v_mfma_f32_16x16x32_bf16 v[10:13], v[142:145], v[230:233], v[10:13]
	s_add_i32 vcc_hi, vcc_hi, 2
	s_add_u32 s76, s76, 0x100
	s_addc_u32 s77, s77, 0
	s_add_u32 s87, s87, 0x100
	s_addc_u32 vcc_lo, vcc_lo, 0
	v_mfma_f32_16x16x32_bf16 v[54:57], v[146:149], v[184:187], v[54:57]
	v_mfma_f32_16x16x32_bf16 v[54:57], v[150:153], v[188:191], v[54:57]
	v_mfma_f32_16x16x32_bf16 v[50:53], v[154:157], v[184:187], v[50:53]
	v_mfma_f32_16x16x32_bf16 v[50:53], v[158:161], v[188:191], v[50:53]
	v_mfma_f32_16x16x32_bf16 v[38:41], v[146:149], v[198:201], v[38:41]
	v_mfma_f32_16x16x32_bf16 v[38:41], v[150:153], v[214:217], v[38:41]
	v_mfma_f32_16x16x32_bf16 v[34:37], v[154:157], v[198:201], v[34:37]
	v_mfma_f32_16x16x32_bf16 v[34:37], v[158:161], v[214:217], v[34:37]
	v_mfma_f32_16x16x32_bf16 v[22:25], v[146:149], v[218:221], v[22:25]
	v_mfma_f32_16x16x32_bf16 v[22:25], v[150:153], v[222:225], v[22:25]
	v_mfma_f32_16x16x32_bf16 v[18:21], v[154:157], v[218:221], v[18:21]
	v_mfma_f32_16x16x32_bf16 v[18:21], v[158:161], v[222:225], v[18:21]
	v_mfma_f32_16x16x32_bf16 v[6:9], v[146:149], v[226:229], v[6:9]
	v_mfma_f32_16x16x32_bf16 v[6:9], v[150:153], v[230:233], v[6:9]
	v_mfma_f32_16x16x32_bf16 v[2:5], v[154:157], v[226:229], v[2:5]
	v_mfma_f32_16x16x32_bf16 v[2:5], v[158:161], v[230:233], v[2:5]
	s_barrier
	s_cmp_gt_u32 vcc_hi, 13
	s_cbranch_scc0 .LBB0_778
	s_setprio 0
	s_and_b64 vcc, exec, s[50:51]
	s_cbranch_vccz .LBB0_781
	s_barrier

.LBB0_849:
	s_ashr_i32 s79, s78, 31
	s_lshl_b64 s[20:21], s[78:79], 19
	s_add_u32 s88, s4, s20
	s_addc_u32 s89, s5, s21
	s_and_b64 s[20:21], s[54:55], exec
	s_cselect_b32 s76, s89, s57
	s_cselect_b32 s77, s88, s56
	s_ashr_i32 s69, s68, 31
	s_lshl_b64 s[20:21], s[68:69], 19
	v_readlane_b32 s12, v247, 42
	s_add_u32 s94, s12, s20
	v_readlane_b32 s12, v245, 61
	s_addc_u32 s95, s12, s21
	s_and_b64 s[20:21], s[54:55], exec
	s_cselect_b32 s69, s95, s59
	s_cselect_b32 s79, s94, s58
	s_add_u32 s56, s56, 0x40080
	s_addc_u32 s57, s57, 0
	s_add_u32 s86, s58, 0x100
	v_mov_b32_e32 v2, 0
	s_addc_u32 s87, s59, 0
	s_mov_b32 s91, -2
	v_add_u32_e32 v243, 0x10000, v145
	s_add_i32 vcc_lo, 0, 0x10000
	s_add_i32 vcc_hi, 0, 0x14000
	ds_read_b128 v[138:141], v243
	ds_read_b128 v[146:149], v243 offset:1024
	ds_read_b128 v[150:153], v243 offset:2048
	ds_read_b128 v[158:161], v243 offset:3072
	ds_read_b128 v[182:185], v243 offset:16384
	ds_read_b128 v[186:189], v243 offset:17408
	ds_read_b128 v[190:193], v243 offset:18432
	ds_read_b128 v[194:197], v243 offset:19456
	ds_read_b128 v[198:201], v157
	ds_read_b128 v[214:217], v157 offset:1024
	ds_read_b128 v[218:221], v157 offset:2048
	ds_read_b128 v[222:225], v157 offset:3072
	ds_read_b128 v[226:229], v157 offset:4096
	ds_read_b128 v[230:233], v157 offset:5120
	ds_read_b128 v[234:237], v157 offset:6144
	ds_read_b128 v[238:241], v157 offset:7168
	s_cmp_eq_u64 s[62:63], 0
	s_cbranch_scc0 .Lpr_850
	s_setprio 1

.Lmid1_850:
	s_add_i32 vcc_lo, 0, 0x10000
	s_add_i32 vcc_hi, 0, 0x14000
	s_add_u32 s20, s56, 0xfffc0080
	s_addc_u32 s21, s57, -1
	s_cmp_eq_u32 s91, 12
	s_cselect_b32 s59, s76, s21
	s_cselect_b32 s58, s77, s20
	s_cselect_b32 s21, s69, s87
	s_cselect_b32 s20, s79, s86
	s_add_i32 m0, s15, 0xc000
	v_lshl_add_u64 v[142:143], s[56:57], 0, v[136:137]
	global_load_lds_dwordx4 v[142:143], off
	v_lshl_add_u64 v[142:143], v[142:143], 0, s[72:73]
	s_add_i32 m0, s15, 0xe000
	s_nop 0
	global_load_lds_dwordx4 v[142:143], off
	s_waitcnt vmcnt(8) lgkmcnt(0)
	s_barrier
	v_mfma_f32_16x16x32_bf16 v[126:129], v[138:141], v[198:201], 0
	v_mfma_f32_16x16x32_bf16 v[126:129], v[146:149], v[214:217], v[126:129]
	v_mfma_f32_16x16x32_bf16 v[122:125], v[150:153], v[198:201], 0
	v_mfma_f32_16x16x32_bf16 v[122:125], v[158:161], v[214:217], v[122:125]
	v_mfma_f32_16x16x32_bf16 v[110:113], v[138:141], v[218:221], 0
	v_mfma_f32_16x16x32_bf16 v[110:113], v[146:149], v[222:225], v[110:113]
	v_mfma_f32_16x16x32_bf16 v[106:109], v[150:153], v[218:221], 0
	v_mfma_f32_16x16x32_bf16 v[106:109], v[158:161], v[222:225], v[106:109]
	v_mfma_f32_16x16x32_bf16 v[94:97], v[138:141], v[226:229], 0
	v_mfma_f32_16x16x32_bf16 v[94:97], v[146:149], v[230:233], v[94:97]
	v_mfma_f32_16x16x32_bf16 v[90:93], v[150:153], v[226:229], 0
	v_mfma_f32_16x16x32_bf16 v[90:93], v[158:161], v[230:233], v[90:93]
	v_mfma_f32_16x16x32_bf16 v[78:81], v[138:141], v[234:237], 0
	v_mfma_f32_16x16x32_bf16 v[78:81], v[146:149], v[238:241], v[78:81]
	v_mfma_f32_16x16x32_bf16 v[74:77], v[150:153], v[234:237], 0
	v_mfma_f32_16x16x32_bf16 v[74:77], v[158:161], v[238:241], v[74:77]
	v_mfma_f32_16x16x32_bf16 v[118:121], v[182:185], v[198:201], 0
	v_mfma_f32_16x16x32_bf16 v[118:121], v[186:189], v[214:217], v[118:121]
	v_mfma_f32_16x16x32_bf16 v[114:117], v[190:193], v[198:201], 0
	v_mfma_f32_16x16x32_bf16 v[114:117], v[194:197], v[214:217], v[114:117]
	v_mfma_f32_16x16x32_bf16 v[102:105], v[182:185], v[218:221], 0
	v_mfma_f32_16x16x32_bf16 v[102:105], v[186:189], v[222:225], v[102:105]
	v_mfma_f32_16x16x32_bf16 v[98:101], v[190:193], v[218:221], 0
	v_mfma_f32_16x16x32_bf16 v[98:101], v[194:197], v[222:225], v[98:101]
	v_mfma_f32_16x16x32_bf16 v[86:89], v[182:185], v[226:229], 0
	v_mfma_f32_16x16x32_bf16 v[86:89], v[186:189], v[230:233], v[86:89]
	v_mfma_f32_16x16x32_bf16 v[82:85], v[190:193], v[226:229], 0
	v_mfma_f32_16x16x32_bf16 v[82:85], v[194:197], v[230:233], v[82:85]
	v_mfma_f32_16x16x32_bf16 v[70:73], v[182:185], v[234:237], 0
	v_mfma_f32_16x16x32_bf16 v[70:73], v[186:189], v[238:241], v[70:73]
	v_mfma_f32_16x16x32_bf16 v[66:69], v[190:193], v[234:237], 0
	v_mfma_f32_16x16x32_bf16 v[66:69], v[194:197], v[238:241], v[66:69]
	s_barrier
	ds_read_b128 v[198:201], v157 offset:16384
	ds_read_b128 v[214:217], v157 offset:17408
	ds_read_b128 v[218:221], v157 offset:18432
	ds_read_b128 v[222:225], v157 offset:19456
	ds_read_b128 v[226:229], v157 offset:20480
	ds_read_b128 v[230:233], v157 offset:21504
	ds_read_b128 v[234:237], v157 offset:22528
	ds_read_b128 v[238:241], v157 offset:23552
	v_lshl_add_u64 v[142:143], s[20:21], 0, v[130:131]
	s_add_i32 s20, vcc_lo, s14
	s_mov_b32 m0, s20
	s_nop 0
	s_nop 0
	global_load_lds_dwordx4 v[142:143], off
	v_lshl_add_u64 v[162:163], v[142:143], 0, s[72:73]
	s_add_i32 m0, s20, 0x2000
	s_add_i32 s20, vcc_hi, s14
	global_load_lds_dwordx4 v[162:163], off
	v_lshl_add_u64 v[162:163], v[142:143], 0, s[28:29]
	s_mov_b32 m0, s20
	s_nop 0
	global_load_lds_dwordx4 v[162:163], off
	v_lshl_add_u64 v[162:163], v[142:143], 0, s[82:83]
	s_add_i32 m0, s20, 0x2000
	s_nop 0
	global_load_lds_dwordx4 v[162:163], off
	v_lshl_add_u64 v[162:163], s[58:59], 0, v[132:133]
	s_mov_b32 m0, s15
	v_lshl_add_u64 v[202:203], v[162:163], 0, s[72:73]
	global_load_lds_dwordx4 v[162:163], off
	s_mov_b32 m0, s42
	s_nop 0
	global_load_lds_dwordx4 v[202:203], off
	s_waitcnt vmcnt(8) lgkmcnt(0)
	s_barrier
	v_mfma_f32_16x16x32_bf16 v[62:65], v[138:141], v[198:201], 0
	v_mfma_f32_16x16x32_bf16 v[62:65], v[146:149], v[214:217], v[62:65]
	v_mfma_f32_16x16x32_bf16 v[58:61], v[150:153], v[198:201], 0
	v_mfma_f32_16x16x32_bf16 v[58:61], v[158:161], v[214:217], v[58:61]
	v_mfma_f32_16x16x32_bf16 v[46:49], v[138:141], v[218:221], 0
	v_mfma_f32_16x16x32_bf16 v[46:49], v[146:149], v[222:225], v[46:49]
	v_mfma_f32_16x16x32_bf16 v[42:45], v[150:153], v[218:221], 0
	v_mfma_f32_16x16x32_bf16 v[42:45], v[158:161], v[222:225], v[42:45]
	v_mfma_f32_16x16x32_bf16 v[30:33], v[138:141], v[226:229], 0
	v_mfma_f32_16x16x32_bf16 v[30:33], v[146:149], v[230:233], v[30:33]
	v_mfma_f32_16x16x32_bf16 v[26:29], v[150:153], v[226:229], 0
	v_mfma_f32_16x16x32_bf16 v[26:29], v[158:161], v[230:233], v[26:29]
	v_mfma_f32_16x16x32_bf16 v[14:17], v[138:141], v[234:237], 0
	v_mfma_f32_16x16x32_bf16 v[14:17], v[146:149], v[238:241], v[14:17]
	v_mfma_f32_16x16x32_bf16 v[10:13], v[150:153], v[234:237], 0
	v_mfma_f32_16x16x32_bf16 v[10:13], v[158:161], v[238:241], v[10:13]
	v_mfma_f32_16x16x32_bf16 v[54:57], v[182:185], v[198:201], 0
	v_mfma_f32_16x16x32_bf16 v[54:57], v[186:189], v[214:217], v[54:57]
	v_mfma_f32_16x16x32_bf16 v[50:53], v[190:193], v[198:201], 0
	v_mfma_f32_16x16x32_bf16 v[50:53], v[194:197], v[214:217], v[50:53]
	v_mfma_f32_16x16x32_bf16 v[38:41], v[182:185], v[218:221], 0
	v_mfma_f32_16x16x32_bf16 v[38:41], v[186:189], v[222:225], v[38:41]
	v_mfma_f32_16x16x32_bf16 v[34:37], v[190:193], v[218:221], 0
	v_mfma_f32_16x16x32_bf16 v[34:37], v[194:197], v[222:225], v[34:37]
	v_mfma_f32_16x16x32_bf16 v[22:25], v[182:185], v[226:229], 0
	v_mfma_f32_16x16x32_bf16 v[22:25], v[186:189], v[230:233], v[22:25]
	v_mfma_f32_16x16x32_bf16 v[18:21], v[190:193], v[226:229], 0
	v_mfma_f32_16x16x32_bf16 v[18:21], v[194:197], v[230:233], v[18:21]
	v_mfma_f32_16x16x32_bf16 v[6:9], v[182:185], v[234:237], 0
	v_mfma_f32_16x16x32_bf16 v[6:9], v[186:189], v[238:241], v[6:9]
	v_mfma_f32_16x16x32_bf16 v[2:5], v[190:193], v[234:237], 0
	v_mfma_f32_16x16x32_bf16 v[2:5], v[194:197], v[238:241], v[2:5]
	s_barrier
	s_add_i32 s20, 0, 0x18000
	s_add_i32 s21, 0, 0x1c000
	ds_read_b128 v[138:141], v243 offset:32768
	ds_read_b128 v[146:149], v243 offset:33792
	ds_read_b128 v[150:153], v243 offset:34816
	ds_read_b128 v[158:161], v243 offset:35840
	ds_read_b128 v[182:185], v243 offset:49152
	ds_read_b128 v[186:189], v243 offset:50176
	ds_read_b128 v[190:193], v243 offset:51200
	ds_read_b128 v[194:197], v243 offset:52224
	ds_read_b128 v[198:201], v157 offset:32768
	ds_read_b128 v[214:217], v157 offset:33792
	ds_read_b128 v[218:221], v157 offset:34816
	ds_read_b128 v[222:225], v157 offset:35840
	ds_read_b128 v[226:229], v157 offset:36864
	ds_read_b128 v[230:233], v157 offset:37888
	ds_read_b128 v[234:237], v157 offset:38912
	ds_read_b128 v[238:241], v157 offset:39936
	s_mov_b32 m0, s43
	v_lshl_add_u64 v[202:203], v[162:163], 0, s[28:29]
	global_load_lds_dwordx4 v[202:203], off
	v_lshl_add_u64 v[202:203], v[162:163], 0, s[82:83]
	s_mov_b32 m0, s46
	s_nop 0
	global_load_lds_dwordx4 v[202:203], off
	s_waitcnt vmcnt(8) lgkmcnt(0)
	s_barrier
	v_mfma_f32_16x16x32_bf16 v[126:129], v[138:141], v[198:201], v[126:129]
	v_mfma_f32_16x16x32_bf16 v[126:129], v[146:149], v[214:217], v[126:129]
	v_mfma_f32_16x16x32_bf16 v[122:125], v[150:153], v[198:201], v[122:125]
	v_mfma_f32_16x16x32_bf16 v[122:125], v[158:161], v[214:217], v[122:125]
	v_mfma_f32_16x16x32_bf16 v[110:113], v[138:141], v[218:221], v[110:113]
	v_mfma_f32_16x16x32_bf16 v[110:113], v[146:149], v[222:225], v[110:113]
	v_mfma_f32_16x16x32_bf16 v[106:109], v[150:153], v[218:221], v[106:109]
	v_mfma_f32_16x16x32_bf16 v[106:109], v[158:161], v[222:225], v[106:109]
	v_mfma_f32_16x16x32_bf16 v[94:97], v[138:141], v[226:229], v[94:97]
	v_mfma_f32_16x16x32_bf16 v[94:97], v[146:149], v[230:233], v[94:97]
	v_mfma_f32_16x16x32_bf16 v[90:93], v[150:153], v[226:229], v[90:93]
	v_mfma_f32_16x16x32_bf16 v[90:93], v[158:161], v[230:233], v[90:93]
	v_mfma_f32_16x16x32_bf16 v[78:81], v[138:141], v[234:237], v[78:81]
	v_mfma_f32_16x16x32_bf16 v[78:81], v[146:149], v[238:241], v[78:81]
	v_mfma_f32_16x16x32_bf16 v[74:77], v[150:153], v[234:237], v[74:77]
	v_mfma_f32_16x16x32_bf16 v[74:77], v[158:161], v[238:241], v[74:77]
	v_mfma_f32_16x16x32_bf16 v[118:121], v[182:185], v[198:201], v[118:121]
	v_mfma_f32_16x16x32_bf16 v[118:121], v[186:189], v[214:217], v[118:121]
	v_mfma_f32_16x16x32_bf16 v[114:117], v[190:193], v[198:201], v[114:117]
	v_mfma_f32_16x16x32_bf16 v[114:117], v[194:197], v[214:217], v[114:117]
	v_mfma_f32_16x16x32_bf16 v[102:105], v[182:185], v[218:221], v[102:105]
	v_mfma_f32_16x16x32_bf16 v[102:105], v[186:189], v[222:225], v[102:105]
	v_mfma_f32_16x16x32_bf16 v[98:101], v[190:193], v[218:221], v[98:101]
	v_mfma_f32_16x16x32_bf16 v[98:101], v[194:197], v[222:225], v[98:101]
	v_mfma_f32_16x16x32_bf16 v[86:89], v[182:185], v[226:229], v[86:89]
	v_mfma_f32_16x16x32_bf16 v[86:89], v[186:189], v[230:233], v[86:89]
	v_mfma_f32_16x16x32_bf16 v[82:85], v[190:193], v[226:229], v[82:85]
	v_mfma_f32_16x16x32_bf16 v[82:85], v[194:197], v[230:233], v[82:85]
	v_mfma_f32_16x16x32_bf16 v[70:73], v[182:185], v[234:237], v[70:73]
	v_mfma_f32_16x16x32_bf16 v[70:73], v[186:189], v[238:241], v[70:73]
	v_mfma_f32_16x16x32_bf16 v[66:69], v[190:193], v[234:237], v[66:69]
	v_mfma_f32_16x16x32_bf16 v[66:69], v[194:197], v[238:241], v[66:69]
	s_barrier
	ds_read_b128 v[198:201], v157 offset:49152
	ds_read_b128 v[214:217], v157 offset:50176
	ds_read_b128 v[218:221], v157 offset:51200
	ds_read_b128 v[222:225], v157 offset:52224
	ds_read_b128 v[226:229], v157 offset:53248
	ds_read_b128 v[230:233], v157 offset:54272
	ds_read_b128 v[234:237], v157 offset:55296
	ds_read_b128 v[238:241], v157 offset:56320
	s_add_i32 s20, s20, s14
	s_mov_b32 m0, s20
	v_lshl_add_u64 v[202:203], v[142:143], 0, s[34:35]
	global_load_lds_dwordx4 v[202:203], off
	v_lshl_add_u64 v[202:203], v[142:143], 0, s[38:39]
	s_add_i32 m0, s20, 0x2000
	s_add_i32 s20, s21, s14
	global_load_lds_dwordx4 v[202:203], off
	v_lshl_add_u64 v[202:203], v[142:143], 0, s[44:45]
	s_mov_b32 m0, s20
	v_lshl_add_u64 v[142:143], v[142:143], 0, s[10:11]
	global_load_lds_dwordx4 v[202:203], off
	s_add_i32 m0, s20, 0x2000
	s_nop 0
	global_load_lds_dwordx4 v[142:143], off
	v_lshl_add_u64 v[142:143], v[162:163], 0, s[34:35]
	s_mov_b32 m0, s47
	s_nop 0
	global_load_lds_dwordx4 v[142:143], off
	v_lshl_add_u64 v[142:143], v[162:163], 0, s[38:39]
	s_mov_b32 m0, s96
	s_nop 0
	global_load_lds_dwordx4 v[142:143], off
	s_waitcnt vmcnt(8) lgkmcnt(0)
	s_barrier
	v_mfma_f32_16x16x32_bf16 v[62:65], v[138:141], v[198:201], v[62:65]
	v_mfma_f32_16x16x32_bf16 v[62:65], v[146:149], v[214:217], v[62:65]
	v_mfma_f32_16x16x32_bf16 v[58:61], v[150:153], v[198:201], v[58:61]
	v_mfma_f32_16x16x32_bf16 v[58:61], v[158:161], v[214:217], v[58:61]
	v_mfma_f32_16x16x32_bf16 v[46:49], v[138:141], v[218:221], v[46:49]
	v_mfma_f32_16x16x32_bf16 v[46:49], v[146:149], v[222:225], v[46:49]
	v_mfma_f32_16x16x32_bf16 v[42:45], v[150:153], v[218:221], v[42:45]
	v_mfma_f32_16x16x32_bf16 v[42:45], v[158:161], v[222:225], v[42:45]
	v_mfma_f32_16x16x32_bf16 v[30:33], v[138:141], v[226:229], v[30:33]
	v_mfma_f32_16x16x32_bf16 v[30:33], v[146:149], v[230:233], v[30:33]
	v_mfma_f32_16x16x32_bf16 v[26:29], v[150:153], v[226:229], v[26:29]
	v_mfma_f32_16x16x32_bf16 v[26:29], v[158:161], v[230:233], v[26:29]
	v_mfma_f32_16x16x32_bf16 v[14:17], v[138:141], v[234:237], v[14:17]
	v_mfma_f32_16x16x32_bf16 v[14:17], v[146:149], v[238:241], v[14:17]
	v_mfma_f32_16x16x32_bf16 v[10:13], v[150:153], v[234:237], v[10:13]
	v_mfma_f32_16x16x32_bf16 v[10:13], v[158:161], v[238:241], v[10:13]
	s_add_i32 s91, s91, 2
	s_add_u32 s56, s56, 0x100
	s_addc_u32 s57, s57, 0
	s_add_u32 s86, s86, 0x100
	s_addc_u32 s87, s87, 0
	v_mfma_f32_16x16x32_bf16 v[54:57], v[182:185], v[198:201], v[54:57]
	v_mfma_f32_16x16x32_bf16 v[54:57], v[186:189], v[214:217], v[54:57]
	v_mfma_f32_16x16x32_bf16 v[50:53], v[190:193], v[198:201], v[50:53]
	v_mfma_f32_16x16x32_bf16 v[50:53], v[194:197], v[214:217], v[50:53]
	v_mfma_f32_16x16x32_bf16 v[38:41], v[182:185], v[218:221], v[38:41]
	v_mfma_f32_16x16x32_bf16 v[38:41], v[186:189], v[222:225], v[38:41]
	v_mfma_f32_16x16x32_bf16 v[34:37], v[190:193], v[218:221], v[34:37]
	v_mfma_f32_16x16x32_bf16 v[34:37], v[194:197], v[222:225], v[34:37]
	v_mfma_f32_16x16x32_bf16 v[22:25], v[182:185], v[226:229], v[22:25]
	v_mfma_f32_16x16x32_bf16 v[22:25], v[186:189], v[230:233], v[22:25]
	v_mfma_f32_16x16x32_bf16 v[18:21], v[190:193], v[226:229], v[18:21]
	v_mfma_f32_16x16x32_bf16 v[18:21], v[194:197], v[230:233], v[18:21]
	v_mfma_f32_16x16x32_bf16 v[6:9], v[182:185], v[234:237], v[6:9]
	v_mfma_f32_16x16x32_bf16 v[6:9], v[186:189], v[238:241], v[6:9]
	v_mfma_f32_16x16x32_bf16 v[2:5], v[190:193], v[234:237], v[2:5]
	v_mfma_f32_16x16x32_bf16 v[2:5], v[194:197], v[238:241], v[2:5]
	s_barrier
	s_branch .LBB0_850
	.p2alignl 6, 3212836864
.LBB0_850:
	s_add_i32 vcc_lo, 0, 0x10000
	s_add_i32 vcc_hi, 0, 0x14000
	ds_read_b128 v[138:141], v243
	ds_read_b128 v[146:149], v243 offset:1024
	ds_read_b128 v[150:153], v243 offset:2048
	ds_read_b128 v[158:161], v243 offset:3072
	ds_read_b128 v[182:185], v243 offset:16384
	ds_read_b128 v[186:189], v243 offset:17408
	ds_read_b128 v[190:193], v243 offset:18432
	ds_read_b128 v[194:197], v243 offset:19456
	ds_read_b128 v[198:201], v157
	ds_read_b128 v[214:217], v157 offset:1024
	ds_read_b128 v[218:221], v157 offset:2048
	ds_read_b128 v[222:225], v157 offset:3072
	ds_read_b128 v[226:229], v157 offset:4096
	ds_read_b128 v[230:233], v157 offset:5120
	ds_read_b128 v[234:237], v157 offset:6144
	ds_read_b128 v[238:241], v157 offset:7168
	s_add_u32 s20, s56, 0xfffc0080
	s_addc_u32 s21, s57, -1
	s_cmp_eq_u32 s91, 12
	s_cselect_b32 s59, s76, s21
	s_cselect_b32 s58, s77, s20
	s_cselect_b32 s21, s69, s87
	s_cselect_b32 s20, s79, s86
	s_add_i32 m0, s15, 0xc000
	v_lshl_add_u64 v[142:143], s[56:57], 0, v[136:137]
	global_load_lds_dwordx4 v[142:143], off
	v_lshl_add_u64 v[142:143], v[142:143], 0, s[72:73]
	s_add_i32 m0, s15, 0xe000
	s_nop 0
	global_load_lds_dwordx4 v[142:143], off
	s_waitcnt vmcnt(8) lgkmcnt(0)
	s_barrier
	v_mfma_f32_16x16x32_bf16 v[126:129], v[138:141], v[198:201], v[126:129]
	v_mfma_f32_16x16x32_bf16 v[126:129], v[146:149], v[214:217], v[126:129]
	v_mfma_f32_16x16x32_bf16 v[122:125], v[150:153], v[198:201], v[122:125]
	v_mfma_f32_16x16x32_bf16 v[122:125], v[158:161], v[214:217], v[122:125]
	v_mfma_f32_16x16x32_bf16 v[110:113], v[138:141], v[218:221], v[110:113]
	v_mfma_f32_16x16x32_bf16 v[110:113], v[146:149], v[222:225], v[110:113]
	v_mfma_f32_16x16x32_bf16 v[106:109], v[150:153], v[218:221], v[106:109]
	v_mfma_f32_16x16x32_bf16 v[106:109], v[158:161], v[222:225], v[106:109]
	v_mfma_f32_16x16x32_bf16 v[94:97], v[138:141], v[226:229], v[94:97]
	v_mfma_f32_16x16x32_bf16 v[94:97], v[146:149], v[230:233], v[94:97]
	v_mfma_f32_16x16x32_bf16 v[90:93], v[150:153], v[226:229], v[90:93]
	v_mfma_f32_16x16x32_bf16 v[90:93], v[158:161], v[230:233], v[90:93]
	v_mfma_f32_16x16x32_bf16 v[78:81], v[138:141], v[234:237], v[78:81]
	v_mfma_f32_16x16x32_bf16 v[78:81], v[146:149], v[238:241], v[78:81]
	v_mfma_f32_16x16x32_bf16 v[74:77], v[150:153], v[234:237], v[74:77]
	v_mfma_f32_16x16x32_bf16 v[74:77], v[158:161], v[238:241], v[74:77]
	v_mfma_f32_16x16x32_bf16 v[118:121], v[182:185], v[198:201], v[118:121]
	v_mfma_f32_16x16x32_bf16 v[118:121], v[186:189], v[214:217], v[118:121]
	v_mfma_f32_16x16x32_bf16 v[114:117], v[190:193], v[198:201], v[114:117]
	v_mfma_f32_16x16x32_bf16 v[114:117], v[194:197], v[214:217], v[114:117]
	v_mfma_f32_16x16x32_bf16 v[102:105], v[182:185], v[218:221], v[102:105]
	v_mfma_f32_16x16x32_bf16 v[102:105], v[186:189], v[222:225], v[102:105]
	v_mfma_f32_16x16x32_bf16 v[98:101], v[190:193], v[218:221], v[98:101]
	v_mfma_f32_16x16x32_bf16 v[98:101], v[194:197], v[222:225], v[98:101]
	v_mfma_f32_16x16x32_bf16 v[86:89], v[182:185], v[226:229], v[86:89]
	v_mfma_f32_16x16x32_bf16 v[86:89], v[186:189], v[230:233], v[86:89]
	v_mfma_f32_16x16x32_bf16 v[82:85], v[190:193], v[226:229], v[82:85]
	v_mfma_f32_16x16x32_bf16 v[82:85], v[194:197], v[230:233], v[82:85]
	v_mfma_f32_16x16x32_bf16 v[70:73], v[182:185], v[234:237], v[70:73]
	v_mfma_f32_16x16x32_bf16 v[70:73], v[186:189], v[238:241], v[70:73]
	v_mfma_f32_16x16x32_bf16 v[66:69], v[190:193], v[234:237], v[66:69]
	v_mfma_f32_16x16x32_bf16 v[66:69], v[194:197], v[238:241], v[66:69]
	s_barrier
	ds_read_b128 v[198:201], v157 offset:16384
	ds_read_b128 v[214:217], v157 offset:17408
	ds_read_b128 v[218:221], v157 offset:18432
	ds_read_b128 v[222:225], v157 offset:19456
	ds_read_b128 v[226:229], v157 offset:20480
	ds_read_b128 v[230:233], v157 offset:21504
	ds_read_b128 v[234:237], v157 offset:22528
	ds_read_b128 v[238:241], v157 offset:23552
	v_lshl_add_u64 v[142:143], s[20:21], 0, v[130:131]
	s_add_i32 s20, vcc_lo, s14
	s_mov_b32 m0, s20
	s_nop 0
	s_nop 0
	global_load_lds_dwordx4 v[142:143], off
	v_lshl_add_u64 v[162:163], v[142:143], 0, s[72:73]
	s_add_i32 m0, s20, 0x2000
	s_add_i32 s20, vcc_hi, s14
	global_load_lds_dwordx4 v[162:163], off
	v_lshl_add_u64 v[162:163], v[142:143], 0, s[28:29]
	s_mov_b32 m0, s20
	s_nop 0
	global_load_lds_dwordx4 v[162:163], off
	v_lshl_add_u64 v[162:163], v[142:143], 0, s[82:83]
	s_add_i32 m0, s20, 0x2000
	s_nop 0
	global_load_lds_dwordx4 v[162:163], off
	v_lshl_add_u64 v[162:163], s[58:59], 0, v[132:133]
	s_mov_b32 m0, s15
	v_lshl_add_u64 v[202:203], v[162:163], 0, s[72:73]
	global_load_lds_dwordx4 v[162:163], off
	s_mov_b32 m0, s42
	s_nop 0
	global_load_lds_dwordx4 v[202:203], off
	s_waitcnt vmcnt(8) lgkmcnt(0)
	s_barrier
	v_mfma_f32_16x16x32_bf16 v[62:65], v[138:141], v[198:201], v[62:65]
	v_mfma_f32_16x16x32_bf16 v[62:65], v[146:149], v[214:217], v[62:65]
	v_mfma_f32_16x16x32_bf16 v[58:61], v[150:153], v[198:201], v[58:61]
	v_mfma_f32_16x16x32_bf16 v[58:61], v[158:161], v[214:217], v[58:61]
	v_mfma_f32_16x16x32_bf16 v[46:49], v[138:141], v[218:221], v[46:49]
	v_mfma_f32_16x16x32_bf16 v[46:49], v[146:149], v[222:225], v[46:49]
	v_mfma_f32_16x16x32_bf16 v[42:45], v[150:153], v[218:221], v[42:45]
	v_mfma_f32_16x16x32_bf16 v[42:45], v[158:161], v[222:225], v[42:45]
	v_mfma_f32_16x16x32_bf16 v[30:33], v[138:141], v[226:229], v[30:33]
	v_mfma_f32_16x16x32_bf16 v[30:33], v[146:149], v[230:233], v[30:33]
	v_mfma_f32_16x16x32_bf16 v[26:29], v[150:153], v[226:229], v[26:29]
	v_mfma_f32_16x16x32_bf16 v[26:29], v[158:161], v[230:233], v[26:29]
	v_mfma_f32_16x16x32_bf16 v[14:17], v[138:141], v[234:237], v[14:17]
	v_mfma_f32_16x16x32_bf16 v[14:17], v[146:149], v[238:241], v[14:17]
	v_mfma_f32_16x16x32_bf16 v[10:13], v[150:153], v[234:237], v[10:13]
	v_mfma_f32_16x16x32_bf16 v[10:13], v[158:161], v[238:241], v[10:13]
	v_mfma_f32_16x16x32_bf16 v[54:57], v[182:185], v[198:201], v[54:57]
	v_mfma_f32_16x16x32_bf16 v[54:57], v[186:189], v[214:217], v[54:57]
	v_mfma_f32_16x16x32_bf16 v[50:53], v[190:193], v[198:201], v[50:53]
	v_mfma_f32_16x16x32_bf16 v[50:53], v[194:197], v[214:217], v[50:53]
	v_mfma_f32_16x16x32_bf16 v[38:41], v[182:185], v[218:221], v[38:41]
	v_mfma_f32_16x16x32_bf16 v[38:41], v[186:189], v[222:225], v[38:41]
	v_mfma_f32_16x16x32_bf16 v[34:37], v[190:193], v[218:221], v[34:37]
	v_mfma_f32_16x16x32_bf16 v[34:37], v[194:197], v[222:225], v[34:37]
	v_mfma_f32_16x16x32_bf16 v[22:25], v[182:185], v[226:229], v[22:25]
	v_mfma_f32_16x16x32_bf16 v[22:25], v[186:189], v[230:233], v[22:25]
	v_mfma_f32_16x16x32_bf16 v[18:21], v[190:193], v[226:229], v[18:21]
	v_mfma_f32_16x16x32_bf16 v[18:21], v[194:197], v[230:233], v[18:21]
	v_mfma_f32_16x16x32_bf16 v[6:9], v[182:185], v[234:237], v[6:9]
	v_mfma_f32_16x16x32_bf16 v[6:9], v[186:189], v[238:241], v[6:9]
	v_mfma_f32_16x16x32_bf16 v[2:5], v[190:193], v[234:237], v[2:5]
	v_mfma_f32_16x16x32_bf16 v[2:5], v[194:197], v[238:241], v[2:5]
	s_barrier
	s_add_i32 s20, 0, 0x18000
	s_add_i32 s21, 0, 0x1c000
	ds_read_b128 v[138:141], v243 offset:32768
	ds_read_b128 v[146:149], v243 offset:33792
	ds_read_b128 v[150:153], v243 offset:34816
	ds_read_b128 v[158:161], v243 offset:35840
	ds_read_b128 v[182:185], v243 offset:49152
	ds_read_b128 v[186:189], v243 offset:50176
	ds_read_b128 v[190:193], v243 offset:51200
	ds_read_b128 v[194:197], v243 offset:52224
	ds_read_b128 v[198:201], v157 offset:32768
	ds_read_b128 v[214:217], v157 offset:33792
	ds_read_b128 v[218:221], v157 offset:34816
	ds_read_b128 v[222:225], v157 offset:35840
	ds_read_b128 v[226:229], v157 offset:36864
	ds_read_b128 v[230:233], v157 offset:37888
	ds_read_b128 v[234:237], v157 offset:38912
	ds_read_b128 v[238:241], v157 offset:39936
	s_mov_b32 m0, s43
	v_lshl_add_u64 v[202:203], v[162:163], 0, s[28:29]
	global_load_lds_dwordx4 v[202:203], off
	v_lshl_add_u64 v[202:203], v[162:163], 0, s[82:83]
	s_mov_b32 m0, s46
	s_nop 0
	global_load_lds_dwordx4 v[202:203], off
	s_waitcnt vmcnt(8) lgkmcnt(0)
	s_barrier
	v_mfma_f32_16x16x32_bf16 v[126:129], v[138:141], v[198:201], v[126:129]
	v_mfma_f32_16x16x32_bf16 v[126:129], v[146:149], v[214:217], v[126:129]
	v_mfma_f32_16x16x32_bf16 v[122:125], v[150:153], v[198:201], v[122:125]
	v_mfma_f32_16x16x32_bf16 v[122:125], v[158:161], v[214:217], v[122:125]
	v_mfma_f32_16x16x32_bf16 v[110:113], v[138:141], v[218:221], v[110:113]
	v_mfma_f32_16x16x32_bf16 v[110:113], v[146:149], v[222:225], v[110:113]
	v_mfma_f32_16x16x32_bf16 v[106:109], v[150:153], v[218:221], v[106:109]
	v_mfma_f32_16x16x32_bf16 v[106:109], v[158:161], v[222:225], v[106:109]
	v_mfma_f32_16x16x32_bf16 v[94:97], v[138:141], v[226:229], v[94:97]
	v_mfma_f32_16x16x32_bf16 v[94:97], v[146:149], v[230:233], v[94:97]
	v_mfma_f32_16x16x32_bf16 v[90:93], v[150:153], v[226:229], v[90:93]
	v_mfma_f32_16x16x32_bf16 v[90:93], v[158:161], v[230:233], v[90:93]
	v_mfma_f32_16x16x32_bf16 v[78:81], v[138:141], v[234:237], v[78:81]
	v_mfma_f32_16x16x32_bf16 v[78:81], v[146:149], v[238:241], v[78:81]
	v_mfma_f32_16x16x32_bf16 v[74:77], v[150:153], v[234:237], v[74:77]
	v_mfma_f32_16x16x32_bf16 v[74:77], v[158:161], v[238:241], v[74:77]
	v_mfma_f32_16x16x32_bf16 v[118:121], v[182:185], v[198:201], v[118:121]
	v_mfma_f32_16x16x32_bf16 v[118:121], v[186:189], v[214:217], v[118:121]
	v_mfma_f32_16x16x32_bf16 v[114:117], v[190:193], v[198:201], v[114:117]
	v_mfma_f32_16x16x32_bf16 v[114:117], v[194:197], v[214:217], v[114:117]
	v_mfma_f32_16x16x32_bf16 v[102:105], v[182:185], v[218:221], v[102:105]
	v_mfma_f32_16x16x32_bf16 v[102:105], v[186:189], v[222:225], v[102:105]
	v_mfma_f32_16x16x32_bf16 v[98:101], v[190:193], v[218:221], v[98:101]
	v_mfma_f32_16x16x32_bf16 v[98:101], v[194:197], v[222:225], v[98:101]
	v_mfma_f32_16x16x32_bf16 v[86:89], v[182:185], v[226:229], v[86:89]
	v_mfma_f32_16x16x32_bf16 v[86:89], v[186:189], v[230:233], v[86:89]
	v_mfma_f32_16x16x32_bf16 v[82:85], v[190:193], v[226:229], v[82:85]
	v_mfma_f32_16x16x32_bf16 v[82:85], v[194:197], v[230:233], v[82:85]
	v_mfma_f32_16x16x32_bf16 v[70:73], v[182:185], v[234:237], v[70:73]
	v_mfma_f32_16x16x32_bf16 v[70:73], v[186:189], v[238:241], v[70:73]
	v_mfma_f32_16x16x32_bf16 v[66:69], v[190:193], v[234:237], v[66:69]
	v_mfma_f32_16x16x32_bf16 v[66:69], v[194:197], v[238:241], v[66:69]
	s_barrier
	ds_read_b128 v[198:201], v157 offset:49152
	ds_read_b128 v[214:217], v157 offset:50176
	ds_read_b128 v[218:221], v157 offset:51200
	ds_read_b128 v[222:225], v157 offset:52224
	ds_read_b128 v[226:229], v157 offset:53248
	ds_read_b128 v[230:233], v157 offset:54272
	ds_read_b128 v[234:237], v157 offset:55296
	ds_read_b128 v[238:241], v157 offset:56320
	s_add_i32 s20, s20, s14
	s_mov_b32 m0, s20
	v_lshl_add_u64 v[202:203], v[142:143], 0, s[34:35]
	global_load_lds_dwordx4 v[202:203], off
	v_lshl_add_u64 v[202:203], v[142:143], 0, s[38:39]
	s_add_i32 m0, s20, 0x2000
	s_add_i32 s20, s21, s14
	global_load_lds_dwordx4 v[202:203], off
	v_lshl_add_u64 v[202:203], v[142:143], 0, s[44:45]
	s_mov_b32 m0, s20
	v_lshl_add_u64 v[142:143], v[142:143], 0, s[10:11]
	global_load_lds_dwordx4 v[202:203], off
	s_add_i32 m0, s20, 0x2000
	s_nop 0
	global_load_lds_dwordx4 v[142:143], off
	v_lshl_add_u64 v[142:143], v[162:163], 0, s[34:35]
	s_mov_b32 m0, s47
	s_nop 0
	global_load_lds_dwordx4 v[142:143], off
	v_lshl_add_u64 v[142:143], v[162:163], 0, s[38:39]
	s_mov_b32 m0, s96
	s_nop 0
	global_load_lds_dwordx4 v[142:143], off
	s_waitcnt vmcnt(8) lgkmcnt(0)
	s_barrier
	v_mfma_f32_16x16x32_bf16 v[62:65], v[138:141], v[198:201], v[62:65]
	v_mfma_f32_16x16x32_bf16 v[62:65], v[146:149], v[214:217], v[62:65]
	v_mfma_f32_16x16x32_bf16 v[58:61], v[150:153], v[198:201], v[58:61]
	v_mfma_f32_16x16x32_bf16 v[58:61], v[158:161], v[214:217], v[58:61]
	v_mfma_f32_16x16x32_bf16 v[46:49], v[138:141], v[218:221], v[46:49]
	v_mfma_f32_16x16x32_bf16 v[46:49], v[146:149], v[222:225], v[46:49]
	v_mfma_f32_16x16x32_bf16 v[42:45], v[150:153], v[218:221], v[42:45]
	v_mfma_f32_16x16x32_bf16 v[42:45], v[158:161], v[222:225], v[42:45]
	v_mfma_f32_16x16x32_bf16 v[30:33], v[138:141], v[226:229], v[30:33]
	v_mfma_f32_16x16x32_bf16 v[30:33], v[146:149], v[230:233], v[30:33]
	v_mfma_f32_16x16x32_bf16 v[26:29], v[150:153], v[226:229], v[26:29]
	v_mfma_f32_16x16x32_bf16 v[26:29], v[158:161], v[230:233], v[26:29]
	v_mfma_f32_16x16x32_bf16 v[14:17], v[138:141], v[234:237], v[14:17]
	v_mfma_f32_16x16x32_bf16 v[14:17], v[146:149], v[238:241], v[14:17]
	v_mfma_f32_16x16x32_bf16 v[10:13], v[150:153], v[234:237], v[10:13]
	v_mfma_f32_16x16x32_bf16 v[10:13], v[158:161], v[238:241], v[10:13]
	s_add_i32 s91, s91, 2
	s_add_u32 s56, s56, 0x100
	s_addc_u32 s57, s57, 0
	s_add_u32 s86, s86, 0x100
	s_addc_u32 s87, s87, 0
	v_mfma_f32_16x16x32_bf16 v[54:57], v[182:185], v[198:201], v[54:57]
	v_mfma_f32_16x16x32_bf16 v[54:57], v[186:189], v[214:217], v[54:57]
	v_mfma_f32_16x16x32_bf16 v[50:53], v[190:193], v[198:201], v[50:53]
	v_mfma_f32_16x16x32_bf16 v[50:53], v[194:197], v[214:217], v[50:53]
	v_mfma_f32_16x16x32_bf16 v[38:41], v[182:185], v[218:221], v[38:41]
	v_mfma_f32_16x16x32_bf16 v[38:41], v[186:189], v[222:225], v[38:41]
	v_mfma_f32_16x16x32_bf16 v[34:37], v[190:193], v[218:221], v[34:37]
	v_mfma_f32_16x16x32_bf16 v[34:37], v[194:197], v[222:225], v[34:37]
	v_mfma_f32_16x16x32_bf16 v[22:25], v[182:185], v[226:229], v[22:25]
	v_mfma_f32_16x16x32_bf16 v[22:25], v[186:189], v[230:233], v[22:25]
	v_mfma_f32_16x16x32_bf16 v[18:21], v[190:193], v[226:229], v[18:21]
	v_mfma_f32_16x16x32_bf16 v[18:21], v[194:197], v[230:233], v[18:21]
	v_mfma_f32_16x16x32_bf16 v[6:9], v[182:185], v[234:237], v[6:9]
	v_mfma_f32_16x16x32_bf16 v[6:9], v[186:189], v[238:241], v[6:9]
	v_mfma_f32_16x16x32_bf16 v[2:5], v[190:193], v[234:237], v[2:5]
	v_mfma_f32_16x16x32_bf16 v[2:5], v[194:197], v[238:241], v[2:5]
	s_barrier
	s_cmp_gt_u32 s91, 13
	s_cbranch_scc0 .LBB0_850
	s_setprio 0
	s_and_b64 vcc, exec, s[62:63]
	s_cbranch_vccz .LBB0_853
	s_barrier
